# K-loop LDS-DMA addressing moved off the VALU: 14 of 16 loads per iteration use scalar base + 32-bit lane offset (12 of 16 v_lshl_add_u64 removed); rest of stack as before
# speedup vs baseline: 1.0135x; 1.0135x over previous
.LBB0_243:
	s_lshl_b32 s24, s12, 20
	s_and_b32 s24, s24, 0xff00000
	v_readlane_b32 s36, v248, 22
	v_readlane_b32 s37, v248, 23
	s_add_u32 s24, s36, s24
	s_addc_u32 s35, s37, 0
	s_lshr_b32 s36, s12, 13
	s_and_b32 s36, s36, 0x7ff80
	s_add_u32 s54, s24, s36
	s_addc_u32 s55, s35, 0
	s_lshl_b32 s24, s12, 12
	s_and_b32 s24, s24, 0xff00000
	v_readlane_b32 s38, v248, 24
	v_readlane_b32 s39, v248, 25
	s_add_u32 s24, s38, s24
	s_addc_u32 s35, s39, 0
	s_add_u32 s70, s24, s36
	s_addc_u32 s71, s35, 0
	s_cmp_lt_i32 s1, 1
	v_cmp_gt_i64_e64 s[72:73], s[12:13], -1
	s_cbranch_scc1 .LBB0_253
	s_and_b64 s[12:13], s[72:73], exec
	s_cselect_b32 s24, s55, s5
	s_cselect_b32 s35, s54, s4
	s_cselect_b32 s36, s71, s3
	s_cselect_b32 s37, s70, s2
	s_add_i32 s38, s1, -2
	s_add_u32 s4, s4, 0x80080
	s_addc_u32 s5, s5, 0
	s_add_u32 s39, s2, 0x100
	s_addc_u32 s40, s3, 0
	s_mov_b32 s2, 0
	v_add_u32_e32 v138, s29, v183
	ds_read_b128 v[144:147], v138
	ds_read_b128 v[148:151], v138 offset:1024
	ds_read_b128 v[152:155], v138 offset:2048
	ds_read_b128 v[156:159], v138 offset:3072
	v_add_u32_e32 v138, s34, v183
	ds_read_b128 v[160:163], v138
	ds_read_b128 v[164:167], v138 offset:1024
	ds_read_b128 v[186:189], v138 offset:2048
	ds_read_b128 v[190:193], v138 offset:3072
	s_add_i32 s41, s2, 2
	s_add_u32 s3, s4, 0xfff80080
	s_addc_u32 s12, s5, -1
	s_cmp_eq_u32 s38, s2
	s_cselect_b32 s2, s37, s39
	s_cselect_b32 s13, s24, s12
	s_cselect_b32 s12, s35, s3
	s_cselect_b32 s3, s36, s40
	s_add_i32 m0, s17, 0xc000
	ds_read_b128 v[194:197], v185
	ds_read_b128 v[198:201], v185 offset:1024
	ds_read_b128 v[202:205], v185 offset:2048
	ds_read_b128 v[208:211], v185 offset:3072
	ds_read_b128 v[212:215], v185 offset:4096
	ds_read_b128 v[216:219], v185 offset:5120
	ds_read_b128 v[220:223], v185 offset:6144
	ds_read_b128 v[224:227], v185 offset:7168
	global_load_lds_dwordx4 v140, s[4:5]
	s_add_i32 m0, s17, 0xe000
	s_nop 0
	global_load_lds_dwordx4 v142, s[4:5]
	s_waitcnt vmcnt(8)
	s_waitcnt lgkmcnt(0)
	s_barrier
	s_setprio 1
	s_waitcnt lgkmcnt(0)
	v_mfma_i32_16x16x64_i8 v[126:129], v[144:147], v[194:197], 0
	v_mfma_i32_16x16x64_i8 v[126:129], v[148:151], v[198:201], v[126:129]
	v_mfma_i32_16x16x64_i8 v[122:125], v[152:155], v[194:197], 0
	v_mfma_i32_16x16x64_i8 v[122:125], v[156:159], v[198:201], v[122:125]
	v_mfma_i32_16x16x64_i8 v[118:121], v[144:147], v[202:205], 0
	v_mfma_i32_16x16x64_i8 v[118:121], v[148:151], v[208:211], v[118:121]
	v_mfma_i32_16x16x64_i8 v[114:117], v[152:155], v[202:205], 0
	v_mfma_i32_16x16x64_i8 v[114:117], v[156:159], v[208:211], v[114:117]
	v_mfma_i32_16x16x64_i8 v[110:113], v[144:147], v[212:215], 0
	v_mfma_i32_16x16x64_i8 v[110:113], v[148:151], v[216:219], v[110:113]
	v_mfma_i32_16x16x64_i8 v[106:109], v[152:155], v[212:215], 0
	v_mfma_i32_16x16x64_i8 v[106:109], v[156:159], v[216:219], v[106:109]
	v_mfma_i32_16x16x64_i8 v[102:105], v[144:147], v[220:223], 0
	v_mfma_i32_16x16x64_i8 v[102:105], v[148:151], v[224:227], v[102:105]
	v_mfma_i32_16x16x64_i8 v[98:101], v[152:155], v[220:223], 0
	v_mfma_i32_16x16x64_i8 v[98:101], v[156:159], v[224:227], v[98:101]
	s_setprio 0
	s_setprio 1
	v_mfma_i32_16x16x64_i8 v[94:97], v[160:163], v[194:197], 0
	v_mfma_i32_16x16x64_i8 v[94:97], v[164:167], v[198:201], v[94:97]
	v_mfma_i32_16x16x64_i8 v[90:93], v[186:189], v[194:197], 0
	v_mfma_i32_16x16x64_i8 v[90:93], v[190:193], v[198:201], v[90:93]
	v_mfma_i32_16x16x64_i8 v[86:89], v[160:163], v[202:205], 0
	v_mfma_i32_16x16x64_i8 v[86:89], v[164:167], v[208:211], v[86:89]
	v_mfma_i32_16x16x64_i8 v[82:85], v[186:189], v[202:205], 0
	v_mfma_i32_16x16x64_i8 v[82:85], v[190:193], v[208:211], v[82:85]
	v_mfma_i32_16x16x64_i8 v[78:81], v[160:163], v[212:215], 0
	v_mfma_i32_16x16x64_i8 v[78:81], v[164:167], v[216:219], v[78:81]
	v_mfma_i32_16x16x64_i8 v[74:77], v[186:189], v[212:215], 0
	v_mfma_i32_16x16x64_i8 v[74:77], v[190:193], v[216:219], v[74:77]
	v_mfma_i32_16x16x64_i8 v[70:73], v[160:163], v[220:223], 0
	v_mfma_i32_16x16x64_i8 v[70:73], v[164:167], v[224:227], v[70:73]
	v_mfma_i32_16x16x64_i8 v[66:69], v[186:189], v[220:223], 0
	v_mfma_i32_16x16x64_i8 v[66:69], v[190:193], v[224:227], v[66:69]
	s_setprio 0
	s_barrier
	s_add_i32 s42, s29, s16
	s_mov_b32 m0, s42
	ds_read_b128 v[194:197], v185 offset:16384
	ds_read_b128 v[198:201], v185 offset:17408
	ds_read_b128 v[202:205], v185 offset:18432
	ds_read_b128 v[208:211], v185 offset:19456
	ds_read_b128 v[212:215], v185 offset:20480
	ds_read_b128 v[216:219], v185 offset:21504
	ds_read_b128 v[220:223], v185 offset:22528
	ds_read_b128 v[224:227], v185 offset:23552
	global_load_lds_dwordx4 v132, s[2:3]
	s_add_i32 m0, s42, 0x2000
	s_add_u32 s42, s2, 0x80000
	s_addc_u32 s43, s3, 0
	s_add_i32 s44, s34, s16
	global_load_lds_dwordx4 v136, s[2:3]
	s_mov_b32 m0, s44
	v_lshl_add_u64 v[234:235], s[12:13], 0, v[134:135]
	global_load_lds_dwordx4 v132, s[42:43]
	s_add_i32 m0, s44, 0x2000
	s_nop 0
	global_load_lds_dwordx4 v136, s[42:43]
	v_lshl_add_u64 v[232:233], s[12:13], 0, v[130:131]
	s_mov_b32 m0, s17
	s_nop 0
	global_load_lds_dwordx4 v130, s[12:13]
	s_mov_b32 m0, s18
	s_nop 0
	global_load_lds_dwordx4 v134, s[12:13]
	s_waitcnt vmcnt(8)
	s_waitcnt lgkmcnt(0)
	s_barrier
	s_setprio 1
	s_waitcnt lgkmcnt(0)
	v_mfma_i32_16x16x64_i8 v[62:65], v[144:147], v[194:197], 0
	v_mfma_i32_16x16x64_i8 v[62:65], v[148:151], v[198:201], v[62:65]
	v_mfma_i32_16x16x64_i8 v[58:61], v[152:155], v[194:197], 0
	v_mfma_i32_16x16x64_i8 v[58:61], v[156:159], v[198:201], v[58:61]
	v_mfma_i32_16x16x64_i8 v[54:57], v[144:147], v[202:205], 0
	v_mfma_i32_16x16x64_i8 v[54:57], v[148:151], v[208:211], v[54:57]
	v_mfma_i32_16x16x64_i8 v[50:53], v[152:155], v[202:205], 0
	v_mfma_i32_16x16x64_i8 v[50:53], v[156:159], v[208:211], v[50:53]
	v_mfma_i32_16x16x64_i8 v[46:49], v[144:147], v[212:215], 0
	v_mfma_i32_16x16x64_i8 v[46:49], v[148:151], v[216:219], v[46:49]
	v_mfma_i32_16x16x64_i8 v[42:45], v[152:155], v[212:215], 0
	v_mfma_i32_16x16x64_i8 v[42:45], v[156:159], v[216:219], v[42:45]
	v_mfma_i32_16x16x64_i8 v[38:41], v[144:147], v[220:223], 0
	v_mfma_i32_16x16x64_i8 v[38:41], v[148:151], v[224:227], v[38:41]
	v_mfma_i32_16x16x64_i8 v[34:37], v[152:155], v[220:223], 0
	v_mfma_i32_16x16x64_i8 v[34:37], v[156:159], v[224:227], v[34:37]
	s_setprio 0
	s_setprio 1
	v_mfma_i32_16x16x64_i8 v[30:33], v[160:163], v[194:197], 0
	v_mfma_i32_16x16x64_i8 v[30:33], v[164:167], v[198:201], v[30:33]
	v_mfma_i32_16x16x64_i8 v[26:29], v[186:189], v[194:197], 0
	v_mfma_i32_16x16x64_i8 v[26:29], v[190:193], v[198:201], v[26:29]
	v_mfma_i32_16x16x64_i8 v[22:25], v[160:163], v[202:205], 0
	v_mfma_i32_16x16x64_i8 v[22:25], v[164:167], v[208:211], v[22:25]
	v_mfma_i32_16x16x64_i8 v[18:21], v[186:189], v[202:205], 0
	v_mfma_i32_16x16x64_i8 v[18:21], v[190:193], v[208:211], v[18:21]
	v_mfma_i32_16x16x64_i8 v[14:17], v[160:163], v[212:215], 0
	v_mfma_i32_16x16x64_i8 v[14:17], v[164:167], v[216:219], v[14:17]
	v_mfma_i32_16x16x64_i8 v[10:13], v[186:189], v[212:215], 0
	v_mfma_i32_16x16x64_i8 v[10:13], v[190:193], v[216:219], v[10:13]
	v_mfma_i32_16x16x64_i8 v[6:9], v[160:163], v[220:223], 0
	v_mfma_i32_16x16x64_i8 v[6:9], v[164:167], v[224:227], v[6:9]
	v_mfma_i32_16x16x64_i8 v[2:5], v[186:189], v[220:223], 0
	v_mfma_i32_16x16x64_i8 v[2:5], v[190:193], v[224:227], v[2:5]
	s_setprio 0
	s_barrier
	s_add_i32 s42, 0, 0x18000
	v_add_u32_e32 v138, s42, v183
	s_add_i32 s43, 0, 0x1c000
	ds_read_b128 v[144:147], v138
	ds_read_b128 v[148:151], v138 offset:1024
	ds_read_b128 v[152:155], v138 offset:2048
	ds_read_b128 v[156:159], v138 offset:3072
	v_add_u32_e32 v138, s43, v183
	ds_read_b128 v[160:163], v138
	ds_read_b128 v[164:167], v138 offset:1024
	ds_read_b128 v[186:189], v138 offset:2048
	ds_read_b128 v[190:193], v138 offset:3072
	s_add_u32 s12, s12, 0x80000
	s_addc_u32 s13, s13, 0
	s_mov_b32 m0, s19
	ds_read_b128 v[194:197], v185 offset:32768
	ds_read_b128 v[198:201], v185 offset:33792
	ds_read_b128 v[202:205], v185 offset:34816
	ds_read_b128 v[208:211], v185 offset:35840
	ds_read_b128 v[212:215], v185 offset:36864
	ds_read_b128 v[216:219], v185 offset:37888
	ds_read_b128 v[220:223], v185 offset:38912
	ds_read_b128 v[224:227], v185 offset:39936
	global_load_lds_dwordx4 v130, s[12:13]
	s_mov_b32 m0, s20
	s_nop 0
	global_load_lds_dwordx4 v134, s[12:13]
	s_waitcnt vmcnt(8)
	s_waitcnt lgkmcnt(0)
	s_barrier
	s_setprio 1
	s_waitcnt lgkmcnt(0)
	v_mfma_i32_16x16x64_i8 v[126:129], v[144:147], v[194:197], v[126:129]
	v_mfma_i32_16x16x64_i8 v[126:129], v[148:151], v[198:201], v[126:129]
	v_mfma_i32_16x16x64_i8 v[122:125], v[152:155], v[194:197], v[122:125]
	v_mfma_i32_16x16x64_i8 v[122:125], v[156:159], v[198:201], v[122:125]
	v_mfma_i32_16x16x64_i8 v[118:121], v[144:147], v[202:205], v[118:121]
	v_mfma_i32_16x16x64_i8 v[118:121], v[148:151], v[208:211], v[118:121]
	v_mfma_i32_16x16x64_i8 v[114:117], v[152:155], v[202:205], v[114:117]
	v_mfma_i32_16x16x64_i8 v[114:117], v[156:159], v[208:211], v[114:117]
	v_mfma_i32_16x16x64_i8 v[110:113], v[144:147], v[212:215], v[110:113]
	v_mfma_i32_16x16x64_i8 v[110:113], v[148:151], v[216:219], v[110:113]
	v_mfma_i32_16x16x64_i8 v[106:109], v[152:155], v[212:215], v[106:109]
	v_mfma_i32_16x16x64_i8 v[106:109], v[156:159], v[216:219], v[106:109]
	v_mfma_i32_16x16x64_i8 v[102:105], v[144:147], v[220:223], v[102:105]
	v_mfma_i32_16x16x64_i8 v[102:105], v[148:151], v[224:227], v[102:105]
	v_mfma_i32_16x16x64_i8 v[98:101], v[152:155], v[220:223], v[98:101]
	v_mfma_i32_16x16x64_i8 v[98:101], v[156:159], v[224:227], v[98:101]
	s_setprio 0
	s_setprio 1
	v_mfma_i32_16x16x64_i8 v[94:97], v[160:163], v[194:197], v[94:97]
	v_mfma_i32_16x16x64_i8 v[94:97], v[164:167], v[198:201], v[94:97]
	v_mfma_i32_16x16x64_i8 v[90:93], v[186:189], v[194:197], v[90:93]
	v_mfma_i32_16x16x64_i8 v[90:93], v[190:193], v[198:201], v[90:93]
	v_mfma_i32_16x16x64_i8 v[86:89], v[160:163], v[202:205], v[86:89]
	v_mfma_i32_16x16x64_i8 v[86:89], v[164:167], v[208:211], v[86:89]
	v_mfma_i32_16x16x64_i8 v[82:85], v[186:189], v[202:205], v[82:85]
	v_mfma_i32_16x16x64_i8 v[82:85], v[190:193], v[208:211], v[82:85]
	v_mfma_i32_16x16x64_i8 v[78:81], v[160:163], v[212:215], v[78:81]
	v_mfma_i32_16x16x64_i8 v[78:81], v[164:167], v[216:219], v[78:81]
	v_mfma_i32_16x16x64_i8 v[74:77], v[186:189], v[212:215], v[74:77]
	v_mfma_i32_16x16x64_i8 v[74:77], v[190:193], v[216:219], v[74:77]
	v_mfma_i32_16x16x64_i8 v[70:73], v[160:163], v[220:223], v[70:73]
	v_mfma_i32_16x16x64_i8 v[70:73], v[164:167], v[224:227], v[70:73]
	v_mfma_i32_16x16x64_i8 v[66:69], v[186:189], v[220:223], v[66:69]
	v_mfma_i32_16x16x64_i8 v[66:69], v[190:193], v[224:227], v[66:69]
	s_setprio 0
	s_barrier
	s_add_i32 s12, s42, s16
	s_add_u32 s98, s2, s10
	s_addc_u32 s99, s3, s11
	s_mov_b32 m0, s12
	ds_read_b128 v[194:197], v185 offset:49152
	ds_read_b128 v[198:201], v185 offset:50176
	ds_read_b128 v[202:205], v185 offset:51200
	ds_read_b128 v[208:211], v185 offset:52224
	ds_read_b128 v[212:215], v185 offset:53248
	ds_read_b128 v[216:219], v185 offset:54272
	ds_read_b128 v[220:223], v185 offset:55296
	ds_read_b128 v[224:227], v185 offset:56320
	global_load_lds_dwordx4 v132, s[98:99]
	s_add_i32 m0, s12, 0x2000
	s_add_u32 s2, s2, 0x80080
	s_addc_u32 s3, s3, 0
	s_add_i32 s12, s43, s16
	global_load_lds_dwordx4 v136, s[98:99]
	s_mov_b32 m0, s12
	s_nop 0
	global_load_lds_dwordx4 v132, s[2:3]
	s_add_i32 m0, s12, 0x2000
	s_nop 0
	global_load_lds_dwordx4 v136, s[2:3]
	v_lshl_add_u64 v[228:229], v[232:233], 0, s[10:11]
	s_mov_b32 m0, s22
	s_nop 0
	global_load_lds_dwordx4 v[228:229], off
	v_lshl_add_u64 v[228:229], v[234:235], 0, s[10:11]
	s_mov_b32 m0, s23
	s_nop 0
	global_load_lds_dwordx4 v[228:229], off
	s_waitcnt vmcnt(8)
	s_waitcnt lgkmcnt(0)
	s_barrier
	s_setprio 1
	s_waitcnt lgkmcnt(0)
	v_mfma_i32_16x16x64_i8 v[62:65], v[144:147], v[194:197], v[62:65]
	v_mfma_i32_16x16x64_i8 v[62:65], v[148:151], v[198:201], v[62:65]
	v_mfma_i32_16x16x64_i8 v[58:61], v[152:155], v[194:197], v[58:61]
	v_mfma_i32_16x16x64_i8 v[58:61], v[156:159], v[198:201], v[58:61]
	v_mfma_i32_16x16x64_i8 v[54:57], v[144:147], v[202:205], v[54:57]
	v_mfma_i32_16x16x64_i8 v[54:57], v[148:151], v[208:211], v[54:57]
	v_mfma_i32_16x16x64_i8 v[50:53], v[152:155], v[202:205], v[50:53]
	v_mfma_i32_16x16x64_i8 v[50:53], v[156:159], v[208:211], v[50:53]
	v_mfma_i32_16x16x64_i8 v[46:49], v[144:147], v[212:215], v[46:49]
	v_mfma_i32_16x16x64_i8 v[46:49], v[148:151], v[216:219], v[46:49]
	v_mfma_i32_16x16x64_i8 v[42:45], v[152:155], v[212:215], v[42:45]
	v_mfma_i32_16x16x64_i8 v[42:45], v[156:159], v[216:219], v[42:45]
	v_mfma_i32_16x16x64_i8 v[38:41], v[144:147], v[220:223], v[38:41]
	v_mfma_i32_16x16x64_i8 v[38:41], v[148:151], v[224:227], v[38:41]
	v_mfma_i32_16x16x64_i8 v[34:37], v[152:155], v[220:223], v[34:37]
	v_mfma_i32_16x16x64_i8 v[34:37], v[156:159], v[224:227], v[34:37]
	s_setprio 0
	s_setprio 1
	v_mfma_i32_16x16x64_i8 v[30:33], v[160:163], v[194:197], v[30:33]
	v_mfma_i32_16x16x64_i8 v[30:33], v[164:167], v[198:201], v[30:33]
	v_mfma_i32_16x16x64_i8 v[26:29], v[186:189], v[194:197], v[26:29]
	v_mfma_i32_16x16x64_i8 v[26:29], v[190:193], v[198:201], v[26:29]
	v_mfma_i32_16x16x64_i8 v[22:25], v[160:163], v[202:205], v[22:25]
	v_mfma_i32_16x16x64_i8 v[22:25], v[164:167], v[208:211], v[22:25]
	v_mfma_i32_16x16x64_i8 v[18:21], v[186:189], v[202:205], v[18:21]
	v_mfma_i32_16x16x64_i8 v[18:21], v[190:193], v[208:211], v[18:21]
	v_mfma_i32_16x16x64_i8 v[14:17], v[160:163], v[212:215], v[14:17]
	v_mfma_i32_16x16x64_i8 v[14:17], v[164:167], v[216:219], v[14:17]
	v_mfma_i32_16x16x64_i8 v[10:13], v[186:189], v[212:215], v[10:13]
	v_mfma_i32_16x16x64_i8 v[10:13], v[190:193], v[216:219], v[10:13]
	v_mfma_i32_16x16x64_i8 v[6:9], v[160:163], v[220:223], v[6:9]
	v_mfma_i32_16x16x64_i8 v[6:9], v[164:167], v[224:227], v[6:9]
	v_mfma_i32_16x16x64_i8 v[2:5], v[186:189], v[220:223], v[2:5]
	v_mfma_i32_16x16x64_i8 v[2:5], v[190:193], v[224:227], v[2:5]
	s_setprio 0
	s_barrier
	s_add_u32 s4, s4, 0x100
	s_addc_u32 s5, s5, 0
	s_add_u32 s39, s39, 0x100
	s_addc_u32 s40, s40, 0
	s_cmp_ge_i32 s41, s1
	s_mov_b32 s2, s41
	s_cbranch_scc1 .Lkpeel_exit_0
.LBB0_245:
	v_add_u32_e32 v138, s29, v183
	ds_read_b128 v[144:147], v138
	ds_read_b128 v[148:151], v138 offset:1024
	ds_read_b128 v[152:155], v138 offset:2048
	ds_read_b128 v[156:159], v138 offset:3072
	v_add_u32_e32 v138, s34, v183
	ds_read_b128 v[160:163], v138
	ds_read_b128 v[164:167], v138 offset:1024
	ds_read_b128 v[186:189], v138 offset:2048
	ds_read_b128 v[190:193], v138 offset:3072
	s_add_i32 s41, s2, 2
	s_add_u32 s3, s4, 0xfff80080
	s_addc_u32 s12, s5, -1
	s_cmp_eq_u32 s38, s2
	s_cselect_b32 s2, s37, s39
	s_cselect_b32 s13, s24, s12
	s_cselect_b32 s12, s35, s3
	s_cselect_b32 s3, s36, s40
	s_add_i32 m0, s17, 0xc000
	ds_read_b128 v[194:197], v185
	ds_read_b128 v[198:201], v185 offset:1024
	ds_read_b128 v[202:205], v185 offset:2048
	ds_read_b128 v[208:211], v185 offset:3072
	ds_read_b128 v[212:215], v185 offset:4096
	ds_read_b128 v[216:219], v185 offset:5120
	ds_read_b128 v[220:223], v185 offset:6144
	ds_read_b128 v[224:227], v185 offset:7168
	global_load_lds_dwordx4 v140, s[4:5]
	s_add_i32 m0, s17, 0xe000
	s_nop 0
	global_load_lds_dwordx4 v142, s[4:5]
	s_waitcnt vmcnt(8)
	s_waitcnt lgkmcnt(0)
	s_barrier
	s_setprio 1
	s_waitcnt lgkmcnt(0)
	v_mfma_i32_16x16x64_i8 v[126:129], v[144:147], v[194:197], v[126:129]
	v_mfma_i32_16x16x64_i8 v[126:129], v[148:151], v[198:201], v[126:129]
	v_mfma_i32_16x16x64_i8 v[122:125], v[152:155], v[194:197], v[122:125]
	v_mfma_i32_16x16x64_i8 v[122:125], v[156:159], v[198:201], v[122:125]
	v_mfma_i32_16x16x64_i8 v[118:121], v[144:147], v[202:205], v[118:121]
	v_mfma_i32_16x16x64_i8 v[118:121], v[148:151], v[208:211], v[118:121]
	v_mfma_i32_16x16x64_i8 v[114:117], v[152:155], v[202:205], v[114:117]
	v_mfma_i32_16x16x64_i8 v[114:117], v[156:159], v[208:211], v[114:117]
	v_mfma_i32_16x16x64_i8 v[110:113], v[144:147], v[212:215], v[110:113]
	v_mfma_i32_16x16x64_i8 v[110:113], v[148:151], v[216:219], v[110:113]
	v_mfma_i32_16x16x64_i8 v[106:109], v[152:155], v[212:215], v[106:109]
	v_mfma_i32_16x16x64_i8 v[106:109], v[156:159], v[216:219], v[106:109]
	v_mfma_i32_16x16x64_i8 v[102:105], v[144:147], v[220:223], v[102:105]
	v_mfma_i32_16x16x64_i8 v[102:105], v[148:151], v[224:227], v[102:105]
	v_mfma_i32_16x16x64_i8 v[98:101], v[152:155], v[220:223], v[98:101]
	v_mfma_i32_16x16x64_i8 v[98:101], v[156:159], v[224:227], v[98:101]
	s_setprio 0
	s_setprio 1
	v_mfma_i32_16x16x64_i8 v[94:97], v[160:163], v[194:197], v[94:97]
	v_mfma_i32_16x16x64_i8 v[94:97], v[164:167], v[198:201], v[94:97]
	v_mfma_i32_16x16x64_i8 v[90:93], v[186:189], v[194:197], v[90:93]
	v_mfma_i32_16x16x64_i8 v[90:93], v[190:193], v[198:201], v[90:93]
	v_mfma_i32_16x16x64_i8 v[86:89], v[160:163], v[202:205], v[86:89]
	v_mfma_i32_16x16x64_i8 v[86:89], v[164:167], v[208:211], v[86:89]
	v_mfma_i32_16x16x64_i8 v[82:85], v[186:189], v[202:205], v[82:85]
	v_mfma_i32_16x16x64_i8 v[82:85], v[190:193], v[208:211], v[82:85]
	v_mfma_i32_16x16x64_i8 v[78:81], v[160:163], v[212:215], v[78:81]
	v_mfma_i32_16x16x64_i8 v[78:81], v[164:167], v[216:219], v[78:81]
	v_mfma_i32_16x16x64_i8 v[74:77], v[186:189], v[212:215], v[74:77]
	v_mfma_i32_16x16x64_i8 v[74:77], v[190:193], v[216:219], v[74:77]
	v_mfma_i32_16x16x64_i8 v[70:73], v[160:163], v[220:223], v[70:73]
	v_mfma_i32_16x16x64_i8 v[70:73], v[164:167], v[224:227], v[70:73]
	v_mfma_i32_16x16x64_i8 v[66:69], v[186:189], v[220:223], v[66:69]
	v_mfma_i32_16x16x64_i8 v[66:69], v[190:193], v[224:227], v[66:69]
	s_setprio 0
	s_barrier
	s_add_i32 s42, s29, s16
	s_mov_b32 m0, s42
	ds_read_b128 v[194:197], v185 offset:16384
	ds_read_b128 v[198:201], v185 offset:17408
	ds_read_b128 v[202:205], v185 offset:18432
	ds_read_b128 v[208:211], v185 offset:19456
	ds_read_b128 v[212:215], v185 offset:20480
	ds_read_b128 v[216:219], v185 offset:21504
	ds_read_b128 v[220:223], v185 offset:22528
	ds_read_b128 v[224:227], v185 offset:23552
	global_load_lds_dwordx4 v132, s[2:3]
	s_add_i32 m0, s42, 0x2000
	s_add_u32 s42, s2, 0x80000
	s_addc_u32 s43, s3, 0
	s_add_i32 s44, s34, s16
	global_load_lds_dwordx4 v136, s[2:3]
	s_mov_b32 m0, s44
	v_lshl_add_u64 v[234:235], s[12:13], 0, v[134:135]
	global_load_lds_dwordx4 v132, s[42:43]
	s_add_i32 m0, s44, 0x2000
	s_nop 0
	global_load_lds_dwordx4 v136, s[42:43]
	v_lshl_add_u64 v[232:233], s[12:13], 0, v[130:131]
	s_mov_b32 m0, s17
	s_nop 0
	global_load_lds_dwordx4 v130, s[12:13]
	s_mov_b32 m0, s18
	s_nop 0
	global_load_lds_dwordx4 v134, s[12:13]
	s_waitcnt vmcnt(8)
	s_waitcnt lgkmcnt(0)
	s_barrier
	s_setprio 1
	s_waitcnt lgkmcnt(0)
	v_mfma_i32_16x16x64_i8 v[62:65], v[144:147], v[194:197], v[62:65]
	v_mfma_i32_16x16x64_i8 v[62:65], v[148:151], v[198:201], v[62:65]
	v_mfma_i32_16x16x64_i8 v[58:61], v[152:155], v[194:197], v[58:61]
	v_mfma_i32_16x16x64_i8 v[58:61], v[156:159], v[198:201], v[58:61]
	v_mfma_i32_16x16x64_i8 v[54:57], v[144:147], v[202:205], v[54:57]
	v_mfma_i32_16x16x64_i8 v[54:57], v[148:151], v[208:211], v[54:57]
	v_mfma_i32_16x16x64_i8 v[50:53], v[152:155], v[202:205], v[50:53]
	v_mfma_i32_16x16x64_i8 v[50:53], v[156:159], v[208:211], v[50:53]
	v_mfma_i32_16x16x64_i8 v[46:49], v[144:147], v[212:215], v[46:49]
	v_mfma_i32_16x16x64_i8 v[46:49], v[148:151], v[216:219], v[46:49]
	v_mfma_i32_16x16x64_i8 v[42:45], v[152:155], v[212:215], v[42:45]
	v_mfma_i32_16x16x64_i8 v[42:45], v[156:159], v[216:219], v[42:45]
	v_mfma_i32_16x16x64_i8 v[38:41], v[144:147], v[220:223], v[38:41]
	v_mfma_i32_16x16x64_i8 v[38:41], v[148:151], v[224:227], v[38:41]
	v_mfma_i32_16x16x64_i8 v[34:37], v[152:155], v[220:223], v[34:37]
	v_mfma_i32_16x16x64_i8 v[34:37], v[156:159], v[224:227], v[34:37]
	s_setprio 0
	s_setprio 1
	v_mfma_i32_16x16x64_i8 v[30:33], v[160:163], v[194:197], v[30:33]
	v_mfma_i32_16x16x64_i8 v[30:33], v[164:167], v[198:201], v[30:33]
	v_mfma_i32_16x16x64_i8 v[26:29], v[186:189], v[194:197], v[26:29]
	v_mfma_i32_16x16x64_i8 v[26:29], v[190:193], v[198:201], v[26:29]
	v_mfma_i32_16x16x64_i8 v[22:25], v[160:163], v[202:205], v[22:25]
	v_mfma_i32_16x16x64_i8 v[22:25], v[164:167], v[208:211], v[22:25]
	v_mfma_i32_16x16x64_i8 v[18:21], v[186:189], v[202:205], v[18:21]
	v_mfma_i32_16x16x64_i8 v[18:21], v[190:193], v[208:211], v[18:21]
	v_mfma_i32_16x16x64_i8 v[14:17], v[160:163], v[212:215], v[14:17]
	v_mfma_i32_16x16x64_i8 v[14:17], v[164:167], v[216:219], v[14:17]
	v_mfma_i32_16x16x64_i8 v[10:13], v[186:189], v[212:215], v[10:13]
	v_mfma_i32_16x16x64_i8 v[10:13], v[190:193], v[216:219], v[10:13]
	v_mfma_i32_16x16x64_i8 v[6:9], v[160:163], v[220:223], v[6:9]
	v_mfma_i32_16x16x64_i8 v[6:9], v[164:167], v[224:227], v[6:9]
	v_mfma_i32_16x16x64_i8 v[2:5], v[186:189], v[220:223], v[2:5]
	v_mfma_i32_16x16x64_i8 v[2:5], v[190:193], v[224:227], v[2:5]
	s_setprio 0
	s_barrier
	s_add_i32 s42, 0, 0x18000
	v_add_u32_e32 v138, s42, v183
	s_add_i32 s43, 0, 0x1c000
	ds_read_b128 v[144:147], v138
	ds_read_b128 v[148:151], v138 offset:1024
	ds_read_b128 v[152:155], v138 offset:2048
	ds_read_b128 v[156:159], v138 offset:3072
	v_add_u32_e32 v138, s43, v183
	ds_read_b128 v[160:163], v138
	ds_read_b128 v[164:167], v138 offset:1024
	ds_read_b128 v[186:189], v138 offset:2048
	ds_read_b128 v[190:193], v138 offset:3072
	s_add_u32 s12, s12, 0x80000
	s_addc_u32 s13, s13, 0
	s_mov_b32 m0, s19
	ds_read_b128 v[194:197], v185 offset:32768
	ds_read_b128 v[198:201], v185 offset:33792
	ds_read_b128 v[202:205], v185 offset:34816
	ds_read_b128 v[208:211], v185 offset:35840
	ds_read_b128 v[212:215], v185 offset:36864
	ds_read_b128 v[216:219], v185 offset:37888
	ds_read_b128 v[220:223], v185 offset:38912
	ds_read_b128 v[224:227], v185 offset:39936
	global_load_lds_dwordx4 v130, s[12:13]
	s_mov_b32 m0, s20
	s_nop 0
	global_load_lds_dwordx4 v134, s[12:13]
	s_waitcnt vmcnt(8)
	s_waitcnt lgkmcnt(0)
	s_barrier
	s_setprio 1
	s_waitcnt lgkmcnt(0)
	v_mfma_i32_16x16x64_i8 v[126:129], v[144:147], v[194:197], v[126:129]
	v_mfma_i32_16x16x64_i8 v[126:129], v[148:151], v[198:201], v[126:129]
	v_mfma_i32_16x16x64_i8 v[122:125], v[152:155], v[194:197], v[122:125]
	v_mfma_i32_16x16x64_i8 v[122:125], v[156:159], v[198:201], v[122:125]
	v_mfma_i32_16x16x64_i8 v[118:121], v[144:147], v[202:205], v[118:121]
	v_mfma_i32_16x16x64_i8 v[118:121], v[148:151], v[208:211], v[118:121]
	v_mfma_i32_16x16x64_i8 v[114:117], v[152:155], v[202:205], v[114:117]
	v_mfma_i32_16x16x64_i8 v[114:117], v[156:159], v[208:211], v[114:117]
	v_mfma_i32_16x16x64_i8 v[110:113], v[144:147], v[212:215], v[110:113]
	v_mfma_i32_16x16x64_i8 v[110:113], v[148:151], v[216:219], v[110:113]
	v_mfma_i32_16x16x64_i8 v[106:109], v[152:155], v[212:215], v[106:109]
	v_mfma_i32_16x16x64_i8 v[106:109], v[156:159], v[216:219], v[106:109]
	v_mfma_i32_16x16x64_i8 v[102:105], v[144:147], v[220:223], v[102:105]
	v_mfma_i32_16x16x64_i8 v[102:105], v[148:151], v[224:227], v[102:105]
	v_mfma_i32_16x16x64_i8 v[98:101], v[152:155], v[220:223], v[98:101]
	v_mfma_i32_16x16x64_i8 v[98:101], v[156:159], v[224:227], v[98:101]
	s_setprio 0
	s_setprio 1
	v_mfma_i32_16x16x64_i8 v[94:97], v[160:163], v[194:197], v[94:97]
	v_mfma_i32_16x16x64_i8 v[94:97], v[164:167], v[198:201], v[94:97]
	v_mfma_i32_16x16x64_i8 v[90:93], v[186:189], v[194:197], v[90:93]
	v_mfma_i32_16x16x64_i8 v[90:93], v[190:193], v[198:201], v[90:93]
	v_mfma_i32_16x16x64_i8 v[86:89], v[160:163], v[202:205], v[86:89]
	v_mfma_i32_16x16x64_i8 v[86:89], v[164:167], v[208:211], v[86:89]
	v_mfma_i32_16x16x64_i8 v[82:85], v[186:189], v[202:205], v[82:85]
	v_mfma_i32_16x16x64_i8 v[82:85], v[190:193], v[208:211], v[82:85]
	v_mfma_i32_16x16x64_i8 v[78:81], v[160:163], v[212:215], v[78:81]
	v_mfma_i32_16x16x64_i8 v[78:81], v[164:167], v[216:219], v[78:81]
	v_mfma_i32_16x16x64_i8 v[74:77], v[186:189], v[212:215], v[74:77]
	v_mfma_i32_16x16x64_i8 v[74:77], v[190:193], v[216:219], v[74:77]
	v_mfma_i32_16x16x64_i8 v[70:73], v[160:163], v[220:223], v[70:73]
	v_mfma_i32_16x16x64_i8 v[70:73], v[164:167], v[224:227], v[70:73]
	v_mfma_i32_16x16x64_i8 v[66:69], v[186:189], v[220:223], v[66:69]
	v_mfma_i32_16x16x64_i8 v[66:69], v[190:193], v[224:227], v[66:69]
	s_setprio 0
	s_barrier
	s_add_i32 s12, s42, s16
	s_add_u32 s98, s2, s10
	s_addc_u32 s99, s3, s11
	s_mov_b32 m0, s12
	ds_read_b128 v[194:197], v185 offset:49152
	ds_read_b128 v[198:201], v185 offset:50176
	ds_read_b128 v[202:205], v185 offset:51200
	ds_read_b128 v[208:211], v185 offset:52224
	ds_read_b128 v[212:215], v185 offset:53248
	ds_read_b128 v[216:219], v185 offset:54272
	ds_read_b128 v[220:223], v185 offset:55296
	ds_read_b128 v[224:227], v185 offset:56320
	global_load_lds_dwordx4 v132, s[98:99]
	s_add_i32 m0, s12, 0x2000
	s_add_u32 s2, s2, 0x80080
	s_addc_u32 s3, s3, 0
	s_add_i32 s12, s43, s16
	global_load_lds_dwordx4 v136, s[98:99]
	s_mov_b32 m0, s12
	s_nop 0
	global_load_lds_dwordx4 v132, s[2:3]
	s_add_i32 m0, s12, 0x2000
	s_nop 0
	global_load_lds_dwordx4 v136, s[2:3]
	v_lshl_add_u64 v[228:229], v[232:233], 0, s[10:11]
	s_mov_b32 m0, s22
	s_nop 0
	global_load_lds_dwordx4 v[228:229], off
	v_lshl_add_u64 v[228:229], v[234:235], 0, s[10:11]
	s_mov_b32 m0, s23
	s_nop 0
	global_load_lds_dwordx4 v[228:229], off
	s_waitcnt vmcnt(8)
	s_waitcnt lgkmcnt(0)
	s_barrier
	s_setprio 1
	s_waitcnt lgkmcnt(0)
	v_mfma_i32_16x16x64_i8 v[62:65], v[144:147], v[194:197], v[62:65]
	v_mfma_i32_16x16x64_i8 v[62:65], v[148:151], v[198:201], v[62:65]
	v_mfma_i32_16x16x64_i8 v[58:61], v[152:155], v[194:197], v[58:61]
	v_mfma_i32_16x16x64_i8 v[58:61], v[156:159], v[198:201], v[58:61]
	v_mfma_i32_16x16x64_i8 v[54:57], v[144:147], v[202:205], v[54:57]
	v_mfma_i32_16x16x64_i8 v[54:57], v[148:151], v[208:211], v[54:57]
	v_mfma_i32_16x16x64_i8 v[50:53], v[152:155], v[202:205], v[50:53]
	v_mfma_i32_16x16x64_i8 v[50:53], v[156:159], v[208:211], v[50:53]
	v_mfma_i32_16x16x64_i8 v[46:49], v[144:147], v[212:215], v[46:49]
	v_mfma_i32_16x16x64_i8 v[46:49], v[148:151], v[216:219], v[46:49]
	v_mfma_i32_16x16x64_i8 v[42:45], v[152:155], v[212:215], v[42:45]
	v_mfma_i32_16x16x64_i8 v[42:45], v[156:159], v[216:219], v[42:45]
	v_mfma_i32_16x16x64_i8 v[38:41], v[144:147], v[220:223], v[38:41]
	v_mfma_i32_16x16x64_i8 v[38:41], v[148:151], v[224:227], v[38:41]
	v_mfma_i32_16x16x64_i8 v[34:37], v[152:155], v[220:223], v[34:37]
	v_mfma_i32_16x16x64_i8 v[34:37], v[156:159], v[224:227], v[34:37]
	s_setprio 0
	s_setprio 1
	v_mfma_i32_16x16x64_i8 v[30:33], v[160:163], v[194:197], v[30:33]
	v_mfma_i32_16x16x64_i8 v[30:33], v[164:167], v[198:201], v[30:33]
	v_mfma_i32_16x16x64_i8 v[26:29], v[186:189], v[194:197], v[26:29]
	v_mfma_i32_16x16x64_i8 v[26:29], v[190:193], v[198:201], v[26:29]
	v_mfma_i32_16x16x64_i8 v[22:25], v[160:163], v[202:205], v[22:25]
	v_mfma_i32_16x16x64_i8 v[22:25], v[164:167], v[208:211], v[22:25]
	v_mfma_i32_16x16x64_i8 v[18:21], v[186:189], v[202:205], v[18:21]
	v_mfma_i32_16x16x64_i8 v[18:21], v[190:193], v[208:211], v[18:21]
	v_mfma_i32_16x16x64_i8 v[14:17], v[160:163], v[212:215], v[14:17]
	v_mfma_i32_16x16x64_i8 v[14:17], v[164:167], v[216:219], v[14:17]
	v_mfma_i32_16x16x64_i8 v[10:13], v[186:189], v[212:215], v[10:13]
	v_mfma_i32_16x16x64_i8 v[10:13], v[190:193], v[216:219], v[10:13]
	v_mfma_i32_16x16x64_i8 v[6:9], v[160:163], v[220:223], v[6:9]
	v_mfma_i32_16x16x64_i8 v[6:9], v[164:167], v[224:227], v[6:9]
	v_mfma_i32_16x16x64_i8 v[2:5], v[186:189], v[220:223], v[2:5]
	v_mfma_i32_16x16x64_i8 v[2:5], v[190:193], v[224:227], v[2:5]
	s_setprio 0
	s_barrier
	s_add_u32 s4, s4, 0x100
	s_addc_u32 s5, s5, 0
	s_add_u32 s39, s39, 0x100
	s_addc_u32 s40, s40, 0
	s_cmp_ge_i32 s41, s1
	s_mov_b32 s2, s41
	s_cbranch_scc0 .LBB0_245

.LBB0_265:
	s_lshl_b32 s10, s8, 21
	s_and_b32 s10, s10, 0x1fe00000
	v_readlane_b32 s40, v248, 20
	v_readlane_b32 s41, v248, 21
	s_add_u32 s10, s40, s10
	s_addc_u32 s33, s41, 0
	s_lshr_b32 s39, s8, 13
	s_and_b32 s39, s39, 0x7ff80
	s_add_u32 s70, s10, s39
	s_addc_u32 s71, s33, 0
	s_lshl_b32 s10, s8, 13
	s_and_b32 s10, s10, 0x1fe00000
	v_readlane_b32 s40, v248, 18
	v_readlane_b32 s41, v248, 19
	s_add_u32 s10, s40, s10
	s_addc_u32 s33, s41, 0
	s_add_u32 s72, s10, s39
	s_addc_u32 s73, s33, 0
	s_cmp_lt_i32 s1, 1
	v_cmp_gt_i64_e64 s[74:75], s[8:9], -1
	s_cbranch_scc1 .LBB0_324
	s_and_b64 s[8:9], s[74:75], exec
	s_cselect_b32 s10, s71, s5
	s_cselect_b32 s33, s70, s4
	s_cselect_b32 s39, s73, s3
	s_cselect_b32 s40, s72, s2
	s_add_i32 s41, s1, -2
	s_add_u32 s4, s4, 0x100080
	s_addc_u32 s5, s5, 0
	s_add_u32 s42, s2, 0x100
	s_addc_u32 s43, s3, 0
	s_mov_b32 s2, 0
	ds_read_b128 v[148:151], v145
	ds_read_b128 v[152:155], v145 offset:1024
	ds_read_b128 v[156:159], v145 offset:2048
	ds_read_b128 v[160:163], v145 offset:3072
	ds_read_b128 v[164:167], v146
	ds_read_b128 v[168:171], v146 offset:1024
	ds_read_b128 v[172:175], v146 offset:2048
	ds_read_b128 v[176:179], v146 offset:3072
	s_add_i32 s44, s2, 2
	s_add_u32 s3, s4, 0xfff00080
	s_addc_u32 s8, s5, -1
	s_cmp_eq_u32 s41, s2
	s_cselect_b32 s2, s40, s42
	s_cselect_b32 s9, s10, s8
	s_cselect_b32 s8, s33, s3
	s_cselect_b32 s3, s39, s43
	s_add_i32 m0, s16, 0xc000
	ds_read_b128 v[180:183], v147
	ds_read_b128 v[184:187], v147 offset:1024
	ds_read_b128 v[188:191], v147 offset:2048
	ds_read_b128 v[192:195], v147 offset:3072
	ds_read_b128 v[196:199], v147 offset:4096
	ds_read_b128 v[200:203], v147 offset:5120
	ds_read_b128 v[208:211], v147 offset:6144
	ds_read_b128 v[212:215], v147 offset:7168
	global_load_lds_dwordx4 v138, s[4:5]
	s_add_i32 m0, s16, 0xe000
	s_nop 0
	global_load_lds_dwordx4 v140, s[4:5]
	s_waitcnt vmcnt(8)
	s_waitcnt lgkmcnt(0)
	s_barrier
	s_setprio 1
	s_waitcnt lgkmcnt(0)
	v_mfma_f32_16x16x32_bf16 v[122:125], v[148:151], v[180:183], 0
	v_mfma_f32_16x16x32_bf16 v[122:125], v[152:155], v[184:187], v[122:125]
	v_mfma_f32_16x16x32_bf16 v[118:121], v[156:159], v[180:183], 0
	v_mfma_f32_16x16x32_bf16 v[118:121], v[160:163], v[184:187], v[118:121]
	v_mfma_f32_16x16x32_bf16 v[110:113], v[148:151], v[188:191], 0
	v_mfma_f32_16x16x32_bf16 v[110:113], v[152:155], v[192:195], v[110:113]
	v_mfma_f32_16x16x32_bf16 v[102:105], v[156:159], v[188:191], 0
	v_mfma_f32_16x16x32_bf16 v[102:105], v[160:163], v[192:195], v[102:105]
	v_mfma_f32_16x16x32_bf16 v[94:97], v[148:151], v[196:199], 0
	v_mfma_f32_16x16x32_bf16 v[94:97], v[152:155], v[200:203], v[94:97]
	v_mfma_f32_16x16x32_bf16 v[86:89], v[156:159], v[196:199], 0
	v_mfma_f32_16x16x32_bf16 v[86:89], v[160:163], v[200:203], v[86:89]
	v_mfma_f32_16x16x32_bf16 v[78:81], v[148:151], v[208:211], 0
	v_mfma_f32_16x16x32_bf16 v[78:81], v[152:155], v[212:215], v[78:81]
	v_mfma_f32_16x16x32_bf16 v[70:73], v[156:159], v[208:211], 0
	v_mfma_f32_16x16x32_bf16 v[70:73], v[160:163], v[212:215], v[70:73]
	s_setprio 0
	s_setprio 1
	v_mfma_f32_16x16x32_bf16 v[126:129], v[164:167], v[180:183], 0
	v_mfma_f32_16x16x32_bf16 v[126:129], v[168:171], v[184:187], v[126:129]
	v_mfma_f32_16x16x32_bf16 v[114:117], v[172:175], v[180:183], 0
	v_mfma_f32_16x16x32_bf16 v[114:117], v[176:179], v[184:187], v[114:117]
	v_mfma_f32_16x16x32_bf16 v[106:109], v[164:167], v[188:191], 0
	v_mfma_f32_16x16x32_bf16 v[106:109], v[168:171], v[192:195], v[106:109]
	v_mfma_f32_16x16x32_bf16 v[98:101], v[172:175], v[188:191], 0
	v_mfma_f32_16x16x32_bf16 v[98:101], v[176:179], v[192:195], v[98:101]
	v_mfma_f32_16x16x32_bf16 v[90:93], v[164:167], v[196:199], 0
	v_mfma_f32_16x16x32_bf16 v[90:93], v[168:171], v[200:203], v[90:93]
	v_mfma_f32_16x16x32_bf16 v[82:85], v[172:175], v[196:199], 0
	v_mfma_f32_16x16x32_bf16 v[82:85], v[176:179], v[200:203], v[82:85]
	v_mfma_f32_16x16x32_bf16 v[74:77], v[164:167], v[208:211], 0
	v_mfma_f32_16x16x32_bf16 v[74:77], v[168:171], v[212:215], v[74:77]
	v_mfma_f32_16x16x32_bf16 v[66:69], v[172:175], v[208:211], 0
	v_mfma_f32_16x16x32_bf16 v[66:69], v[176:179], v[212:215], v[66:69]
	s_setprio 0
	s_barrier
	s_add_i32 s45, s36, s13
	s_mov_b32 m0, s45
	ds_read_b128 v[180:183], v147 offset:16384
	ds_read_b128 v[184:187], v147 offset:17408
	ds_read_b128 v[188:191], v147 offset:18432
	ds_read_b128 v[192:195], v147 offset:19456
	ds_read_b128 v[196:199], v147 offset:20480
	ds_read_b128 v[200:203], v147 offset:21504
	ds_read_b128 v[208:211], v147 offset:22528
	ds_read_b128 v[212:215], v147 offset:23552
	global_load_lds_dwordx4 v132, s[2:3]
	s_add_i32 m0, s45, 0x2000
	s_add_u32 s46, s2, 0x100000
	s_addc_u32 s47, s3, 0
	s_add_i32 s45, s37, s13
	global_load_lds_dwordx4 v136, s[2:3]
	s_mov_b32 m0, s45
	v_lshl_add_u64 v[220:221], s[8:9], 0, v[134:135]
	global_load_lds_dwordx4 v132, s[46:47]
	s_add_i32 m0, s45, 0x2000
	s_nop 0
	global_load_lds_dwordx4 v136, s[46:47]
	v_lshl_add_u64 v[218:219], s[8:9], 0, v[130:131]
	s_mov_b32 m0, s16
	s_nop 0
	global_load_lds_dwordx4 v130, s[8:9]
	s_mov_b32 m0, s17
	s_nop 0
	global_load_lds_dwordx4 v134, s[8:9]
	s_waitcnt vmcnt(8)
	s_waitcnt lgkmcnt(0)
	s_barrier
	s_setprio 1
	s_waitcnt lgkmcnt(0)
	v_mfma_f32_16x16x32_bf16 v[62:65], v[148:151], v[180:183], 0
	v_mfma_f32_16x16x32_bf16 v[62:65], v[152:155], v[184:187], v[62:65]
	v_mfma_f32_16x16x32_bf16 v[54:57], v[156:159], v[180:183], 0
	v_mfma_f32_16x16x32_bf16 v[54:57], v[160:163], v[184:187], v[54:57]
	v_mfma_f32_16x16x32_bf16 v[46:49], v[148:151], v[188:191], 0
	v_mfma_f32_16x16x32_bf16 v[46:49], v[152:155], v[192:195], v[46:49]
	v_mfma_f32_16x16x32_bf16 v[38:41], v[156:159], v[188:191], 0
	v_mfma_f32_16x16x32_bf16 v[38:41], v[160:163], v[192:195], v[38:41]
	v_mfma_f32_16x16x32_bf16 v[30:33], v[148:151], v[196:199], 0
	v_mfma_f32_16x16x32_bf16 v[30:33], v[152:155], v[200:203], v[30:33]
	v_mfma_f32_16x16x32_bf16 v[22:25], v[156:159], v[196:199], 0
	v_mfma_f32_16x16x32_bf16 v[22:25], v[160:163], v[200:203], v[22:25]
	v_mfma_f32_16x16x32_bf16 v[14:17], v[148:151], v[208:211], 0
	v_mfma_f32_16x16x32_bf16 v[14:17], v[152:155], v[212:215], v[14:17]
	v_mfma_f32_16x16x32_bf16 v[6:9], v[156:159], v[208:211], 0
	v_mfma_f32_16x16x32_bf16 v[6:9], v[160:163], v[212:215], v[6:9]
	s_setprio 0
	s_setprio 1
	v_mfma_f32_16x16x32_bf16 v[58:61], v[164:167], v[180:183], 0
	v_mfma_f32_16x16x32_bf16 v[58:61], v[168:171], v[184:187], v[58:61]
	v_mfma_f32_16x16x32_bf16 v[50:53], v[172:175], v[180:183], 0
	v_mfma_f32_16x16x32_bf16 v[50:53], v[176:179], v[184:187], v[50:53]
	v_mfma_f32_16x16x32_bf16 v[42:45], v[164:167], v[188:191], 0
	v_mfma_f32_16x16x32_bf16 v[42:45], v[168:171], v[192:195], v[42:45]
	v_mfma_f32_16x16x32_bf16 v[34:37], v[172:175], v[188:191], 0
	v_mfma_f32_16x16x32_bf16 v[34:37], v[176:179], v[192:195], v[34:37]
	v_mfma_f32_16x16x32_bf16 v[26:29], v[164:167], v[196:199], 0
	v_mfma_f32_16x16x32_bf16 v[26:29], v[168:171], v[200:203], v[26:29]
	v_mfma_f32_16x16x32_bf16 v[18:21], v[172:175], v[196:199], 0
	v_mfma_f32_16x16x32_bf16 v[18:21], v[176:179], v[200:203], v[18:21]
	v_mfma_f32_16x16x32_bf16 v[10:13], v[164:167], v[208:211], 0
	v_mfma_f32_16x16x32_bf16 v[10:13], v[168:171], v[212:215], v[10:13]
	v_mfma_f32_16x16x32_bf16 v[2:5], v[172:175], v[208:211], 0
	v_mfma_f32_16x16x32_bf16 v[2:5], v[176:179], v[212:215], v[2:5]
	s_setprio 0
	s_barrier
	s_add_i32 s45, 0, 0x18000
	s_add_i32 s46, 0, 0x1c000
	v_add_u32_e32 v160, s45, v1
	v_add_u32_e32 v176, s46, v1
	ds_read_b128 v[148:151], v160
	ds_read_b128 v[152:155], v160 offset:1024
	ds_read_b128 v[156:159], v160 offset:2048
	ds_read_b128 v[160:163], v160 offset:3072
	ds_read_b128 v[164:167], v176
	ds_read_b128 v[168:171], v176 offset:1024
	ds_read_b128 v[172:175], v176 offset:2048
	ds_read_b128 v[176:179], v176 offset:3072
	s_add_u32 s8, s8, 0x100000
	s_addc_u32 s9, s9, 0
	s_mov_b32 m0, s18
	ds_read_b128 v[180:183], v147 offset:32768
	ds_read_b128 v[184:187], v147 offset:33792
	ds_read_b128 v[188:191], v147 offset:34816
	ds_read_b128 v[192:195], v147 offset:35840
	ds_read_b128 v[196:199], v147 offset:36864
	ds_read_b128 v[200:203], v147 offset:37888
	ds_read_b128 v[208:211], v147 offset:38912
	ds_read_b128 v[212:215], v147 offset:39936
	global_load_lds_dwordx4 v130, s[8:9]
	s_mov_b32 m0, s19
	s_nop 0
	global_load_lds_dwordx4 v134, s[8:9]
	s_waitcnt vmcnt(8)
	s_waitcnt lgkmcnt(0)
	s_barrier
	s_setprio 1
	s_waitcnt lgkmcnt(0)
	v_mfma_f32_16x16x32_bf16 v[122:125], v[148:151], v[180:183], v[122:125]
	v_mfma_f32_16x16x32_bf16 v[122:125], v[152:155], v[184:187], v[122:125]
	v_mfma_f32_16x16x32_bf16 v[118:121], v[156:159], v[180:183], v[118:121]
	v_mfma_f32_16x16x32_bf16 v[118:121], v[160:163], v[184:187], v[118:121]
	v_mfma_f32_16x16x32_bf16 v[110:113], v[148:151], v[188:191], v[110:113]
	v_mfma_f32_16x16x32_bf16 v[110:113], v[152:155], v[192:195], v[110:113]
	v_mfma_f32_16x16x32_bf16 v[102:105], v[156:159], v[188:191], v[102:105]
	v_mfma_f32_16x16x32_bf16 v[102:105], v[160:163], v[192:195], v[102:105]
	v_mfma_f32_16x16x32_bf16 v[94:97], v[148:151], v[196:199], v[94:97]
	v_mfma_f32_16x16x32_bf16 v[94:97], v[152:155], v[200:203], v[94:97]
	v_mfma_f32_16x16x32_bf16 v[86:89], v[156:159], v[196:199], v[86:89]
	v_mfma_f32_16x16x32_bf16 v[86:89], v[160:163], v[200:203], v[86:89]
	v_mfma_f32_16x16x32_bf16 v[78:81], v[148:151], v[208:211], v[78:81]
	v_mfma_f32_16x16x32_bf16 v[78:81], v[152:155], v[212:215], v[78:81]
	v_mfma_f32_16x16x32_bf16 v[70:73], v[156:159], v[208:211], v[70:73]
	v_mfma_f32_16x16x32_bf16 v[70:73], v[160:163], v[212:215], v[70:73]
	s_setprio 0
	s_setprio 1
	v_mfma_f32_16x16x32_bf16 v[126:129], v[164:167], v[180:183], v[126:129]
	v_mfma_f32_16x16x32_bf16 v[126:129], v[168:171], v[184:187], v[126:129]
	v_mfma_f32_16x16x32_bf16 v[114:117], v[172:175], v[180:183], v[114:117]
	v_mfma_f32_16x16x32_bf16 v[114:117], v[176:179], v[184:187], v[114:117]
	v_mfma_f32_16x16x32_bf16 v[106:109], v[164:167], v[188:191], v[106:109]
	v_mfma_f32_16x16x32_bf16 v[106:109], v[168:171], v[192:195], v[106:109]
	v_mfma_f32_16x16x32_bf16 v[98:101], v[172:175], v[188:191], v[98:101]
	v_mfma_f32_16x16x32_bf16 v[98:101], v[176:179], v[192:195], v[98:101]
	v_mfma_f32_16x16x32_bf16 v[90:93], v[164:167], v[196:199], v[90:93]
	v_mfma_f32_16x16x32_bf16 v[90:93], v[168:171], v[200:203], v[90:93]
	v_mfma_f32_16x16x32_bf16 v[82:85], v[172:175], v[196:199], v[82:85]
	v_mfma_f32_16x16x32_bf16 v[82:85], v[176:179], v[200:203], v[82:85]
	v_mfma_f32_16x16x32_bf16 v[74:77], v[164:167], v[208:211], v[74:77]
	v_mfma_f32_16x16x32_bf16 v[74:77], v[168:171], v[212:215], v[74:77]
	v_mfma_f32_16x16x32_bf16 v[66:69], v[172:175], v[208:211], v[66:69]
	v_mfma_f32_16x16x32_bf16 v[66:69], v[176:179], v[212:215], v[66:69]
	s_setprio 0
	s_barrier
	s_add_i32 s8, s45, s13
	s_add_u32 s98, s2, s24
	s_addc_u32 s99, s3, s25
	s_mov_b32 m0, s8
	ds_read_b128 v[180:183], v147 offset:49152
	ds_read_b128 v[184:187], v147 offset:50176
	ds_read_b128 v[188:191], v147 offset:51200
	ds_read_b128 v[192:195], v147 offset:52224
	ds_read_b128 v[196:199], v147 offset:53248
	ds_read_b128 v[200:203], v147 offset:54272
	ds_read_b128 v[208:211], v147 offset:55296
	ds_read_b128 v[212:215], v147 offset:56320
	global_load_lds_dwordx4 v132, s[98:99]
	s_add_i32 m0, s8, 0x2000
	s_add_u32 s2, s2, 0x100080
	s_addc_u32 s3, s3, 0
	s_add_i32 s8, s46, s13
	global_load_lds_dwordx4 v136, s[98:99]
	s_mov_b32 m0, s8
	s_nop 0
	global_load_lds_dwordx4 v132, s[2:3]
	s_add_i32 m0, s8, 0x2000
	s_nop 0
	global_load_lds_dwordx4 v136, s[2:3]
	v_lshl_add_u64 v[204:205], v[218:219], 0, s[24:25]
	s_mov_b32 m0, s29
	s_nop 0
	global_load_lds_dwordx4 v[204:205], off
	v_lshl_add_u64 v[204:205], v[220:221], 0, s[24:25]
	s_mov_b32 m0, s34
	s_nop 0
	global_load_lds_dwordx4 v[204:205], off
	s_waitcnt vmcnt(8)
	s_waitcnt lgkmcnt(0)
	s_barrier
	s_setprio 1
	s_waitcnt lgkmcnt(0)
	v_mfma_f32_16x16x32_bf16 v[62:65], v[148:151], v[180:183], v[62:65]
	v_mfma_f32_16x16x32_bf16 v[62:65], v[152:155], v[184:187], v[62:65]
	v_mfma_f32_16x16x32_bf16 v[54:57], v[156:159], v[180:183], v[54:57]
	v_mfma_f32_16x16x32_bf16 v[54:57], v[160:163], v[184:187], v[54:57]
	v_mfma_f32_16x16x32_bf16 v[46:49], v[148:151], v[188:191], v[46:49]
	v_mfma_f32_16x16x32_bf16 v[46:49], v[152:155], v[192:195], v[46:49]
	v_mfma_f32_16x16x32_bf16 v[38:41], v[156:159], v[188:191], v[38:41]
	v_mfma_f32_16x16x32_bf16 v[38:41], v[160:163], v[192:195], v[38:41]
	v_mfma_f32_16x16x32_bf16 v[30:33], v[148:151], v[196:199], v[30:33]
	v_mfma_f32_16x16x32_bf16 v[30:33], v[152:155], v[200:203], v[30:33]
	v_mfma_f32_16x16x32_bf16 v[22:25], v[156:159], v[196:199], v[22:25]
	v_mfma_f32_16x16x32_bf16 v[22:25], v[160:163], v[200:203], v[22:25]
	v_mfma_f32_16x16x32_bf16 v[14:17], v[148:151], v[208:211], v[14:17]
	v_mfma_f32_16x16x32_bf16 v[14:17], v[152:155], v[212:215], v[14:17]
	v_mfma_f32_16x16x32_bf16 v[6:9], v[156:159], v[208:211], v[6:9]
	v_mfma_f32_16x16x32_bf16 v[6:9], v[160:163], v[212:215], v[6:9]
	s_setprio 0
	s_setprio 1
	v_mfma_f32_16x16x32_bf16 v[58:61], v[164:167], v[180:183], v[58:61]
	v_mfma_f32_16x16x32_bf16 v[58:61], v[168:171], v[184:187], v[58:61]
	v_mfma_f32_16x16x32_bf16 v[50:53], v[172:175], v[180:183], v[50:53]
	v_mfma_f32_16x16x32_bf16 v[50:53], v[176:179], v[184:187], v[50:53]
	v_mfma_f32_16x16x32_bf16 v[42:45], v[164:167], v[188:191], v[42:45]
	v_mfma_f32_16x16x32_bf16 v[42:45], v[168:171], v[192:195], v[42:45]
	v_mfma_f32_16x16x32_bf16 v[34:37], v[172:175], v[188:191], v[34:37]
	v_mfma_f32_16x16x32_bf16 v[34:37], v[176:179], v[192:195], v[34:37]
	v_mfma_f32_16x16x32_bf16 v[26:29], v[164:167], v[196:199], v[26:29]
	v_mfma_f32_16x16x32_bf16 v[26:29], v[168:171], v[200:203], v[26:29]
	v_mfma_f32_16x16x32_bf16 v[18:21], v[172:175], v[196:199], v[18:21]
	v_mfma_f32_16x16x32_bf16 v[18:21], v[176:179], v[200:203], v[18:21]
	v_mfma_f32_16x16x32_bf16 v[10:13], v[164:167], v[208:211], v[10:13]
	v_mfma_f32_16x16x32_bf16 v[10:13], v[168:171], v[212:215], v[10:13]
	v_mfma_f32_16x16x32_bf16 v[2:5], v[172:175], v[208:211], v[2:5]
	v_mfma_f32_16x16x32_bf16 v[2:5], v[176:179], v[212:215], v[2:5]
	s_setprio 0
	s_barrier
	s_add_u32 s4, s4, 0x100
	s_addc_u32 s5, s5, 0
	s_add_u32 s42, s42, 0x100
	s_addc_u32 s43, s43, 0
	s_cmp_ge_i32 s44, s1
	s_mov_b32 s2, s44
	s_cbranch_scc1 .Lkpeel_exit_1
.LBB0_267:
	ds_read_b128 v[148:151], v145
	ds_read_b128 v[152:155], v145 offset:1024
	ds_read_b128 v[156:159], v145 offset:2048
	ds_read_b128 v[160:163], v145 offset:3072
	ds_read_b128 v[164:167], v146
	ds_read_b128 v[168:171], v146 offset:1024
	ds_read_b128 v[172:175], v146 offset:2048
	ds_read_b128 v[176:179], v146 offset:3072
	s_add_i32 s44, s2, 2
	s_add_u32 s3, s4, 0xfff00080
	s_addc_u32 s8, s5, -1
	s_cmp_eq_u32 s41, s2
	s_cselect_b32 s2, s40, s42
	s_cselect_b32 s9, s10, s8
	s_cselect_b32 s8, s33, s3
	s_cselect_b32 s3, s39, s43
	s_add_i32 m0, s16, 0xc000
	ds_read_b128 v[180:183], v147
	ds_read_b128 v[184:187], v147 offset:1024
	ds_read_b128 v[188:191], v147 offset:2048
	ds_read_b128 v[192:195], v147 offset:3072
	ds_read_b128 v[196:199], v147 offset:4096
	ds_read_b128 v[200:203], v147 offset:5120
	ds_read_b128 v[208:211], v147 offset:6144
	ds_read_b128 v[212:215], v147 offset:7168
	global_load_lds_dwordx4 v138, s[4:5]
	s_add_i32 m0, s16, 0xe000
	s_nop 0
	global_load_lds_dwordx4 v140, s[4:5]
	s_waitcnt vmcnt(8)
	s_waitcnt lgkmcnt(0)
	s_barrier
	s_setprio 1
	s_waitcnt lgkmcnt(0)
	v_mfma_f32_16x16x32_bf16 v[122:125], v[148:151], v[180:183], v[122:125]
	v_mfma_f32_16x16x32_bf16 v[122:125], v[152:155], v[184:187], v[122:125]
	v_mfma_f32_16x16x32_bf16 v[118:121], v[156:159], v[180:183], v[118:121]
	v_mfma_f32_16x16x32_bf16 v[118:121], v[160:163], v[184:187], v[118:121]
	v_mfma_f32_16x16x32_bf16 v[110:113], v[148:151], v[188:191], v[110:113]
	v_mfma_f32_16x16x32_bf16 v[110:113], v[152:155], v[192:195], v[110:113]
	v_mfma_f32_16x16x32_bf16 v[102:105], v[156:159], v[188:191], v[102:105]
	v_mfma_f32_16x16x32_bf16 v[102:105], v[160:163], v[192:195], v[102:105]
	v_mfma_f32_16x16x32_bf16 v[94:97], v[148:151], v[196:199], v[94:97]
	v_mfma_f32_16x16x32_bf16 v[94:97], v[152:155], v[200:203], v[94:97]
	v_mfma_f32_16x16x32_bf16 v[86:89], v[156:159], v[196:199], v[86:89]
	v_mfma_f32_16x16x32_bf16 v[86:89], v[160:163], v[200:203], v[86:89]
	v_mfma_f32_16x16x32_bf16 v[78:81], v[148:151], v[208:211], v[78:81]
	v_mfma_f32_16x16x32_bf16 v[78:81], v[152:155], v[212:215], v[78:81]
	v_mfma_f32_16x16x32_bf16 v[70:73], v[156:159], v[208:211], v[70:73]
	v_mfma_f32_16x16x32_bf16 v[70:73], v[160:163], v[212:215], v[70:73]
	s_setprio 0
	s_setprio 1
	v_mfma_f32_16x16x32_bf16 v[126:129], v[164:167], v[180:183], v[126:129]
	v_mfma_f32_16x16x32_bf16 v[126:129], v[168:171], v[184:187], v[126:129]
	v_mfma_f32_16x16x32_bf16 v[114:117], v[172:175], v[180:183], v[114:117]
	v_mfma_f32_16x16x32_bf16 v[114:117], v[176:179], v[184:187], v[114:117]
	v_mfma_f32_16x16x32_bf16 v[106:109], v[164:167], v[188:191], v[106:109]
	v_mfma_f32_16x16x32_bf16 v[106:109], v[168:171], v[192:195], v[106:109]
	v_mfma_f32_16x16x32_bf16 v[98:101], v[172:175], v[188:191], v[98:101]
	v_mfma_f32_16x16x32_bf16 v[98:101], v[176:179], v[192:195], v[98:101]
	v_mfma_f32_16x16x32_bf16 v[90:93], v[164:167], v[196:199], v[90:93]
	v_mfma_f32_16x16x32_bf16 v[90:93], v[168:171], v[200:203], v[90:93]
	v_mfma_f32_16x16x32_bf16 v[82:85], v[172:175], v[196:199], v[82:85]
	v_mfma_f32_16x16x32_bf16 v[82:85], v[176:179], v[200:203], v[82:85]
	v_mfma_f32_16x16x32_bf16 v[74:77], v[164:167], v[208:211], v[74:77]
	v_mfma_f32_16x16x32_bf16 v[74:77], v[168:171], v[212:215], v[74:77]
	v_mfma_f32_16x16x32_bf16 v[66:69], v[172:175], v[208:211], v[66:69]
	v_mfma_f32_16x16x32_bf16 v[66:69], v[176:179], v[212:215], v[66:69]
	s_setprio 0
	s_barrier
	s_add_i32 s45, s36, s13
	s_mov_b32 m0, s45
	ds_read_b128 v[180:183], v147 offset:16384
	ds_read_b128 v[184:187], v147 offset:17408
	ds_read_b128 v[188:191], v147 offset:18432
	ds_read_b128 v[192:195], v147 offset:19456
	ds_read_b128 v[196:199], v147 offset:20480
	ds_read_b128 v[200:203], v147 offset:21504
	ds_read_b128 v[208:211], v147 offset:22528
	ds_read_b128 v[212:215], v147 offset:23552
	global_load_lds_dwordx4 v132, s[2:3]
	s_add_i32 m0, s45, 0x2000
	s_add_u32 s46, s2, 0x100000
	s_addc_u32 s47, s3, 0
	s_add_i32 s45, s37, s13
	global_load_lds_dwordx4 v136, s[2:3]
	s_mov_b32 m0, s45
	v_lshl_add_u64 v[220:221], s[8:9], 0, v[134:135]
	global_load_lds_dwordx4 v132, s[46:47]
	s_add_i32 m0, s45, 0x2000
	s_nop 0
	global_load_lds_dwordx4 v136, s[46:47]
	v_lshl_add_u64 v[218:219], s[8:9], 0, v[130:131]
	s_mov_b32 m0, s16
	s_nop 0
	global_load_lds_dwordx4 v130, s[8:9]
	s_mov_b32 m0, s17
	s_nop 0
	global_load_lds_dwordx4 v134, s[8:9]
	s_waitcnt vmcnt(8)
	s_waitcnt lgkmcnt(0)
	s_barrier
	s_setprio 1
	s_waitcnt lgkmcnt(0)
	v_mfma_f32_16x16x32_bf16 v[62:65], v[148:151], v[180:183], v[62:65]
	v_mfma_f32_16x16x32_bf16 v[62:65], v[152:155], v[184:187], v[62:65]
	v_mfma_f32_16x16x32_bf16 v[54:57], v[156:159], v[180:183], v[54:57]
	v_mfma_f32_16x16x32_bf16 v[54:57], v[160:163], v[184:187], v[54:57]
	v_mfma_f32_16x16x32_bf16 v[46:49], v[148:151], v[188:191], v[46:49]
	v_mfma_f32_16x16x32_bf16 v[46:49], v[152:155], v[192:195], v[46:49]
	v_mfma_f32_16x16x32_bf16 v[38:41], v[156:159], v[188:191], v[38:41]
	v_mfma_f32_16x16x32_bf16 v[38:41], v[160:163], v[192:195], v[38:41]
	v_mfma_f32_16x16x32_bf16 v[30:33], v[148:151], v[196:199], v[30:33]
	v_mfma_f32_16x16x32_bf16 v[30:33], v[152:155], v[200:203], v[30:33]
	v_mfma_f32_16x16x32_bf16 v[22:25], v[156:159], v[196:199], v[22:25]
	v_mfma_f32_16x16x32_bf16 v[22:25], v[160:163], v[200:203], v[22:25]
	v_mfma_f32_16x16x32_bf16 v[14:17], v[148:151], v[208:211], v[14:17]
	v_mfma_f32_16x16x32_bf16 v[14:17], v[152:155], v[212:215], v[14:17]
	v_mfma_f32_16x16x32_bf16 v[6:9], v[156:159], v[208:211], v[6:9]
	v_mfma_f32_16x16x32_bf16 v[6:9], v[160:163], v[212:215], v[6:9]
	s_setprio 0
	s_setprio 1
	v_mfma_f32_16x16x32_bf16 v[58:61], v[164:167], v[180:183], v[58:61]
	v_mfma_f32_16x16x32_bf16 v[58:61], v[168:171], v[184:187], v[58:61]
	v_mfma_f32_16x16x32_bf16 v[50:53], v[172:175], v[180:183], v[50:53]
	v_mfma_f32_16x16x32_bf16 v[50:53], v[176:179], v[184:187], v[50:53]
	v_mfma_f32_16x16x32_bf16 v[42:45], v[164:167], v[188:191], v[42:45]
	v_mfma_f32_16x16x32_bf16 v[42:45], v[168:171], v[192:195], v[42:45]
	v_mfma_f32_16x16x32_bf16 v[34:37], v[172:175], v[188:191], v[34:37]
	v_mfma_f32_16x16x32_bf16 v[34:37], v[176:179], v[192:195], v[34:37]
	v_mfma_f32_16x16x32_bf16 v[26:29], v[164:167], v[196:199], v[26:29]
	v_mfma_f32_16x16x32_bf16 v[26:29], v[168:171], v[200:203], v[26:29]
	v_mfma_f32_16x16x32_bf16 v[18:21], v[172:175], v[196:199], v[18:21]
	v_mfma_f32_16x16x32_bf16 v[18:21], v[176:179], v[200:203], v[18:21]
	v_mfma_f32_16x16x32_bf16 v[10:13], v[164:167], v[208:211], v[10:13]
	v_mfma_f32_16x16x32_bf16 v[10:13], v[168:171], v[212:215], v[10:13]
	v_mfma_f32_16x16x32_bf16 v[2:5], v[172:175], v[208:211], v[2:5]
	v_mfma_f32_16x16x32_bf16 v[2:5], v[176:179], v[212:215], v[2:5]
	s_setprio 0
	s_barrier
	s_add_i32 s45, 0, 0x18000
	s_add_i32 s46, 0, 0x1c000
	v_add_u32_e32 v160, s45, v1
	v_add_u32_e32 v176, s46, v1
	ds_read_b128 v[148:151], v160
	ds_read_b128 v[152:155], v160 offset:1024
	ds_read_b128 v[156:159], v160 offset:2048
	ds_read_b128 v[160:163], v160 offset:3072
	ds_read_b128 v[164:167], v176
	ds_read_b128 v[168:171], v176 offset:1024
	ds_read_b128 v[172:175], v176 offset:2048
	ds_read_b128 v[176:179], v176 offset:3072
	s_add_u32 s8, s8, 0x100000
	s_addc_u32 s9, s9, 0
	s_mov_b32 m0, s18
	ds_read_b128 v[180:183], v147 offset:32768
	ds_read_b128 v[184:187], v147 offset:33792
	ds_read_b128 v[188:191], v147 offset:34816
	ds_read_b128 v[192:195], v147 offset:35840
	ds_read_b128 v[196:199], v147 offset:36864
	ds_read_b128 v[200:203], v147 offset:37888
	ds_read_b128 v[208:211], v147 offset:38912
	ds_read_b128 v[212:215], v147 offset:39936
	global_load_lds_dwordx4 v130, s[8:9]
	s_mov_b32 m0, s19
	s_nop 0
	global_load_lds_dwordx4 v134, s[8:9]
	s_waitcnt vmcnt(8)
	s_waitcnt lgkmcnt(0)
	s_barrier
	s_setprio 1
	s_waitcnt lgkmcnt(0)
	v_mfma_f32_16x16x32_bf16 v[122:125], v[148:151], v[180:183], v[122:125]
	v_mfma_f32_16x16x32_bf16 v[122:125], v[152:155], v[184:187], v[122:125]
	v_mfma_f32_16x16x32_bf16 v[118:121], v[156:159], v[180:183], v[118:121]
	v_mfma_f32_16x16x32_bf16 v[118:121], v[160:163], v[184:187], v[118:121]
	v_mfma_f32_16x16x32_bf16 v[110:113], v[148:151], v[188:191], v[110:113]
	v_mfma_f32_16x16x32_bf16 v[110:113], v[152:155], v[192:195], v[110:113]
	v_mfma_f32_16x16x32_bf16 v[102:105], v[156:159], v[188:191], v[102:105]
	v_mfma_f32_16x16x32_bf16 v[102:105], v[160:163], v[192:195], v[102:105]
	v_mfma_f32_16x16x32_bf16 v[94:97], v[148:151], v[196:199], v[94:97]
	v_mfma_f32_16x16x32_bf16 v[94:97], v[152:155], v[200:203], v[94:97]
	v_mfma_f32_16x16x32_bf16 v[86:89], v[156:159], v[196:199], v[86:89]
	v_mfma_f32_16x16x32_bf16 v[86:89], v[160:163], v[200:203], v[86:89]
	v_mfma_f32_16x16x32_bf16 v[78:81], v[148:151], v[208:211], v[78:81]
	v_mfma_f32_16x16x32_bf16 v[78:81], v[152:155], v[212:215], v[78:81]
	v_mfma_f32_16x16x32_bf16 v[70:73], v[156:159], v[208:211], v[70:73]
	v_mfma_f32_16x16x32_bf16 v[70:73], v[160:163], v[212:215], v[70:73]
	s_setprio 0
	s_setprio 1
	v_mfma_f32_16x16x32_bf16 v[126:129], v[164:167], v[180:183], v[126:129]
	v_mfma_f32_16x16x32_bf16 v[126:129], v[168:171], v[184:187], v[126:129]
	v_mfma_f32_16x16x32_bf16 v[114:117], v[172:175], v[180:183], v[114:117]
	v_mfma_f32_16x16x32_bf16 v[114:117], v[176:179], v[184:187], v[114:117]
	v_mfma_f32_16x16x32_bf16 v[106:109], v[164:167], v[188:191], v[106:109]
	v_mfma_f32_16x16x32_bf16 v[106:109], v[168:171], v[192:195], v[106:109]
	v_mfma_f32_16x16x32_bf16 v[98:101], v[172:175], v[188:191], v[98:101]
	v_mfma_f32_16x16x32_bf16 v[98:101], v[176:179], v[192:195], v[98:101]
	v_mfma_f32_16x16x32_bf16 v[90:93], v[164:167], v[196:199], v[90:93]
	v_mfma_f32_16x16x32_bf16 v[90:93], v[168:171], v[200:203], v[90:93]
	v_mfma_f32_16x16x32_bf16 v[82:85], v[172:175], v[196:199], v[82:85]
	v_mfma_f32_16x16x32_bf16 v[82:85], v[176:179], v[200:203], v[82:85]
	v_mfma_f32_16x16x32_bf16 v[74:77], v[164:167], v[208:211], v[74:77]
	v_mfma_f32_16x16x32_bf16 v[74:77], v[168:171], v[212:215], v[74:77]
	v_mfma_f32_16x16x32_bf16 v[66:69], v[172:175], v[208:211], v[66:69]
	v_mfma_f32_16x16x32_bf16 v[66:69], v[176:179], v[212:215], v[66:69]
	s_setprio 0
	s_barrier
	s_add_i32 s8, s45, s13
	s_add_u32 s98, s2, s24
	s_addc_u32 s99, s3, s25
	s_mov_b32 m0, s8
	ds_read_b128 v[180:183], v147 offset:49152
	ds_read_b128 v[184:187], v147 offset:50176
	ds_read_b128 v[188:191], v147 offset:51200
	ds_read_b128 v[192:195], v147 offset:52224
	ds_read_b128 v[196:199], v147 offset:53248
	ds_read_b128 v[200:203], v147 offset:54272
	ds_read_b128 v[208:211], v147 offset:55296
	ds_read_b128 v[212:215], v147 offset:56320
	global_load_lds_dwordx4 v132, s[98:99]
	s_add_i32 m0, s8, 0x2000
	s_add_u32 s2, s2, 0x100080
	s_addc_u32 s3, s3, 0
	s_add_i32 s8, s46, s13
	global_load_lds_dwordx4 v136, s[98:99]
	s_mov_b32 m0, s8
	s_nop 0
	global_load_lds_dwordx4 v132, s[2:3]
	s_add_i32 m0, s8, 0x2000
	s_nop 0
	global_load_lds_dwordx4 v136, s[2:3]
	v_lshl_add_u64 v[204:205], v[218:219], 0, s[24:25]
	s_mov_b32 m0, s29
	s_nop 0
	global_load_lds_dwordx4 v[204:205], off
	v_lshl_add_u64 v[204:205], v[220:221], 0, s[24:25]
	s_mov_b32 m0, s34
	s_nop 0
	global_load_lds_dwordx4 v[204:205], off
	s_waitcnt vmcnt(8)
	s_waitcnt lgkmcnt(0)
	s_barrier
	s_setprio 1
	s_waitcnt lgkmcnt(0)
	v_mfma_f32_16x16x32_bf16 v[62:65], v[148:151], v[180:183], v[62:65]
	v_mfma_f32_16x16x32_bf16 v[62:65], v[152:155], v[184:187], v[62:65]
	v_mfma_f32_16x16x32_bf16 v[54:57], v[156:159], v[180:183], v[54:57]
	v_mfma_f32_16x16x32_bf16 v[54:57], v[160:163], v[184:187], v[54:57]
	v_mfma_f32_16x16x32_bf16 v[46:49], v[148:151], v[188:191], v[46:49]
	v_mfma_f32_16x16x32_bf16 v[46:49], v[152:155], v[192:195], v[46:49]
	v_mfma_f32_16x16x32_bf16 v[38:41], v[156:159], v[188:191], v[38:41]
	v_mfma_f32_16x16x32_bf16 v[38:41], v[160:163], v[192:195], v[38:41]
	v_mfma_f32_16x16x32_bf16 v[30:33], v[148:151], v[196:199], v[30:33]
	v_mfma_f32_16x16x32_bf16 v[30:33], v[152:155], v[200:203], v[30:33]
	v_mfma_f32_16x16x32_bf16 v[22:25], v[156:159], v[196:199], v[22:25]
	v_mfma_f32_16x16x32_bf16 v[22:25], v[160:163], v[200:203], v[22:25]
	v_mfma_f32_16x16x32_bf16 v[14:17], v[148:151], v[208:211], v[14:17]
	v_mfma_f32_16x16x32_bf16 v[14:17], v[152:155], v[212:215], v[14:17]
	v_mfma_f32_16x16x32_bf16 v[6:9], v[156:159], v[208:211], v[6:9]
	v_mfma_f32_16x16x32_bf16 v[6:9], v[160:163], v[212:215], v[6:9]
	s_setprio 0
	s_setprio 1
	v_mfma_f32_16x16x32_bf16 v[58:61], v[164:167], v[180:183], v[58:61]
	v_mfma_f32_16x16x32_bf16 v[58:61], v[168:171], v[184:187], v[58:61]
	v_mfma_f32_16x16x32_bf16 v[50:53], v[172:175], v[180:183], v[50:53]
	v_mfma_f32_16x16x32_bf16 v[50:53], v[176:179], v[184:187], v[50:53]
	v_mfma_f32_16x16x32_bf16 v[42:45], v[164:167], v[188:191], v[42:45]
	v_mfma_f32_16x16x32_bf16 v[42:45], v[168:171], v[192:195], v[42:45]
	v_mfma_f32_16x16x32_bf16 v[34:37], v[172:175], v[188:191], v[34:37]
	v_mfma_f32_16x16x32_bf16 v[34:37], v[176:179], v[192:195], v[34:37]
	v_mfma_f32_16x16x32_bf16 v[26:29], v[164:167], v[196:199], v[26:29]
	v_mfma_f32_16x16x32_bf16 v[26:29], v[168:171], v[200:203], v[26:29]
	v_mfma_f32_16x16x32_bf16 v[18:21], v[172:175], v[196:199], v[18:21]
	v_mfma_f32_16x16x32_bf16 v[18:21], v[176:179], v[200:203], v[18:21]
	v_mfma_f32_16x16x32_bf16 v[10:13], v[164:167], v[208:211], v[10:13]
	v_mfma_f32_16x16x32_bf16 v[10:13], v[168:171], v[212:215], v[10:13]
	v_mfma_f32_16x16x32_bf16 v[2:5], v[172:175], v[208:211], v[2:5]
	v_mfma_f32_16x16x32_bf16 v[2:5], v[176:179], v[212:215], v[2:5]
	s_setprio 0
	s_barrier
	s_add_u32 s4, s4, 0x100
	s_addc_u32 s5, s5, 0
	s_add_u32 s42, s42, 0x100
	s_addc_u32 s43, s43, 0
	s_cmp_ge_i32 s44, s1
	s_mov_b32 s2, s44
	s_cbranch_scc0 .LBB0_267

.LBB0_524:
	s_lshl_b32 s0, s26, 20
	s_and_b32 s0, s0, 0xff00000
	s_add_u32 s0, s70, s0
	s_addc_u32 s23, s71, 0
	s_lshr_b32 s22, s26, 13
	s_and_b32 s24, s22, 0x7ff80
	s_add_u32 s22, s0, s24
	s_addc_u32 s23, s23, 0
	s_lshl_b32 s0, s26, 12
	s_and_b32 s0, s0, 0xff00000
	s_add_u32 s0, s30, s0
	s_addc_u32 s25, s31, 0
	s_add_u32 s24, s0, s24
	s_addc_u32 s25, s25, 0
	s_cmp_lt_i32 s37, 1
	v_cmp_gt_i64_e64 s[26:27], s[26:27], -1
	s_cbranch_scc1 .LBB0_546
	s_and_b64 s[40:41], s[26:27], exec
	s_cselect_b32 s0, s23, s39
	s_cselect_b32 s36, s22, s38
	s_cselect_b32 s65, s25, s3
	s_cselect_b32 s66, s24, s2
	s_add_i32 s67, s37, -2
	s_add_u32 s38, s38, 0x80080
	s_addc_u32 s39, s39, 0
	s_add_u32 s68, s2, 0x100
	s_addc_u32 s69, s3, 0
	s_mov_b32 s2, 0
	ds_read_b128 v[148:151], v144
	ds_read_b128 v[152:155], v144 offset:1024
	ds_read_b128 v[156:159], v144 offset:2048
	ds_read_b128 v[160:163], v144 offset:3072
	ds_read_b128 v[164:167], v145
	ds_read_b128 v[168:171], v145 offset:1024
	ds_read_b128 v[172:175], v145 offset:2048
	ds_read_b128 v[176:179], v145 offset:3072
	s_waitcnt lgkmcnt(0)
	s_add_i32 s72, s2, 2
	s_add_u32 s3, s38, 0xfff80080
	s_addc_u32 s40, s39, -1
	s_cmp_eq_u32 s67, s2
	s_cselect_b32 s2, s66, s68
	s_cselect_b32 s41, s0, s40
	s_cselect_b32 s40, s36, s3
	s_cselect_b32 s3, s65, s69
	s_add_i32 m0, s29, 0xc000
	ds_read_b128 v[180:183], v146
	ds_read_b128 v[184:187], v146 offset:1024
	ds_read_b128 v[188:191], v146 offset:2048
	ds_read_b128 v[192:195], v146 offset:3072
	ds_read_b128 v[196:199], v146 offset:4096
	ds_read_b128 v[200:203], v146 offset:5120
	ds_read_b128 v[208:211], v146 offset:6144
	ds_read_b128 v[212:215], v146 offset:7168
	global_load_lds_dwordx4 v138, s[38:39]
	s_add_i32 m0, s29, 0xe000
	s_nop 0
	global_load_lds_dwordx4 v140, s[38:39]
	s_waitcnt vmcnt(8)
	s_waitcnt lgkmcnt(0)
	s_barrier
	s_setprio 1
	s_waitcnt lgkmcnt(0)
	v_mfma_f32_16x16x32_bf16 v[126:129], v[148:151], v[180:183], 0
	v_mfma_f32_16x16x32_bf16 v[126:129], v[152:155], v[184:187], v[126:129]
	v_mfma_f32_16x16x32_bf16 v[122:125], v[156:159], v[180:183], 0
	v_mfma_f32_16x16x32_bf16 v[122:125], v[160:163], v[184:187], v[122:125]
	v_mfma_f32_16x16x32_bf16 v[110:113], v[148:151], v[188:191], 0
	v_mfma_f32_16x16x32_bf16 v[110:113], v[152:155], v[192:195], v[110:113]
	v_mfma_f32_16x16x32_bf16 v[102:105], v[156:159], v[188:191], 0
	v_mfma_f32_16x16x32_bf16 v[102:105], v[160:163], v[192:195], v[102:105]
	v_mfma_f32_16x16x32_bf16 v[94:97], v[148:151], v[196:199], 0
	v_mfma_f32_16x16x32_bf16 v[94:97], v[152:155], v[200:203], v[94:97]
	v_mfma_f32_16x16x32_bf16 v[86:89], v[156:159], v[196:199], 0
	v_mfma_f32_16x16x32_bf16 v[86:89], v[160:163], v[200:203], v[86:89]
	v_mfma_f32_16x16x32_bf16 v[78:81], v[148:151], v[208:211], 0
	v_mfma_f32_16x16x32_bf16 v[78:81], v[152:155], v[212:215], v[78:81]
	v_mfma_f32_16x16x32_bf16 v[70:73], v[156:159], v[208:211], 0
	v_mfma_f32_16x16x32_bf16 v[70:73], v[160:163], v[212:215], v[70:73]
	s_setprio 0
	s_setprio 1
	v_mfma_f32_16x16x32_bf16 v[118:121], v[164:167], v[180:183], 0
	v_mfma_f32_16x16x32_bf16 v[118:121], v[168:171], v[184:187], v[118:121]
	v_mfma_f32_16x16x32_bf16 v[114:117], v[172:175], v[180:183], 0
	v_mfma_f32_16x16x32_bf16 v[114:117], v[176:179], v[184:187], v[114:117]
	v_mfma_f32_16x16x32_bf16 v[106:109], v[164:167], v[188:191], 0
	v_mfma_f32_16x16x32_bf16 v[106:109], v[168:171], v[192:195], v[106:109]
	v_mfma_f32_16x16x32_bf16 v[98:101], v[172:175], v[188:191], 0
	v_mfma_f32_16x16x32_bf16 v[98:101], v[176:179], v[192:195], v[98:101]
	v_mfma_f32_16x16x32_bf16 v[90:93], v[164:167], v[196:199], 0
	v_mfma_f32_16x16x32_bf16 v[90:93], v[168:171], v[200:203], v[90:93]
	v_mfma_f32_16x16x32_bf16 v[82:85], v[172:175], v[196:199], 0
	v_mfma_f32_16x16x32_bf16 v[82:85], v[176:179], v[200:203], v[82:85]
	v_mfma_f32_16x16x32_bf16 v[74:77], v[164:167], v[208:211], 0
	v_mfma_f32_16x16x32_bf16 v[74:77], v[168:171], v[212:215], v[74:77]
	v_mfma_f32_16x16x32_bf16 v[66:69], v[172:175], v[208:211], 0
	v_mfma_f32_16x16x32_bf16 v[66:69], v[176:179], v[212:215], v[66:69]
	s_setprio 0
	s_barrier
	s_add_i32 s73, s52, s33
	s_mov_b32 m0, s73
	ds_read_b128 v[180:183], v146 offset:16384
	ds_read_b128 v[184:187], v146 offset:17408
	ds_read_b128 v[188:191], v146 offset:18432
	ds_read_b128 v[192:195], v146 offset:19456
	ds_read_b128 v[196:199], v146 offset:20480
	ds_read_b128 v[200:203], v146 offset:21504
	ds_read_b128 v[208:211], v146 offset:22528
	ds_read_b128 v[212:215], v146 offset:23552
	global_load_lds_dwordx4 v132, s[2:3]
	s_add_i32 m0, s73, 0x2000
	s_add_u32 s74, s2, 0x80000
	s_addc_u32 s75, s3, 0
	s_add_i32 s73, s53, s33
	global_load_lds_dwordx4 v136, s[2:3]
	s_mov_b32 m0, s73
	v_lshl_add_u64 v[220:221], s[40:41], 0, v[134:135]
	global_load_lds_dwordx4 v132, s[74:75]
	s_add_i32 m0, s73, 0x2000
	s_nop 0
	global_load_lds_dwordx4 v136, s[74:75]
	v_lshl_add_u64 v[218:219], s[40:41], 0, v[130:131]
	s_mov_b32 m0, s29
	s_nop 0
	global_load_lds_dwordx4 v130, s[40:41]
	s_mov_b32 m0, s35
	s_nop 0
	global_load_lds_dwordx4 v134, s[40:41]
	s_waitcnt vmcnt(8)
	s_waitcnt lgkmcnt(0)
	s_barrier
	s_setprio 1
	s_waitcnt lgkmcnt(0)
	v_mfma_f32_16x16x32_bf16 v[62:65], v[148:151], v[180:183], 0
	v_mfma_f32_16x16x32_bf16 v[62:65], v[152:155], v[184:187], v[62:65]
	v_mfma_f32_16x16x32_bf16 v[54:57], v[156:159], v[180:183], 0
	v_mfma_f32_16x16x32_bf16 v[54:57], v[160:163], v[184:187], v[54:57]
	v_mfma_f32_16x16x32_bf16 v[46:49], v[148:151], v[188:191], 0
	v_mfma_f32_16x16x32_bf16 v[46:49], v[152:155], v[192:195], v[46:49]
	v_mfma_f32_16x16x32_bf16 v[38:41], v[156:159], v[188:191], 0
	v_mfma_f32_16x16x32_bf16 v[38:41], v[160:163], v[192:195], v[38:41]
	v_mfma_f32_16x16x32_bf16 v[30:33], v[148:151], v[196:199], 0
	v_mfma_f32_16x16x32_bf16 v[30:33], v[152:155], v[200:203], v[30:33]
	v_mfma_f32_16x16x32_bf16 v[22:25], v[156:159], v[196:199], 0
	v_mfma_f32_16x16x32_bf16 v[22:25], v[160:163], v[200:203], v[22:25]
	v_mfma_f32_16x16x32_bf16 v[14:17], v[148:151], v[208:211], 0
	v_mfma_f32_16x16x32_bf16 v[14:17], v[152:155], v[212:215], v[14:17]
	v_mfma_f32_16x16x32_bf16 v[6:9], v[156:159], v[208:211], 0
	v_mfma_f32_16x16x32_bf16 v[6:9], v[160:163], v[212:215], v[6:9]
	s_setprio 0
	s_setprio 1
	v_mfma_f32_16x16x32_bf16 v[58:61], v[164:167], v[180:183], 0
	v_mfma_f32_16x16x32_bf16 v[58:61], v[168:171], v[184:187], v[58:61]
	v_mfma_f32_16x16x32_bf16 v[50:53], v[172:175], v[180:183], 0
	v_mfma_f32_16x16x32_bf16 v[50:53], v[176:179], v[184:187], v[50:53]
	v_mfma_f32_16x16x32_bf16 v[42:45], v[164:167], v[188:191], 0
	v_mfma_f32_16x16x32_bf16 v[42:45], v[168:171], v[192:195], v[42:45]
	v_mfma_f32_16x16x32_bf16 v[34:37], v[172:175], v[188:191], 0
	v_mfma_f32_16x16x32_bf16 v[34:37], v[176:179], v[192:195], v[34:37]
	v_mfma_f32_16x16x32_bf16 v[26:29], v[164:167], v[196:199], 0
	v_mfma_f32_16x16x32_bf16 v[26:29], v[168:171], v[200:203], v[26:29]
	v_mfma_f32_16x16x32_bf16 v[18:21], v[172:175], v[196:199], 0
	v_mfma_f32_16x16x32_bf16 v[18:21], v[176:179], v[200:203], v[18:21]
	v_mfma_f32_16x16x32_bf16 v[10:13], v[164:167], v[208:211], 0
	v_mfma_f32_16x16x32_bf16 v[10:13], v[168:171], v[212:215], v[10:13]
	v_mfma_f32_16x16x32_bf16 v[2:5], v[172:175], v[208:211], 0
	v_mfma_f32_16x16x32_bf16 v[2:5], v[176:179], v[212:215], v[2:5]
	s_setprio 0
	s_barrier
	s_add_i32 s73, 0, 0x18000
	v_add_u32_e32 v147, s73, v142
	s_add_i32 s74, 0, 0x1c000
	ds_read_b128 v[148:151], v147
	ds_read_b128 v[152:155], v147 offset:1024
	ds_read_b128 v[156:159], v147 offset:2048
	ds_read_b128 v[160:163], v147 offset:3072
	v_add_u32_e32 v147, s74, v142
	ds_read_b128 v[164:167], v147
	ds_read_b128 v[168:171], v147 offset:1024
	ds_read_b128 v[172:175], v147 offset:2048
	ds_read_b128 v[176:179], v147 offset:3072
	s_add_u32 s40, s40, 0x80000
	s_addc_u32 s41, s41, 0
	s_mov_b32 m0, s43
	ds_read_b128 v[180:183], v146 offset:32768
	ds_read_b128 v[184:187], v146 offset:33792
	ds_read_b128 v[188:191], v146 offset:34816
	ds_read_b128 v[192:195], v146 offset:35840
	ds_read_b128 v[196:199], v146 offset:36864
	ds_read_b128 v[200:203], v146 offset:37888
	ds_read_b128 v[208:211], v146 offset:38912
	ds_read_b128 v[212:215], v146 offset:39936
	global_load_lds_dwordx4 v130, s[40:41]
	s_mov_b32 m0, s44
	s_nop 0
	global_load_lds_dwordx4 v134, s[40:41]
	s_waitcnt vmcnt(8)
	s_waitcnt lgkmcnt(0)
	s_barrier
	s_setprio 1
	s_waitcnt lgkmcnt(0)
	v_mfma_f32_16x16x32_bf16 v[126:129], v[148:151], v[180:183], v[126:129]
	v_mfma_f32_16x16x32_bf16 v[126:129], v[152:155], v[184:187], v[126:129]
	v_mfma_f32_16x16x32_bf16 v[122:125], v[156:159], v[180:183], v[122:125]
	v_mfma_f32_16x16x32_bf16 v[122:125], v[160:163], v[184:187], v[122:125]
	v_mfma_f32_16x16x32_bf16 v[110:113], v[148:151], v[188:191], v[110:113]
	v_mfma_f32_16x16x32_bf16 v[110:113], v[152:155], v[192:195], v[110:113]
	v_mfma_f32_16x16x32_bf16 v[102:105], v[156:159], v[188:191], v[102:105]
	v_mfma_f32_16x16x32_bf16 v[102:105], v[160:163], v[192:195], v[102:105]
	v_mfma_f32_16x16x32_bf16 v[94:97], v[148:151], v[196:199], v[94:97]
	v_mfma_f32_16x16x32_bf16 v[94:97], v[152:155], v[200:203], v[94:97]
	v_mfma_f32_16x16x32_bf16 v[86:89], v[156:159], v[196:199], v[86:89]
	v_mfma_f32_16x16x32_bf16 v[86:89], v[160:163], v[200:203], v[86:89]
	v_mfma_f32_16x16x32_bf16 v[78:81], v[148:151], v[208:211], v[78:81]
	v_mfma_f32_16x16x32_bf16 v[78:81], v[152:155], v[212:215], v[78:81]
	v_mfma_f32_16x16x32_bf16 v[70:73], v[156:159], v[208:211], v[70:73]
	v_mfma_f32_16x16x32_bf16 v[70:73], v[160:163], v[212:215], v[70:73]
	s_setprio 0
	s_setprio 1
	v_mfma_f32_16x16x32_bf16 v[118:121], v[164:167], v[180:183], v[118:121]
	v_mfma_f32_16x16x32_bf16 v[118:121], v[168:171], v[184:187], v[118:121]
	v_mfma_f32_16x16x32_bf16 v[114:117], v[172:175], v[180:183], v[114:117]
	v_mfma_f32_16x16x32_bf16 v[114:117], v[176:179], v[184:187], v[114:117]
	v_mfma_f32_16x16x32_bf16 v[106:109], v[164:167], v[188:191], v[106:109]
	v_mfma_f32_16x16x32_bf16 v[106:109], v[168:171], v[192:195], v[106:109]
	v_mfma_f32_16x16x32_bf16 v[98:101], v[172:175], v[188:191], v[98:101]
	v_mfma_f32_16x16x32_bf16 v[98:101], v[176:179], v[192:195], v[98:101]
	v_mfma_f32_16x16x32_bf16 v[90:93], v[164:167], v[196:199], v[90:93]
	v_mfma_f32_16x16x32_bf16 v[90:93], v[168:171], v[200:203], v[90:93]
	v_mfma_f32_16x16x32_bf16 v[82:85], v[172:175], v[196:199], v[82:85]
	v_mfma_f32_16x16x32_bf16 v[82:85], v[176:179], v[200:203], v[82:85]
	v_mfma_f32_16x16x32_bf16 v[74:77], v[164:167], v[208:211], v[74:77]
	v_mfma_f32_16x16x32_bf16 v[74:77], v[168:171], v[212:215], v[74:77]
	v_mfma_f32_16x16x32_bf16 v[66:69], v[172:175], v[208:211], v[66:69]
	v_mfma_f32_16x16x32_bf16 v[66:69], v[176:179], v[212:215], v[66:69]
	s_setprio 0
	s_barrier
	s_add_i32 s40, s73, s33
	s_add_u32 s98, s2, s16
	s_addc_u32 s99, s3, s17
	s_mov_b32 m0, s40
	ds_read_b128 v[180:183], v146 offset:49152
	ds_read_b128 v[184:187], v146 offset:50176
	ds_read_b128 v[188:191], v146 offset:51200
	ds_read_b128 v[192:195], v146 offset:52224
	ds_read_b128 v[196:199], v146 offset:53248
	ds_read_b128 v[200:203], v146 offset:54272
	ds_read_b128 v[208:211], v146 offset:55296
	ds_read_b128 v[212:215], v146 offset:56320
	global_load_lds_dwordx4 v132, s[98:99]
	s_add_i32 m0, s40, 0x2000
	s_add_u32 s2, s2, 0x80080
	s_addc_u32 s3, s3, 0
	s_add_i32 s40, s74, s33
	global_load_lds_dwordx4 v136, s[98:99]
	s_mov_b32 m0, s40
	s_nop 0
	global_load_lds_dwordx4 v132, s[2:3]
	s_add_i32 m0, s40, 0x2000
	s_nop 0
	global_load_lds_dwordx4 v136, s[2:3]
	v_lshl_add_u64 v[204:205], v[218:219], 0, s[16:17]
	s_mov_b32 m0, s46
	s_nop 0
	global_load_lds_dwordx4 v[204:205], off
	v_lshl_add_u64 v[204:205], v[220:221], 0, s[16:17]
	s_mov_b32 m0, s47
	s_nop 0
	global_load_lds_dwordx4 v[204:205], off
	s_waitcnt vmcnt(8)
	s_waitcnt lgkmcnt(0)
	s_barrier
	s_setprio 1
	s_waitcnt lgkmcnt(0)
	v_mfma_f32_16x16x32_bf16 v[62:65], v[148:151], v[180:183], v[62:65]
	v_mfma_f32_16x16x32_bf16 v[62:65], v[152:155], v[184:187], v[62:65]
	v_mfma_f32_16x16x32_bf16 v[54:57], v[156:159], v[180:183], v[54:57]
	v_mfma_f32_16x16x32_bf16 v[54:57], v[160:163], v[184:187], v[54:57]
	v_mfma_f32_16x16x32_bf16 v[46:49], v[148:151], v[188:191], v[46:49]
	v_mfma_f32_16x16x32_bf16 v[46:49], v[152:155], v[192:195], v[46:49]
	v_mfma_f32_16x16x32_bf16 v[38:41], v[156:159], v[188:191], v[38:41]
	v_mfma_f32_16x16x32_bf16 v[38:41], v[160:163], v[192:195], v[38:41]
	v_mfma_f32_16x16x32_bf16 v[30:33], v[148:151], v[196:199], v[30:33]
	v_mfma_f32_16x16x32_bf16 v[30:33], v[152:155], v[200:203], v[30:33]
	v_mfma_f32_16x16x32_bf16 v[22:25], v[156:159], v[196:199], v[22:25]
	v_mfma_f32_16x16x32_bf16 v[22:25], v[160:163], v[200:203], v[22:25]
	v_mfma_f32_16x16x32_bf16 v[14:17], v[148:151], v[208:211], v[14:17]
	v_mfma_f32_16x16x32_bf16 v[14:17], v[152:155], v[212:215], v[14:17]
	v_mfma_f32_16x16x32_bf16 v[6:9], v[156:159], v[208:211], v[6:9]
	v_mfma_f32_16x16x32_bf16 v[6:9], v[160:163], v[212:215], v[6:9]
	s_setprio 0
	s_setprio 1
	v_mfma_f32_16x16x32_bf16 v[58:61], v[164:167], v[180:183], v[58:61]
	v_mfma_f32_16x16x32_bf16 v[58:61], v[168:171], v[184:187], v[58:61]
	v_mfma_f32_16x16x32_bf16 v[50:53], v[172:175], v[180:183], v[50:53]
	v_mfma_f32_16x16x32_bf16 v[50:53], v[176:179], v[184:187], v[50:53]
	v_mfma_f32_16x16x32_bf16 v[42:45], v[164:167], v[188:191], v[42:45]
	v_mfma_f32_16x16x32_bf16 v[42:45], v[168:171], v[192:195], v[42:45]
	v_mfma_f32_16x16x32_bf16 v[34:37], v[172:175], v[188:191], v[34:37]
	v_mfma_f32_16x16x32_bf16 v[34:37], v[176:179], v[192:195], v[34:37]
	v_mfma_f32_16x16x32_bf16 v[26:29], v[164:167], v[196:199], v[26:29]
	v_mfma_f32_16x16x32_bf16 v[26:29], v[168:171], v[200:203], v[26:29]
	v_mfma_f32_16x16x32_bf16 v[18:21], v[172:175], v[196:199], v[18:21]
	v_mfma_f32_16x16x32_bf16 v[18:21], v[176:179], v[200:203], v[18:21]
	v_mfma_f32_16x16x32_bf16 v[10:13], v[164:167], v[208:211], v[10:13]
	v_mfma_f32_16x16x32_bf16 v[10:13], v[168:171], v[212:215], v[10:13]
	v_mfma_f32_16x16x32_bf16 v[2:5], v[172:175], v[208:211], v[2:5]
	v_mfma_f32_16x16x32_bf16 v[2:5], v[176:179], v[212:215], v[2:5]
	s_setprio 0
	s_barrier
	s_add_u32 s38, s38, 0x100
	s_addc_u32 s39, s39, 0
	s_add_u32 s68, s68, 0x100
	s_addc_u32 s69, s69, 0
	s_cmp_ge_i32 s72, s37
	s_mov_b32 s2, s72
	s_cbranch_scc1 .Lkpeel_exit_2
.LBB0_526:
	ds_read_b128 v[148:151], v144
	ds_read_b128 v[152:155], v144 offset:1024
	ds_read_b128 v[156:159], v144 offset:2048
	ds_read_b128 v[160:163], v144 offset:3072
	ds_read_b128 v[164:167], v145
	ds_read_b128 v[168:171], v145 offset:1024
	ds_read_b128 v[172:175], v145 offset:2048
	ds_read_b128 v[176:179], v145 offset:3072
	s_waitcnt lgkmcnt(0)
	s_add_i32 s72, s2, 2
	s_add_u32 s3, s38, 0xfff80080
	s_addc_u32 s40, s39, -1
	s_cmp_eq_u32 s67, s2
	s_cselect_b32 s2, s66, s68
	s_cselect_b32 s41, s0, s40
	s_cselect_b32 s40, s36, s3
	s_cselect_b32 s3, s65, s69
	s_add_i32 m0, s29, 0xc000
	ds_read_b128 v[180:183], v146
	ds_read_b128 v[184:187], v146 offset:1024
	ds_read_b128 v[188:191], v146 offset:2048
	ds_read_b128 v[192:195], v146 offset:3072
	ds_read_b128 v[196:199], v146 offset:4096
	ds_read_b128 v[200:203], v146 offset:5120
	ds_read_b128 v[208:211], v146 offset:6144
	ds_read_b128 v[212:215], v146 offset:7168
	global_load_lds_dwordx4 v138, s[38:39]
	s_add_i32 m0, s29, 0xe000
	s_nop 0
	global_load_lds_dwordx4 v140, s[38:39]
	s_waitcnt vmcnt(8)
	s_waitcnt lgkmcnt(0)
	s_barrier
	s_setprio 1
	s_waitcnt lgkmcnt(0)
	v_mfma_f32_16x16x32_bf16 v[126:129], v[148:151], v[180:183], v[126:129]
	v_mfma_f32_16x16x32_bf16 v[126:129], v[152:155], v[184:187], v[126:129]
	v_mfma_f32_16x16x32_bf16 v[122:125], v[156:159], v[180:183], v[122:125]
	v_mfma_f32_16x16x32_bf16 v[122:125], v[160:163], v[184:187], v[122:125]
	v_mfma_f32_16x16x32_bf16 v[110:113], v[148:151], v[188:191], v[110:113]
	v_mfma_f32_16x16x32_bf16 v[110:113], v[152:155], v[192:195], v[110:113]
	v_mfma_f32_16x16x32_bf16 v[102:105], v[156:159], v[188:191], v[102:105]
	v_mfma_f32_16x16x32_bf16 v[102:105], v[160:163], v[192:195], v[102:105]
	v_mfma_f32_16x16x32_bf16 v[94:97], v[148:151], v[196:199], v[94:97]
	v_mfma_f32_16x16x32_bf16 v[94:97], v[152:155], v[200:203], v[94:97]
	v_mfma_f32_16x16x32_bf16 v[86:89], v[156:159], v[196:199], v[86:89]
	v_mfma_f32_16x16x32_bf16 v[86:89], v[160:163], v[200:203], v[86:89]
	v_mfma_f32_16x16x32_bf16 v[78:81], v[148:151], v[208:211], v[78:81]
	v_mfma_f32_16x16x32_bf16 v[78:81], v[152:155], v[212:215], v[78:81]
	v_mfma_f32_16x16x32_bf16 v[70:73], v[156:159], v[208:211], v[70:73]
	v_mfma_f32_16x16x32_bf16 v[70:73], v[160:163], v[212:215], v[70:73]
	s_setprio 0
	s_setprio 1
	v_mfma_f32_16x16x32_bf16 v[118:121], v[164:167], v[180:183], v[118:121]
	v_mfma_f32_16x16x32_bf16 v[118:121], v[168:171], v[184:187], v[118:121]
	v_mfma_f32_16x16x32_bf16 v[114:117], v[172:175], v[180:183], v[114:117]
	v_mfma_f32_16x16x32_bf16 v[114:117], v[176:179], v[184:187], v[114:117]
	v_mfma_f32_16x16x32_bf16 v[106:109], v[164:167], v[188:191], v[106:109]
	v_mfma_f32_16x16x32_bf16 v[106:109], v[168:171], v[192:195], v[106:109]
	v_mfma_f32_16x16x32_bf16 v[98:101], v[172:175], v[188:191], v[98:101]
	v_mfma_f32_16x16x32_bf16 v[98:101], v[176:179], v[192:195], v[98:101]
	v_mfma_f32_16x16x32_bf16 v[90:93], v[164:167], v[196:199], v[90:93]
	v_mfma_f32_16x16x32_bf16 v[90:93], v[168:171], v[200:203], v[90:93]
	v_mfma_f32_16x16x32_bf16 v[82:85], v[172:175], v[196:199], v[82:85]
	v_mfma_f32_16x16x32_bf16 v[82:85], v[176:179], v[200:203], v[82:85]
	v_mfma_f32_16x16x32_bf16 v[74:77], v[164:167], v[208:211], v[74:77]
	v_mfma_f32_16x16x32_bf16 v[74:77], v[168:171], v[212:215], v[74:77]
	v_mfma_f32_16x16x32_bf16 v[66:69], v[172:175], v[208:211], v[66:69]
	v_mfma_f32_16x16x32_bf16 v[66:69], v[176:179], v[212:215], v[66:69]
	s_setprio 0
	s_barrier
	s_add_i32 s73, s52, s33
	s_mov_b32 m0, s73
	ds_read_b128 v[180:183], v146 offset:16384
	ds_read_b128 v[184:187], v146 offset:17408
	ds_read_b128 v[188:191], v146 offset:18432
	ds_read_b128 v[192:195], v146 offset:19456
	ds_read_b128 v[196:199], v146 offset:20480
	ds_read_b128 v[200:203], v146 offset:21504
	ds_read_b128 v[208:211], v146 offset:22528
	ds_read_b128 v[212:215], v146 offset:23552
	global_load_lds_dwordx4 v132, s[2:3]
	s_add_i32 m0, s73, 0x2000
	s_add_u32 s74, s2, 0x80000
	s_addc_u32 s75, s3, 0
	s_add_i32 s73, s53, s33
	global_load_lds_dwordx4 v136, s[2:3]
	s_mov_b32 m0, s73
	v_lshl_add_u64 v[220:221], s[40:41], 0, v[134:135]
	global_load_lds_dwordx4 v132, s[74:75]
	s_add_i32 m0, s73, 0x2000
	s_nop 0
	global_load_lds_dwordx4 v136, s[74:75]
	v_lshl_add_u64 v[218:219], s[40:41], 0, v[130:131]
	s_mov_b32 m0, s29
	s_nop 0
	global_load_lds_dwordx4 v130, s[40:41]
	s_mov_b32 m0, s35
	s_nop 0
	global_load_lds_dwordx4 v134, s[40:41]
	s_waitcnt vmcnt(8)
	s_waitcnt lgkmcnt(0)
	s_barrier
	s_setprio 1
	s_waitcnt lgkmcnt(0)
	v_mfma_f32_16x16x32_bf16 v[62:65], v[148:151], v[180:183], v[62:65]
	v_mfma_f32_16x16x32_bf16 v[62:65], v[152:155], v[184:187], v[62:65]
	v_mfma_f32_16x16x32_bf16 v[54:57], v[156:159], v[180:183], v[54:57]
	v_mfma_f32_16x16x32_bf16 v[54:57], v[160:163], v[184:187], v[54:57]
	v_mfma_f32_16x16x32_bf16 v[46:49], v[148:151], v[188:191], v[46:49]
	v_mfma_f32_16x16x32_bf16 v[46:49], v[152:155], v[192:195], v[46:49]
	v_mfma_f32_16x16x32_bf16 v[38:41], v[156:159], v[188:191], v[38:41]
	v_mfma_f32_16x16x32_bf16 v[38:41], v[160:163], v[192:195], v[38:41]
	v_mfma_f32_16x16x32_bf16 v[30:33], v[148:151], v[196:199], v[30:33]
	v_mfma_f32_16x16x32_bf16 v[30:33], v[152:155], v[200:203], v[30:33]
	v_mfma_f32_16x16x32_bf16 v[22:25], v[156:159], v[196:199], v[22:25]
	v_mfma_f32_16x16x32_bf16 v[22:25], v[160:163], v[200:203], v[22:25]
	v_mfma_f32_16x16x32_bf16 v[14:17], v[148:151], v[208:211], v[14:17]
	v_mfma_f32_16x16x32_bf16 v[14:17], v[152:155], v[212:215], v[14:17]
	v_mfma_f32_16x16x32_bf16 v[6:9], v[156:159], v[208:211], v[6:9]
	v_mfma_f32_16x16x32_bf16 v[6:9], v[160:163], v[212:215], v[6:9]
	s_setprio 0
	s_setprio 1
	v_mfma_f32_16x16x32_bf16 v[58:61], v[164:167], v[180:183], v[58:61]
	v_mfma_f32_16x16x32_bf16 v[58:61], v[168:171], v[184:187], v[58:61]
	v_mfma_f32_16x16x32_bf16 v[50:53], v[172:175], v[180:183], v[50:53]
	v_mfma_f32_16x16x32_bf16 v[50:53], v[176:179], v[184:187], v[50:53]
	v_mfma_f32_16x16x32_bf16 v[42:45], v[164:167], v[188:191], v[42:45]
	v_mfma_f32_16x16x32_bf16 v[42:45], v[168:171], v[192:195], v[42:45]
	v_mfma_f32_16x16x32_bf16 v[34:37], v[172:175], v[188:191], v[34:37]
	v_mfma_f32_16x16x32_bf16 v[34:37], v[176:179], v[192:195], v[34:37]
	v_mfma_f32_16x16x32_bf16 v[26:29], v[164:167], v[196:199], v[26:29]
	v_mfma_f32_16x16x32_bf16 v[26:29], v[168:171], v[200:203], v[26:29]
	v_mfma_f32_16x16x32_bf16 v[18:21], v[172:175], v[196:199], v[18:21]
	v_mfma_f32_16x16x32_bf16 v[18:21], v[176:179], v[200:203], v[18:21]
	v_mfma_f32_16x16x32_bf16 v[10:13], v[164:167], v[208:211], v[10:13]
	v_mfma_f32_16x16x32_bf16 v[10:13], v[168:171], v[212:215], v[10:13]
	v_mfma_f32_16x16x32_bf16 v[2:5], v[172:175], v[208:211], v[2:5]
	v_mfma_f32_16x16x32_bf16 v[2:5], v[176:179], v[212:215], v[2:5]
	s_setprio 0
	s_barrier
	s_add_i32 s73, 0, 0x18000
	v_add_u32_e32 v147, s73, v142
	s_add_i32 s74, 0, 0x1c000
	ds_read_b128 v[148:151], v147
	ds_read_b128 v[152:155], v147 offset:1024
	ds_read_b128 v[156:159], v147 offset:2048
	ds_read_b128 v[160:163], v147 offset:3072
	v_add_u32_e32 v147, s74, v142
	ds_read_b128 v[164:167], v147
	ds_read_b128 v[168:171], v147 offset:1024
	ds_read_b128 v[172:175], v147 offset:2048
	ds_read_b128 v[176:179], v147 offset:3072
	s_add_u32 s40, s40, 0x80000
	s_addc_u32 s41, s41, 0
	s_mov_b32 m0, s43
	ds_read_b128 v[180:183], v146 offset:32768
	ds_read_b128 v[184:187], v146 offset:33792
	ds_read_b128 v[188:191], v146 offset:34816
	ds_read_b128 v[192:195], v146 offset:35840
	ds_read_b128 v[196:199], v146 offset:36864
	ds_read_b128 v[200:203], v146 offset:37888
	ds_read_b128 v[208:211], v146 offset:38912
	ds_read_b128 v[212:215], v146 offset:39936
	global_load_lds_dwordx4 v130, s[40:41]
	s_mov_b32 m0, s44
	s_nop 0
	global_load_lds_dwordx4 v134, s[40:41]
	s_waitcnt vmcnt(8)
	s_waitcnt lgkmcnt(0)
	s_barrier
	s_setprio 1
	s_waitcnt lgkmcnt(0)
	v_mfma_f32_16x16x32_bf16 v[126:129], v[148:151], v[180:183], v[126:129]
	v_mfma_f32_16x16x32_bf16 v[126:129], v[152:155], v[184:187], v[126:129]
	v_mfma_f32_16x16x32_bf16 v[122:125], v[156:159], v[180:183], v[122:125]
	v_mfma_f32_16x16x32_bf16 v[122:125], v[160:163], v[184:187], v[122:125]
	v_mfma_f32_16x16x32_bf16 v[110:113], v[148:151], v[188:191], v[110:113]
	v_mfma_f32_16x16x32_bf16 v[110:113], v[152:155], v[192:195], v[110:113]
	v_mfma_f32_16x16x32_bf16 v[102:105], v[156:159], v[188:191], v[102:105]
	v_mfma_f32_16x16x32_bf16 v[102:105], v[160:163], v[192:195], v[102:105]
	v_mfma_f32_16x16x32_bf16 v[94:97], v[148:151], v[196:199], v[94:97]
	v_mfma_f32_16x16x32_bf16 v[94:97], v[152:155], v[200:203], v[94:97]
	v_mfma_f32_16x16x32_bf16 v[86:89], v[156:159], v[196:199], v[86:89]
	v_mfma_f32_16x16x32_bf16 v[86:89], v[160:163], v[200:203], v[86:89]
	v_mfma_f32_16x16x32_bf16 v[78:81], v[148:151], v[208:211], v[78:81]
	v_mfma_f32_16x16x32_bf16 v[78:81], v[152:155], v[212:215], v[78:81]
	v_mfma_f32_16x16x32_bf16 v[70:73], v[156:159], v[208:211], v[70:73]
	v_mfma_f32_16x16x32_bf16 v[70:73], v[160:163], v[212:215], v[70:73]
	s_setprio 0
	s_setprio 1
	v_mfma_f32_16x16x32_bf16 v[118:121], v[164:167], v[180:183], v[118:121]
	v_mfma_f32_16x16x32_bf16 v[118:121], v[168:171], v[184:187], v[118:121]
	v_mfma_f32_16x16x32_bf16 v[114:117], v[172:175], v[180:183], v[114:117]
	v_mfma_f32_16x16x32_bf16 v[114:117], v[176:179], v[184:187], v[114:117]
	v_mfma_f32_16x16x32_bf16 v[106:109], v[164:167], v[188:191], v[106:109]
	v_mfma_f32_16x16x32_bf16 v[106:109], v[168:171], v[192:195], v[106:109]
	v_mfma_f32_16x16x32_bf16 v[98:101], v[172:175], v[188:191], v[98:101]
	v_mfma_f32_16x16x32_bf16 v[98:101], v[176:179], v[192:195], v[98:101]
	v_mfma_f32_16x16x32_bf16 v[90:93], v[164:167], v[196:199], v[90:93]
	v_mfma_f32_16x16x32_bf16 v[90:93], v[168:171], v[200:203], v[90:93]
	v_mfma_f32_16x16x32_bf16 v[82:85], v[172:175], v[196:199], v[82:85]
	v_mfma_f32_16x16x32_bf16 v[82:85], v[176:179], v[200:203], v[82:85]
	v_mfma_f32_16x16x32_bf16 v[74:77], v[164:167], v[208:211], v[74:77]
	v_mfma_f32_16x16x32_bf16 v[74:77], v[168:171], v[212:215], v[74:77]
	v_mfma_f32_16x16x32_bf16 v[66:69], v[172:175], v[208:211], v[66:69]
	v_mfma_f32_16x16x32_bf16 v[66:69], v[176:179], v[212:215], v[66:69]
	s_setprio 0
	s_barrier
	s_add_i32 s40, s73, s33
	s_add_u32 s98, s2, s16
	s_addc_u32 s99, s3, s17
	s_mov_b32 m0, s40
	ds_read_b128 v[180:183], v146 offset:49152
	ds_read_b128 v[184:187], v146 offset:50176
	ds_read_b128 v[188:191], v146 offset:51200
	ds_read_b128 v[192:195], v146 offset:52224
	ds_read_b128 v[196:199], v146 offset:53248
	ds_read_b128 v[200:203], v146 offset:54272
	ds_read_b128 v[208:211], v146 offset:55296
	ds_read_b128 v[212:215], v146 offset:56320
	global_load_lds_dwordx4 v132, s[98:99]
	s_add_i32 m0, s40, 0x2000
	s_add_u32 s2, s2, 0x80080
	s_addc_u32 s3, s3, 0
	s_add_i32 s40, s74, s33
	global_load_lds_dwordx4 v136, s[98:99]
	s_mov_b32 m0, s40
	s_nop 0
	global_load_lds_dwordx4 v132, s[2:3]
	s_add_i32 m0, s40, 0x2000
	s_nop 0
	global_load_lds_dwordx4 v136, s[2:3]
	v_lshl_add_u64 v[204:205], v[218:219], 0, s[16:17]
	s_mov_b32 m0, s46
	s_nop 0
	global_load_lds_dwordx4 v[204:205], off
	v_lshl_add_u64 v[204:205], v[220:221], 0, s[16:17]
	s_mov_b32 m0, s47
	s_nop 0
	global_load_lds_dwordx4 v[204:205], off
	s_waitcnt vmcnt(8)
	s_waitcnt lgkmcnt(0)
	s_barrier
	s_setprio 1
	s_waitcnt lgkmcnt(0)
	v_mfma_f32_16x16x32_bf16 v[62:65], v[148:151], v[180:183], v[62:65]
	v_mfma_f32_16x16x32_bf16 v[62:65], v[152:155], v[184:187], v[62:65]
	v_mfma_f32_16x16x32_bf16 v[54:57], v[156:159], v[180:183], v[54:57]
	v_mfma_f32_16x16x32_bf16 v[54:57], v[160:163], v[184:187], v[54:57]
	v_mfma_f32_16x16x32_bf16 v[46:49], v[148:151], v[188:191], v[46:49]
	v_mfma_f32_16x16x32_bf16 v[46:49], v[152:155], v[192:195], v[46:49]
	v_mfma_f32_16x16x32_bf16 v[38:41], v[156:159], v[188:191], v[38:41]
	v_mfma_f32_16x16x32_bf16 v[38:41], v[160:163], v[192:195], v[38:41]
	v_mfma_f32_16x16x32_bf16 v[30:33], v[148:151], v[196:199], v[30:33]
	v_mfma_f32_16x16x32_bf16 v[30:33], v[152:155], v[200:203], v[30:33]
	v_mfma_f32_16x16x32_bf16 v[22:25], v[156:159], v[196:199], v[22:25]
	v_mfma_f32_16x16x32_bf16 v[22:25], v[160:163], v[200:203], v[22:25]
	v_mfma_f32_16x16x32_bf16 v[14:17], v[148:151], v[208:211], v[14:17]
	v_mfma_f32_16x16x32_bf16 v[14:17], v[152:155], v[212:215], v[14:17]
	v_mfma_f32_16x16x32_bf16 v[6:9], v[156:159], v[208:211], v[6:9]
	v_mfma_f32_16x16x32_bf16 v[6:9], v[160:163], v[212:215], v[6:9]
	s_setprio 0
	s_setprio 1
	v_mfma_f32_16x16x32_bf16 v[58:61], v[164:167], v[180:183], v[58:61]
	v_mfma_f32_16x16x32_bf16 v[58:61], v[168:171], v[184:187], v[58:61]
	v_mfma_f32_16x16x32_bf16 v[50:53], v[172:175], v[180:183], v[50:53]
	v_mfma_f32_16x16x32_bf16 v[50:53], v[176:179], v[184:187], v[50:53]
	v_mfma_f32_16x16x32_bf16 v[42:45], v[164:167], v[188:191], v[42:45]
	v_mfma_f32_16x16x32_bf16 v[42:45], v[168:171], v[192:195], v[42:45]
	v_mfma_f32_16x16x32_bf16 v[34:37], v[172:175], v[188:191], v[34:37]
	v_mfma_f32_16x16x32_bf16 v[34:37], v[176:179], v[192:195], v[34:37]
	v_mfma_f32_16x16x32_bf16 v[26:29], v[164:167], v[196:199], v[26:29]
	v_mfma_f32_16x16x32_bf16 v[26:29], v[168:171], v[200:203], v[26:29]
	v_mfma_f32_16x16x32_bf16 v[18:21], v[172:175], v[196:199], v[18:21]
	v_mfma_f32_16x16x32_bf16 v[18:21], v[176:179], v[200:203], v[18:21]
	v_mfma_f32_16x16x32_bf16 v[10:13], v[164:167], v[208:211], v[10:13]
	v_mfma_f32_16x16x32_bf16 v[10:13], v[168:171], v[212:215], v[10:13]
	v_mfma_f32_16x16x32_bf16 v[2:5], v[172:175], v[208:211], v[2:5]
	v_mfma_f32_16x16x32_bf16 v[2:5], v[176:179], v[212:215], v[2:5]
	s_setprio 0
	s_barrier
	s_add_u32 s38, s38, 0x100
	s_addc_u32 s39, s39, 0
	s_add_u32 s68, s68, 0x100
	s_addc_u32 s69, s69, 0
	s_cmp_ge_i32 s72, s37
	s_mov_b32 s2, s72
	s_cbranch_scc0 .LBB0_526

.LBB0_632:
	s_lshl_b32 s11, s26, 20
	s_and_b32 s11, s11, 0xff00000
	v_readlane_b32 s46, v248, 20
	v_readlane_b32 s47, v248, 21
	s_add_u32 s11, s46, s11
	v_cmp_gt_i64_e64 s[0:1], s[26:27], -1
	s_addc_u32 s16, s47, 0
	s_lshr_b32 s27, s26, 13
	s_and_b32 s27, s27, 0x7ff80
	s_add_u32 s76, s11, s27
	s_addc_u32 s77, s16, 0
	s_lshl_b32 s11, s26, 12
	s_and_b32 s11, s11, 0xff00000
	s_add_u32 s11, s60, s11
	s_addc_u32 s16, s61, 0
	s_add_u32 s78, s11, s27
	s_addc_u32 s79, s16, 0
	s_cmp_lt_i32 s17, 1
	s_cbranch_scc1 .LBB0_640
	s_and_b64 s[26:27], s[0:1], exec
	s_cselect_b32 s11, s77, s19
	s_cselect_b32 s16, s76, s18
	s_cselect_b32 s46, s79, s3
	s_cselect_b32 s47, s78, s2
	s_add_i32 s50, s17, -2
	s_add_u32 s18, s18, 0x80080
	s_addc_u32 s19, s19, 0
	s_add_u32 s51, s2, 0x100
	s_addc_u32 s52, s3, 0
	s_mov_b32 s2, 0
	ds_read_b128 v[130:133], v197
	ds_read_b128 v[134:137], v197 offset:1024
	ds_read_b128 v[138:141], v197 offset:2048
	ds_read_b128 v[142:145], v197 offset:3072
	ds_read_b128 v[146:149], v198
	ds_read_b128 v[150:153], v198 offset:1024
	ds_read_b128 v[154:157], v198 offset:2048
	ds_read_b128 v[170:173], v198 offset:3072
	s_add_i32 s53, s2, 2
	s_add_u32 s3, s18, 0xfff80080
	s_addc_u32 s26, s19, -1
	s_cmp_eq_u32 s50, s2
	s_cselect_b32 s2, s47, s51
	s_cselect_b32 s27, s11, s26
	s_cselect_b32 s26, s16, s3
	s_cselect_b32 s3, s46, s52
	s_add_i32 m0, s13, 0xc000
	ds_read_b128 v[174:177], v199
	ds_read_b128 v[178:181], v199 offset:1024
	ds_read_b128 v[182:185], v199 offset:2048
	ds_read_b128 v[186:189], v199 offset:3072
	ds_read_b128 v[190:193], v199 offset:4096
	ds_read_b128 v[200:203], v199 offset:5120
	ds_read_b128 v[208:211], v199 offset:6144
	ds_read_b128 v[212:215], v199 offset:7168
	global_load_lds_dwordx4 v166, s[18:19]
	s_add_i32 m0, s13, 0xe000
	s_nop 0
	global_load_lds_dwordx4 v168, s[18:19]
	s_waitcnt vmcnt(8)
	s_waitcnt lgkmcnt(0)
	s_barrier
	s_setprio 1
	s_waitcnt lgkmcnt(0)
	v_mfma_f32_16x16x32_bf16 v[122:125], v[130:133], v[174:177], 0
	v_mfma_f32_16x16x32_bf16 v[122:125], v[134:137], v[178:181], v[122:125]
	v_mfma_f32_16x16x32_bf16 v[114:117], v[138:141], v[174:177], 0
	v_mfma_f32_16x16x32_bf16 v[114:117], v[142:145], v[178:181], v[114:117]
	v_mfma_f32_16x16x32_bf16 v[106:109], v[130:133], v[182:185], 0
	v_mfma_f32_16x16x32_bf16 v[106:109], v[134:137], v[186:189], v[106:109]
	v_mfma_f32_16x16x32_bf16 v[98:101], v[138:141], v[182:185], 0
	v_mfma_f32_16x16x32_bf16 v[98:101], v[142:145], v[186:189], v[98:101]
	v_mfma_f32_16x16x32_bf16 v[90:93], v[130:133], v[190:193], 0
	v_mfma_f32_16x16x32_bf16 v[90:93], v[134:137], v[200:203], v[90:93]
	v_mfma_f32_16x16x32_bf16 v[82:85], v[138:141], v[190:193], 0
	v_mfma_f32_16x16x32_bf16 v[82:85], v[142:145], v[200:203], v[82:85]
	v_mfma_f32_16x16x32_bf16 v[74:77], v[130:133], v[208:211], 0
	v_mfma_f32_16x16x32_bf16 v[74:77], v[134:137], v[212:215], v[74:77]
	v_mfma_f32_16x16x32_bf16 v[66:69], v[138:141], v[208:211], 0
	v_mfma_f32_16x16x32_bf16 v[66:69], v[142:145], v[212:215], v[66:69]
	s_setprio 0
	s_setprio 1
	v_mfma_f32_16x16x32_bf16 v[126:129], v[146:149], v[174:177], 0
	v_mfma_f32_16x16x32_bf16 v[126:129], v[150:153], v[178:181], v[126:129]
	v_mfma_f32_16x16x32_bf16 v[118:121], v[154:157], v[174:177], 0
	v_mfma_f32_16x16x32_bf16 v[118:121], v[170:173], v[178:181], v[118:121]
	v_mfma_f32_16x16x32_bf16 v[110:113], v[146:149], v[182:185], 0
	v_mfma_f32_16x16x32_bf16 v[110:113], v[150:153], v[186:189], v[110:113]
	v_mfma_f32_16x16x32_bf16 v[102:105], v[154:157], v[182:185], 0
	v_mfma_f32_16x16x32_bf16 v[102:105], v[170:173], v[186:189], v[102:105]
	v_mfma_f32_16x16x32_bf16 v[94:97], v[146:149], v[190:193], 0
	v_mfma_f32_16x16x32_bf16 v[94:97], v[150:153], v[200:203], v[94:97]
	v_mfma_f32_16x16x32_bf16 v[86:89], v[154:157], v[190:193], 0
	v_mfma_f32_16x16x32_bf16 v[86:89], v[170:173], v[200:203], v[86:89]
	v_mfma_f32_16x16x32_bf16 v[78:81], v[146:149], v[208:211], 0
	v_mfma_f32_16x16x32_bf16 v[78:81], v[150:153], v[212:215], v[78:81]
	v_mfma_f32_16x16x32_bf16 v[70:73], v[154:157], v[208:211], 0
	v_mfma_f32_16x16x32_bf16 v[70:73], v[170:173], v[212:215], v[70:73]
	s_setprio 0
	s_barrier
	s_add_i32 s64, s44, s35
	s_mov_b32 m0, s64
	ds_read_b128 v[174:177], v199 offset:16384
	ds_read_b128 v[178:181], v199 offset:17408
	ds_read_b128 v[182:185], v199 offset:18432
	ds_read_b128 v[186:189], v199 offset:19456
	ds_read_b128 v[190:193], v199 offset:20480
	ds_read_b128 v[200:203], v199 offset:21504
	ds_read_b128 v[208:211], v199 offset:22528
	ds_read_b128 v[212:215], v199 offset:23552
	global_load_lds_dwordx4 v160, s[2:3]
	s_add_i32 m0, s64, 0x2000
	s_add_u32 s80, s2, 0x80000
	s_addc_u32 s81, s3, 0
	s_add_i32 s64, s45, s35
	global_load_lds_dwordx4 v164, s[2:3]
	s_mov_b32 m0, s64
	v_lshl_add_u64 v[220:221], s[26:27], 0, v[162:163]
	global_load_lds_dwordx4 v160, s[80:81]
	s_add_i32 m0, s64, 0x2000
	s_nop 0
	global_load_lds_dwordx4 v164, s[80:81]
	v_lshl_add_u64 v[218:219], s[26:27], 0, v[158:159]
	s_mov_b32 m0, s13
	s_nop 0
	global_load_lds_dwordx4 v158, s[26:27]
	s_mov_b32 m0, s36
	s_nop 0
	global_load_lds_dwordx4 v162, s[26:27]
	s_waitcnt vmcnt(8)
	s_waitcnt lgkmcnt(0)
	s_barrier
	s_setprio 1
	s_waitcnt lgkmcnt(0)
	v_mfma_f32_16x16x32_bf16 v[58:61], v[130:133], v[174:177], 0
	v_mfma_f32_16x16x32_bf16 v[58:61], v[134:137], v[178:181], v[58:61]
	v_mfma_f32_16x16x32_bf16 v[50:53], v[138:141], v[174:177], 0
	v_mfma_f32_16x16x32_bf16 v[50:53], v[142:145], v[178:181], v[50:53]
	v_mfma_f32_16x16x32_bf16 v[42:45], v[130:133], v[182:185], 0
	v_mfma_f32_16x16x32_bf16 v[42:45], v[134:137], v[186:189], v[42:45]
	v_mfma_f32_16x16x32_bf16 v[34:37], v[138:141], v[182:185], 0
	v_mfma_f32_16x16x32_bf16 v[34:37], v[142:145], v[186:189], v[34:37]
	v_mfma_f32_16x16x32_bf16 v[26:29], v[130:133], v[190:193], 0
	v_mfma_f32_16x16x32_bf16 v[26:29], v[134:137], v[200:203], v[26:29]
	v_mfma_f32_16x16x32_bf16 v[18:21], v[138:141], v[190:193], 0
	v_mfma_f32_16x16x32_bf16 v[18:21], v[142:145], v[200:203], v[18:21]
	v_mfma_f32_16x16x32_bf16 v[10:13], v[130:133], v[208:211], 0
	v_mfma_f32_16x16x32_bf16 v[10:13], v[134:137], v[212:215], v[10:13]
	v_mfma_f32_16x16x32_bf16 v[2:5], v[138:141], v[208:211], 0
	v_mfma_f32_16x16x32_bf16 v[2:5], v[142:145], v[212:215], v[2:5]
	s_setprio 0
	s_setprio 1
	v_mfma_f32_16x16x32_bf16 v[62:65], v[146:149], v[174:177], 0
	v_mfma_f32_16x16x32_bf16 v[62:65], v[150:153], v[178:181], v[62:65]
	v_mfma_f32_16x16x32_bf16 v[54:57], v[154:157], v[174:177], 0
	v_mfma_f32_16x16x32_bf16 v[54:57], v[170:173], v[178:181], v[54:57]
	v_mfma_f32_16x16x32_bf16 v[46:49], v[146:149], v[182:185], 0
	v_mfma_f32_16x16x32_bf16 v[46:49], v[150:153], v[186:189], v[46:49]
	v_mfma_f32_16x16x32_bf16 v[38:41], v[154:157], v[182:185], 0
	v_mfma_f32_16x16x32_bf16 v[38:41], v[170:173], v[186:189], v[38:41]
	v_mfma_f32_16x16x32_bf16 v[30:33], v[146:149], v[190:193], 0
	v_mfma_f32_16x16x32_bf16 v[30:33], v[150:153], v[200:203], v[30:33]
	v_mfma_f32_16x16x32_bf16 v[22:25], v[154:157], v[190:193], 0
	v_mfma_f32_16x16x32_bf16 v[22:25], v[170:173], v[200:203], v[22:25]
	v_mfma_f32_16x16x32_bf16 v[14:17], v[146:149], v[208:211], 0
	v_mfma_f32_16x16x32_bf16 v[14:17], v[150:153], v[212:215], v[14:17]
	v_mfma_f32_16x16x32_bf16 v[6:9], v[154:157], v[208:211], 0
	v_mfma_f32_16x16x32_bf16 v[6:9], v[170:173], v[212:215], v[6:9]
	s_setprio 0
	s_barrier
	s_add_i32 s64, 0, 0x18000
	s_add_i32 s75, 0, 0x1c000
	v_add_u32_e32 v142, s64, v194
	v_add_u32_e32 v170, s75, v194
	ds_read_b128 v[130:133], v142
	ds_read_b128 v[134:137], v142 offset:1024
	ds_read_b128 v[138:141], v142 offset:2048
	ds_read_b128 v[142:145], v142 offset:3072
	ds_read_b128 v[146:149], v170
	ds_read_b128 v[150:153], v170 offset:1024
	ds_read_b128 v[154:157], v170 offset:2048
	ds_read_b128 v[170:173], v170 offset:3072
	s_add_u32 s26, s26, 0x80000
	s_addc_u32 s27, s27, 0
	s_mov_b32 m0, s37
	ds_read_b128 v[174:177], v199 offset:32768
	ds_read_b128 v[178:181], v199 offset:33792
	ds_read_b128 v[182:185], v199 offset:34816
	ds_read_b128 v[186:189], v199 offset:35840
	ds_read_b128 v[190:193], v199 offset:36864
	ds_read_b128 v[200:203], v199 offset:37888
	ds_read_b128 v[208:211], v199 offset:38912
	ds_read_b128 v[212:215], v199 offset:39936
	global_load_lds_dwordx4 v158, s[26:27]
	s_mov_b32 m0, s38
	s_nop 0
	global_load_lds_dwordx4 v162, s[26:27]
	s_waitcnt vmcnt(8)
	s_waitcnt lgkmcnt(0)
	s_barrier
	s_setprio 1
	s_waitcnt lgkmcnt(0)
	v_mfma_f32_16x16x32_bf16 v[122:125], v[130:133], v[174:177], v[122:125]
	v_mfma_f32_16x16x32_bf16 v[122:125], v[134:137], v[178:181], v[122:125]
	v_mfma_f32_16x16x32_bf16 v[114:117], v[138:141], v[174:177], v[114:117]
	v_mfma_f32_16x16x32_bf16 v[114:117], v[142:145], v[178:181], v[114:117]
	v_mfma_f32_16x16x32_bf16 v[106:109], v[130:133], v[182:185], v[106:109]
	v_mfma_f32_16x16x32_bf16 v[106:109], v[134:137], v[186:189], v[106:109]
	v_mfma_f32_16x16x32_bf16 v[98:101], v[138:141], v[182:185], v[98:101]
	v_mfma_f32_16x16x32_bf16 v[98:101], v[142:145], v[186:189], v[98:101]
	v_mfma_f32_16x16x32_bf16 v[90:93], v[130:133], v[190:193], v[90:93]
	v_mfma_f32_16x16x32_bf16 v[90:93], v[134:137], v[200:203], v[90:93]
	v_mfma_f32_16x16x32_bf16 v[82:85], v[138:141], v[190:193], v[82:85]
	v_mfma_f32_16x16x32_bf16 v[82:85], v[142:145], v[200:203], v[82:85]
	v_mfma_f32_16x16x32_bf16 v[74:77], v[130:133], v[208:211], v[74:77]
	v_mfma_f32_16x16x32_bf16 v[74:77], v[134:137], v[212:215], v[74:77]
	v_mfma_f32_16x16x32_bf16 v[66:69], v[138:141], v[208:211], v[66:69]
	v_mfma_f32_16x16x32_bf16 v[66:69], v[142:145], v[212:215], v[66:69]
	s_setprio 0
	s_setprio 1
	v_mfma_f32_16x16x32_bf16 v[126:129], v[146:149], v[174:177], v[126:129]
	v_mfma_f32_16x16x32_bf16 v[126:129], v[150:153], v[178:181], v[126:129]
	v_mfma_f32_16x16x32_bf16 v[118:121], v[154:157], v[174:177], v[118:121]
	v_mfma_f32_16x16x32_bf16 v[118:121], v[170:173], v[178:181], v[118:121]
	v_mfma_f32_16x16x32_bf16 v[110:113], v[146:149], v[182:185], v[110:113]
	v_mfma_f32_16x16x32_bf16 v[110:113], v[150:153], v[186:189], v[110:113]
	v_mfma_f32_16x16x32_bf16 v[102:105], v[154:157], v[182:185], v[102:105]
	v_mfma_f32_16x16x32_bf16 v[102:105], v[170:173], v[186:189], v[102:105]
	v_mfma_f32_16x16x32_bf16 v[94:97], v[146:149], v[190:193], v[94:97]
	v_mfma_f32_16x16x32_bf16 v[94:97], v[150:153], v[200:203], v[94:97]
	v_mfma_f32_16x16x32_bf16 v[86:89], v[154:157], v[190:193], v[86:89]
	v_mfma_f32_16x16x32_bf16 v[86:89], v[170:173], v[200:203], v[86:89]
	v_mfma_f32_16x16x32_bf16 v[78:81], v[146:149], v[208:211], v[78:81]
	v_mfma_f32_16x16x32_bf16 v[78:81], v[150:153], v[212:215], v[78:81]
	v_mfma_f32_16x16x32_bf16 v[70:73], v[154:157], v[208:211], v[70:73]
	v_mfma_f32_16x16x32_bf16 v[70:73], v[170:173], v[212:215], v[70:73]
	s_setprio 0
	s_barrier
	s_add_i32 s26, s64, s35
	s_add_u32 s98, s2, s68
	s_addc_u32 s99, s3, s69
	s_mov_b32 m0, s26
	ds_read_b128 v[174:177], v199 offset:49152
	ds_read_b128 v[178:181], v199 offset:50176
	ds_read_b128 v[182:185], v199 offset:51200
	ds_read_b128 v[186:189], v199 offset:52224
	ds_read_b128 v[190:193], v199 offset:53248
	ds_read_b128 v[200:203], v199 offset:54272
	ds_read_b128 v[208:211], v199 offset:55296
	ds_read_b128 v[212:215], v199 offset:56320
	global_load_lds_dwordx4 v160, s[98:99]
	s_add_i32 m0, s26, 0x2000
	s_add_u32 s2, s2, 0x80080
	s_addc_u32 s3, s3, 0
	s_add_i32 s26, s75, s35
	global_load_lds_dwordx4 v164, s[98:99]
	s_mov_b32 m0, s26
	s_nop 0
	global_load_lds_dwordx4 v160, s[2:3]
	s_add_i32 m0, s26, 0x2000
	s_nop 0
	global_load_lds_dwordx4 v164, s[2:3]
	v_lshl_add_u64 v[204:205], v[218:219], 0, s[68:69]
	s_mov_b32 m0, s40
	s_nop 0
	global_load_lds_dwordx4 v[204:205], off
	v_lshl_add_u64 v[204:205], v[220:221], 0, s[68:69]
	s_mov_b32 m0, s41
	s_nop 0
	global_load_lds_dwordx4 v[204:205], off
	s_waitcnt vmcnt(8)
	s_waitcnt lgkmcnt(0)
	s_barrier
	s_setprio 1
	s_waitcnt lgkmcnt(0)
	v_mfma_f32_16x16x32_bf16 v[58:61], v[130:133], v[174:177], v[58:61]
	v_mfma_f32_16x16x32_bf16 v[58:61], v[134:137], v[178:181], v[58:61]
	v_mfma_f32_16x16x32_bf16 v[50:53], v[138:141], v[174:177], v[50:53]
	v_mfma_f32_16x16x32_bf16 v[50:53], v[142:145], v[178:181], v[50:53]
	v_mfma_f32_16x16x32_bf16 v[42:45], v[130:133], v[182:185], v[42:45]
	v_mfma_f32_16x16x32_bf16 v[42:45], v[134:137], v[186:189], v[42:45]
	v_mfma_f32_16x16x32_bf16 v[34:37], v[138:141], v[182:185], v[34:37]
	v_mfma_f32_16x16x32_bf16 v[34:37], v[142:145], v[186:189], v[34:37]
	v_mfma_f32_16x16x32_bf16 v[26:29], v[130:133], v[190:193], v[26:29]
	v_mfma_f32_16x16x32_bf16 v[26:29], v[134:137], v[200:203], v[26:29]
	v_mfma_f32_16x16x32_bf16 v[18:21], v[138:141], v[190:193], v[18:21]
	v_mfma_f32_16x16x32_bf16 v[18:21], v[142:145], v[200:203], v[18:21]
	v_mfma_f32_16x16x32_bf16 v[10:13], v[130:133], v[208:211], v[10:13]
	v_mfma_f32_16x16x32_bf16 v[10:13], v[134:137], v[212:215], v[10:13]
	v_mfma_f32_16x16x32_bf16 v[2:5], v[138:141], v[208:211], v[2:5]
	v_mfma_f32_16x16x32_bf16 v[2:5], v[142:145], v[212:215], v[2:5]
	s_setprio 0
	s_setprio 1
	v_mfma_f32_16x16x32_bf16 v[62:65], v[146:149], v[174:177], v[62:65]
	v_mfma_f32_16x16x32_bf16 v[62:65], v[150:153], v[178:181], v[62:65]
	v_mfma_f32_16x16x32_bf16 v[54:57], v[154:157], v[174:177], v[54:57]
	v_mfma_f32_16x16x32_bf16 v[54:57], v[170:173], v[178:181], v[54:57]
	v_mfma_f32_16x16x32_bf16 v[46:49], v[146:149], v[182:185], v[46:49]
	v_mfma_f32_16x16x32_bf16 v[46:49], v[150:153], v[186:189], v[46:49]
	v_mfma_f32_16x16x32_bf16 v[38:41], v[154:157], v[182:185], v[38:41]
	v_mfma_f32_16x16x32_bf16 v[38:41], v[170:173], v[186:189], v[38:41]
	v_mfma_f32_16x16x32_bf16 v[30:33], v[146:149], v[190:193], v[30:33]
	v_mfma_f32_16x16x32_bf16 v[30:33], v[150:153], v[200:203], v[30:33]
	v_mfma_f32_16x16x32_bf16 v[22:25], v[154:157], v[190:193], v[22:25]
	v_mfma_f32_16x16x32_bf16 v[22:25], v[170:173], v[200:203], v[22:25]
	v_mfma_f32_16x16x32_bf16 v[14:17], v[146:149], v[208:211], v[14:17]
	v_mfma_f32_16x16x32_bf16 v[14:17], v[150:153], v[212:215], v[14:17]
	v_mfma_f32_16x16x32_bf16 v[6:9], v[154:157], v[208:211], v[6:9]
	v_mfma_f32_16x16x32_bf16 v[6:9], v[170:173], v[212:215], v[6:9]
	s_setprio 0
	s_barrier
	s_add_u32 s18, s18, 0x100
	s_addc_u32 s19, s19, 0
	s_add_u32 s51, s51, 0x100
	s_addc_u32 s52, s52, 0
	s_cmp_ge_i32 s53, s17
	s_mov_b32 s2, s53
	s_cbranch_scc1 .Lkpeel_exit_3
.LBB0_634:
	ds_read_b128 v[130:133], v197
	ds_read_b128 v[134:137], v197 offset:1024
	ds_read_b128 v[138:141], v197 offset:2048
	ds_read_b128 v[142:145], v197 offset:3072
	ds_read_b128 v[146:149], v198
	ds_read_b128 v[150:153], v198 offset:1024
	ds_read_b128 v[154:157], v198 offset:2048
	ds_read_b128 v[170:173], v198 offset:3072
	s_add_i32 s53, s2, 2
	s_add_u32 s3, s18, 0xfff80080
	s_addc_u32 s26, s19, -1
	s_cmp_eq_u32 s50, s2
	s_cselect_b32 s2, s47, s51
	s_cselect_b32 s27, s11, s26
	s_cselect_b32 s26, s16, s3
	s_cselect_b32 s3, s46, s52
	s_add_i32 m0, s13, 0xc000
	ds_read_b128 v[174:177], v199
	ds_read_b128 v[178:181], v199 offset:1024
	ds_read_b128 v[182:185], v199 offset:2048
	ds_read_b128 v[186:189], v199 offset:3072
	ds_read_b128 v[190:193], v199 offset:4096
	ds_read_b128 v[200:203], v199 offset:5120
	ds_read_b128 v[208:211], v199 offset:6144
	ds_read_b128 v[212:215], v199 offset:7168
	global_load_lds_dwordx4 v166, s[18:19]
	s_add_i32 m0, s13, 0xe000
	s_nop 0
	global_load_lds_dwordx4 v168, s[18:19]
	s_waitcnt vmcnt(8)
	s_waitcnt lgkmcnt(0)
	s_barrier
	s_setprio 1
	s_waitcnt lgkmcnt(0)
	v_mfma_f32_16x16x32_bf16 v[122:125], v[130:133], v[174:177], v[122:125]
	v_mfma_f32_16x16x32_bf16 v[122:125], v[134:137], v[178:181], v[122:125]
	v_mfma_f32_16x16x32_bf16 v[114:117], v[138:141], v[174:177], v[114:117]
	v_mfma_f32_16x16x32_bf16 v[114:117], v[142:145], v[178:181], v[114:117]
	v_mfma_f32_16x16x32_bf16 v[106:109], v[130:133], v[182:185], v[106:109]
	v_mfma_f32_16x16x32_bf16 v[106:109], v[134:137], v[186:189], v[106:109]
	v_mfma_f32_16x16x32_bf16 v[98:101], v[138:141], v[182:185], v[98:101]
	v_mfma_f32_16x16x32_bf16 v[98:101], v[142:145], v[186:189], v[98:101]
	v_mfma_f32_16x16x32_bf16 v[90:93], v[130:133], v[190:193], v[90:93]
	v_mfma_f32_16x16x32_bf16 v[90:93], v[134:137], v[200:203], v[90:93]
	v_mfma_f32_16x16x32_bf16 v[82:85], v[138:141], v[190:193], v[82:85]
	v_mfma_f32_16x16x32_bf16 v[82:85], v[142:145], v[200:203], v[82:85]
	v_mfma_f32_16x16x32_bf16 v[74:77], v[130:133], v[208:211], v[74:77]
	v_mfma_f32_16x16x32_bf16 v[74:77], v[134:137], v[212:215], v[74:77]
	v_mfma_f32_16x16x32_bf16 v[66:69], v[138:141], v[208:211], v[66:69]
	v_mfma_f32_16x16x32_bf16 v[66:69], v[142:145], v[212:215], v[66:69]
	s_setprio 0
	s_setprio 1
	v_mfma_f32_16x16x32_bf16 v[126:129], v[146:149], v[174:177], v[126:129]
	v_mfma_f32_16x16x32_bf16 v[126:129], v[150:153], v[178:181], v[126:129]
	v_mfma_f32_16x16x32_bf16 v[118:121], v[154:157], v[174:177], v[118:121]
	v_mfma_f32_16x16x32_bf16 v[118:121], v[170:173], v[178:181], v[118:121]
	v_mfma_f32_16x16x32_bf16 v[110:113], v[146:149], v[182:185], v[110:113]
	v_mfma_f32_16x16x32_bf16 v[110:113], v[150:153], v[186:189], v[110:113]
	v_mfma_f32_16x16x32_bf16 v[102:105], v[154:157], v[182:185], v[102:105]
	v_mfma_f32_16x16x32_bf16 v[102:105], v[170:173], v[186:189], v[102:105]
	v_mfma_f32_16x16x32_bf16 v[94:97], v[146:149], v[190:193], v[94:97]
	v_mfma_f32_16x16x32_bf16 v[94:97], v[150:153], v[200:203], v[94:97]
	v_mfma_f32_16x16x32_bf16 v[86:89], v[154:157], v[190:193], v[86:89]
	v_mfma_f32_16x16x32_bf16 v[86:89], v[170:173], v[200:203], v[86:89]
	v_mfma_f32_16x16x32_bf16 v[78:81], v[146:149], v[208:211], v[78:81]
	v_mfma_f32_16x16x32_bf16 v[78:81], v[150:153], v[212:215], v[78:81]
	v_mfma_f32_16x16x32_bf16 v[70:73], v[154:157], v[208:211], v[70:73]
	v_mfma_f32_16x16x32_bf16 v[70:73], v[170:173], v[212:215], v[70:73]
	s_setprio 0
	s_barrier
	s_add_i32 s64, s44, s35
	s_mov_b32 m0, s64
	ds_read_b128 v[174:177], v199 offset:16384
	ds_read_b128 v[178:181], v199 offset:17408
	ds_read_b128 v[182:185], v199 offset:18432
	ds_read_b128 v[186:189], v199 offset:19456
	ds_read_b128 v[190:193], v199 offset:20480
	ds_read_b128 v[200:203], v199 offset:21504
	ds_read_b128 v[208:211], v199 offset:22528
	ds_read_b128 v[212:215], v199 offset:23552
	global_load_lds_dwordx4 v160, s[2:3]
	s_add_i32 m0, s64, 0x2000
	s_add_u32 s80, s2, 0x80000
	s_addc_u32 s81, s3, 0
	s_add_i32 s64, s45, s35
	global_load_lds_dwordx4 v164, s[2:3]
	s_mov_b32 m0, s64
	v_lshl_add_u64 v[220:221], s[26:27], 0, v[162:163]
	global_load_lds_dwordx4 v160, s[80:81]
	s_add_i32 m0, s64, 0x2000
	s_nop 0
	global_load_lds_dwordx4 v164, s[80:81]
	v_lshl_add_u64 v[218:219], s[26:27], 0, v[158:159]
	s_mov_b32 m0, s13
	s_nop 0
	global_load_lds_dwordx4 v158, s[26:27]
	s_mov_b32 m0, s36
	s_nop 0
	global_load_lds_dwordx4 v162, s[26:27]
	s_waitcnt vmcnt(8)
	s_waitcnt lgkmcnt(0)
	s_barrier
	s_setprio 1
	s_waitcnt lgkmcnt(0)
	v_mfma_f32_16x16x32_bf16 v[58:61], v[130:133], v[174:177], v[58:61]
	v_mfma_f32_16x16x32_bf16 v[58:61], v[134:137], v[178:181], v[58:61]
	v_mfma_f32_16x16x32_bf16 v[50:53], v[138:141], v[174:177], v[50:53]
	v_mfma_f32_16x16x32_bf16 v[50:53], v[142:145], v[178:181], v[50:53]
	v_mfma_f32_16x16x32_bf16 v[42:45], v[130:133], v[182:185], v[42:45]
	v_mfma_f32_16x16x32_bf16 v[42:45], v[134:137], v[186:189], v[42:45]
	v_mfma_f32_16x16x32_bf16 v[34:37], v[138:141], v[182:185], v[34:37]
	v_mfma_f32_16x16x32_bf16 v[34:37], v[142:145], v[186:189], v[34:37]
	v_mfma_f32_16x16x32_bf16 v[26:29], v[130:133], v[190:193], v[26:29]
	v_mfma_f32_16x16x32_bf16 v[26:29], v[134:137], v[200:203], v[26:29]
	v_mfma_f32_16x16x32_bf16 v[18:21], v[138:141], v[190:193], v[18:21]
	v_mfma_f32_16x16x32_bf16 v[18:21], v[142:145], v[200:203], v[18:21]
	v_mfma_f32_16x16x32_bf16 v[10:13], v[130:133], v[208:211], v[10:13]
	v_mfma_f32_16x16x32_bf16 v[10:13], v[134:137], v[212:215], v[10:13]
	v_mfma_f32_16x16x32_bf16 v[2:5], v[138:141], v[208:211], v[2:5]
	v_mfma_f32_16x16x32_bf16 v[2:5], v[142:145], v[212:215], v[2:5]
	s_setprio 0
	s_setprio 1
	v_mfma_f32_16x16x32_bf16 v[62:65], v[146:149], v[174:177], v[62:65]
	v_mfma_f32_16x16x32_bf16 v[62:65], v[150:153], v[178:181], v[62:65]
	v_mfma_f32_16x16x32_bf16 v[54:57], v[154:157], v[174:177], v[54:57]
	v_mfma_f32_16x16x32_bf16 v[54:57], v[170:173], v[178:181], v[54:57]
	v_mfma_f32_16x16x32_bf16 v[46:49], v[146:149], v[182:185], v[46:49]
	v_mfma_f32_16x16x32_bf16 v[46:49], v[150:153], v[186:189], v[46:49]
	v_mfma_f32_16x16x32_bf16 v[38:41], v[154:157], v[182:185], v[38:41]
	v_mfma_f32_16x16x32_bf16 v[38:41], v[170:173], v[186:189], v[38:41]
	v_mfma_f32_16x16x32_bf16 v[30:33], v[146:149], v[190:193], v[30:33]
	v_mfma_f32_16x16x32_bf16 v[30:33], v[150:153], v[200:203], v[30:33]
	v_mfma_f32_16x16x32_bf16 v[22:25], v[154:157], v[190:193], v[22:25]
	v_mfma_f32_16x16x32_bf16 v[22:25], v[170:173], v[200:203], v[22:25]
	v_mfma_f32_16x16x32_bf16 v[14:17], v[146:149], v[208:211], v[14:17]
	v_mfma_f32_16x16x32_bf16 v[14:17], v[150:153], v[212:215], v[14:17]
	v_mfma_f32_16x16x32_bf16 v[6:9], v[154:157], v[208:211], v[6:9]
	v_mfma_f32_16x16x32_bf16 v[6:9], v[170:173], v[212:215], v[6:9]
	s_setprio 0
	s_barrier
	s_add_i32 s64, 0, 0x18000
	s_add_i32 s75, 0, 0x1c000
	v_add_u32_e32 v142, s64, v194
	v_add_u32_e32 v170, s75, v194
	ds_read_b128 v[130:133], v142
	ds_read_b128 v[134:137], v142 offset:1024
	ds_read_b128 v[138:141], v142 offset:2048
	ds_read_b128 v[142:145], v142 offset:3072
	ds_read_b128 v[146:149], v170
	ds_read_b128 v[150:153], v170 offset:1024
	ds_read_b128 v[154:157], v170 offset:2048
	ds_read_b128 v[170:173], v170 offset:3072
	s_add_u32 s26, s26, 0x80000
	s_addc_u32 s27, s27, 0
	s_mov_b32 m0, s37
	ds_read_b128 v[174:177], v199 offset:32768
	ds_read_b128 v[178:181], v199 offset:33792
	ds_read_b128 v[182:185], v199 offset:34816
	ds_read_b128 v[186:189], v199 offset:35840
	ds_read_b128 v[190:193], v199 offset:36864
	ds_read_b128 v[200:203], v199 offset:37888
	ds_read_b128 v[208:211], v199 offset:38912
	ds_read_b128 v[212:215], v199 offset:39936
	global_load_lds_dwordx4 v158, s[26:27]
	s_mov_b32 m0, s38
	s_nop 0
	global_load_lds_dwordx4 v162, s[26:27]
	s_waitcnt vmcnt(8)
	s_waitcnt lgkmcnt(0)
	s_barrier
	s_setprio 1
	s_waitcnt lgkmcnt(0)
	v_mfma_f32_16x16x32_bf16 v[122:125], v[130:133], v[174:177], v[122:125]
	v_mfma_f32_16x16x32_bf16 v[122:125], v[134:137], v[178:181], v[122:125]
	v_mfma_f32_16x16x32_bf16 v[114:117], v[138:141], v[174:177], v[114:117]
	v_mfma_f32_16x16x32_bf16 v[114:117], v[142:145], v[178:181], v[114:117]
	v_mfma_f32_16x16x32_bf16 v[106:109], v[130:133], v[182:185], v[106:109]
	v_mfma_f32_16x16x32_bf16 v[106:109], v[134:137], v[186:189], v[106:109]
	v_mfma_f32_16x16x32_bf16 v[98:101], v[138:141], v[182:185], v[98:101]
	v_mfma_f32_16x16x32_bf16 v[98:101], v[142:145], v[186:189], v[98:101]
	v_mfma_f32_16x16x32_bf16 v[90:93], v[130:133], v[190:193], v[90:93]
	v_mfma_f32_16x16x32_bf16 v[90:93], v[134:137], v[200:203], v[90:93]
	v_mfma_f32_16x16x32_bf16 v[82:85], v[138:141], v[190:193], v[82:85]
	v_mfma_f32_16x16x32_bf16 v[82:85], v[142:145], v[200:203], v[82:85]
	v_mfma_f32_16x16x32_bf16 v[74:77], v[130:133], v[208:211], v[74:77]
	v_mfma_f32_16x16x32_bf16 v[74:77], v[134:137], v[212:215], v[74:77]
	v_mfma_f32_16x16x32_bf16 v[66:69], v[138:141], v[208:211], v[66:69]
	v_mfma_f32_16x16x32_bf16 v[66:69], v[142:145], v[212:215], v[66:69]
	s_setprio 0
	s_setprio 1
	v_mfma_f32_16x16x32_bf16 v[126:129], v[146:149], v[174:177], v[126:129]
	v_mfma_f32_16x16x32_bf16 v[126:129], v[150:153], v[178:181], v[126:129]
	v_mfma_f32_16x16x32_bf16 v[118:121], v[154:157], v[174:177], v[118:121]
	v_mfma_f32_16x16x32_bf16 v[118:121], v[170:173], v[178:181], v[118:121]
	v_mfma_f32_16x16x32_bf16 v[110:113], v[146:149], v[182:185], v[110:113]
	v_mfma_f32_16x16x32_bf16 v[110:113], v[150:153], v[186:189], v[110:113]
	v_mfma_f32_16x16x32_bf16 v[102:105], v[154:157], v[182:185], v[102:105]
	v_mfma_f32_16x16x32_bf16 v[102:105], v[170:173], v[186:189], v[102:105]
	v_mfma_f32_16x16x32_bf16 v[94:97], v[146:149], v[190:193], v[94:97]
	v_mfma_f32_16x16x32_bf16 v[94:97], v[150:153], v[200:203], v[94:97]
	v_mfma_f32_16x16x32_bf16 v[86:89], v[154:157], v[190:193], v[86:89]
	v_mfma_f32_16x16x32_bf16 v[86:89], v[170:173], v[200:203], v[86:89]
	v_mfma_f32_16x16x32_bf16 v[78:81], v[146:149], v[208:211], v[78:81]
	v_mfma_f32_16x16x32_bf16 v[78:81], v[150:153], v[212:215], v[78:81]
	v_mfma_f32_16x16x32_bf16 v[70:73], v[154:157], v[208:211], v[70:73]
	v_mfma_f32_16x16x32_bf16 v[70:73], v[170:173], v[212:215], v[70:73]
	s_setprio 0
	s_barrier
	s_add_i32 s26, s64, s35
	s_add_u32 s98, s2, s68
	s_addc_u32 s99, s3, s69
	s_mov_b32 m0, s26
	ds_read_b128 v[174:177], v199 offset:49152
	ds_read_b128 v[178:181], v199 offset:50176
	ds_read_b128 v[182:185], v199 offset:51200
	ds_read_b128 v[186:189], v199 offset:52224
	ds_read_b128 v[190:193], v199 offset:53248
	ds_read_b128 v[200:203], v199 offset:54272
	ds_read_b128 v[208:211], v199 offset:55296
	ds_read_b128 v[212:215], v199 offset:56320
	global_load_lds_dwordx4 v160, s[98:99]
	s_add_i32 m0, s26, 0x2000
	s_add_u32 s2, s2, 0x80080
	s_addc_u32 s3, s3, 0
	s_add_i32 s26, s75, s35
	global_load_lds_dwordx4 v164, s[98:99]
	s_mov_b32 m0, s26
	s_nop 0
	global_load_lds_dwordx4 v160, s[2:3]
	s_add_i32 m0, s26, 0x2000
	s_nop 0
	global_load_lds_dwordx4 v164, s[2:3]
	v_lshl_add_u64 v[204:205], v[218:219], 0, s[68:69]
	s_mov_b32 m0, s40
	s_nop 0
	global_load_lds_dwordx4 v[204:205], off
	v_lshl_add_u64 v[204:205], v[220:221], 0, s[68:69]
	s_mov_b32 m0, s41
	s_nop 0
	global_load_lds_dwordx4 v[204:205], off
	s_waitcnt vmcnt(8)
	s_waitcnt lgkmcnt(0)
	s_barrier
	s_setprio 1
	s_waitcnt lgkmcnt(0)
	v_mfma_f32_16x16x32_bf16 v[58:61], v[130:133], v[174:177], v[58:61]
	v_mfma_f32_16x16x32_bf16 v[58:61], v[134:137], v[178:181], v[58:61]
	v_mfma_f32_16x16x32_bf16 v[50:53], v[138:141], v[174:177], v[50:53]
	v_mfma_f32_16x16x32_bf16 v[50:53], v[142:145], v[178:181], v[50:53]
	v_mfma_f32_16x16x32_bf16 v[42:45], v[130:133], v[182:185], v[42:45]
	v_mfma_f32_16x16x32_bf16 v[42:45], v[134:137], v[186:189], v[42:45]
	v_mfma_f32_16x16x32_bf16 v[34:37], v[138:141], v[182:185], v[34:37]
	v_mfma_f32_16x16x32_bf16 v[34:37], v[142:145], v[186:189], v[34:37]
	v_mfma_f32_16x16x32_bf16 v[26:29], v[130:133], v[190:193], v[26:29]
	v_mfma_f32_16x16x32_bf16 v[26:29], v[134:137], v[200:203], v[26:29]
	v_mfma_f32_16x16x32_bf16 v[18:21], v[138:141], v[190:193], v[18:21]
	v_mfma_f32_16x16x32_bf16 v[18:21], v[142:145], v[200:203], v[18:21]
	v_mfma_f32_16x16x32_bf16 v[10:13], v[130:133], v[208:211], v[10:13]
	v_mfma_f32_16x16x32_bf16 v[10:13], v[134:137], v[212:215], v[10:13]
	v_mfma_f32_16x16x32_bf16 v[2:5], v[138:141], v[208:211], v[2:5]
	v_mfma_f32_16x16x32_bf16 v[2:5], v[142:145], v[212:215], v[2:5]
	s_setprio 0
	s_setprio 1
	v_mfma_f32_16x16x32_bf16 v[62:65], v[146:149], v[174:177], v[62:65]
	v_mfma_f32_16x16x32_bf16 v[62:65], v[150:153], v[178:181], v[62:65]
	v_mfma_f32_16x16x32_bf16 v[54:57], v[154:157], v[174:177], v[54:57]
	v_mfma_f32_16x16x32_bf16 v[54:57], v[170:173], v[178:181], v[54:57]
	v_mfma_f32_16x16x32_bf16 v[46:49], v[146:149], v[182:185], v[46:49]
	v_mfma_f32_16x16x32_bf16 v[46:49], v[150:153], v[186:189], v[46:49]
	v_mfma_f32_16x16x32_bf16 v[38:41], v[154:157], v[182:185], v[38:41]
	v_mfma_f32_16x16x32_bf16 v[38:41], v[170:173], v[186:189], v[38:41]
	v_mfma_f32_16x16x32_bf16 v[30:33], v[146:149], v[190:193], v[30:33]
	v_mfma_f32_16x16x32_bf16 v[30:33], v[150:153], v[200:203], v[30:33]
	v_mfma_f32_16x16x32_bf16 v[22:25], v[154:157], v[190:193], v[22:25]
	v_mfma_f32_16x16x32_bf16 v[22:25], v[170:173], v[200:203], v[22:25]
	v_mfma_f32_16x16x32_bf16 v[14:17], v[146:149], v[208:211], v[14:17]
	v_mfma_f32_16x16x32_bf16 v[14:17], v[150:153], v[212:215], v[14:17]
	v_mfma_f32_16x16x32_bf16 v[6:9], v[154:157], v[208:211], v[6:9]
	v_mfma_f32_16x16x32_bf16 v[6:9], v[170:173], v[212:215], v[6:9]
	s_setprio 0
	s_barrier
	s_add_u32 s18, s18, 0x100
	s_addc_u32 s19, s19, 0
	s_add_u32 s51, s51, 0x100
	s_addc_u32 s52, s52, 0
	s_cmp_ge_i32 s53, s17
	s_mov_b32 s2, s53
	s_cbranch_scc0 .LBB0_634

.LBB0_798:
	s_lshl_b32 s0, s26, 21
	s_and_b32 s0, s0, 0x1fe00000
	v_readlane_b32 s22, v248, 22
	v_readlane_b32 s23, v248, 23
	s_add_u32 s0, s22, s0
	s_addc_u32 s23, s23, 0
	s_lshr_b32 s22, s26, 13
	s_and_b32 s24, s22, 0x7ff80
	s_add_u32 s22, s0, s24
	s_addc_u32 s23, s23, 0
	s_lshl_b32 s0, s26, 13
	s_and_b32 s0, s0, 0x1fe00000
	s_add_u32 s0, s82, s0
	s_addc_u32 s25, s83, 0
	s_add_u32 s24, s0, s24
	s_addc_u32 s25, s25, 0
	s_cmp_lt_i32 s35, 1
	v_cmp_gt_i64_e64 s[26:27], s[26:27], -1
	s_cbranch_scc1 .LBB0_820
	s_and_b64 s[38:39], s[26:27], exec
	s_cselect_b32 s0, s23, s37
	s_cselect_b32 s34, s22, s36
	s_cselect_b32 s56, s25, s3
	s_cselect_b32 s57, s24, s2
	s_add_i32 s58, s35, -2
	s_add_u32 s36, s36, 0x100080
	s_addc_u32 s37, s37, 0
	s_add_u32 s59, s2, 0x100
	s_addc_u32 s60, s3, 0
	s_mov_b32 s2, 0
	ds_read_b128 v[148:151], v144
	ds_read_b128 v[152:155], v144 offset:1024
	ds_read_b128 v[156:159], v144 offset:2048
	ds_read_b128 v[160:163], v144 offset:3072
	ds_read_b128 v[164:167], v145
	ds_read_b128 v[168:171], v145 offset:1024
	ds_read_b128 v[172:175], v145 offset:2048
	ds_read_b128 v[176:179], v145 offset:3072
	s_add_i32 s61, s2, 2
	s_add_u32 s3, s36, 0xfff00080
	s_addc_u32 s38, s37, -1
	s_cmp_eq_u32 s58, s2
	s_cselect_b32 s2, s57, s59
	s_cselect_b32 s39, s0, s38
	s_cselect_b32 s38, s34, s3
	s_cselect_b32 s3, s56, s60
	s_add_i32 m0, s29, 0xc000
	ds_read_b128 v[180:183], v146
	ds_read_b128 v[184:187], v146 offset:1024
	ds_read_b128 v[188:191], v146 offset:2048
	ds_read_b128 v[192:195], v146 offset:3072
	ds_read_b128 v[196:199], v146 offset:4096
	ds_read_b128 v[200:203], v146 offset:5120
	ds_read_b128 v[208:211], v146 offset:6144
	ds_read_b128 v[212:215], v146 offset:7168
	global_load_lds_dwordx4 v138, s[36:37]
	s_add_i32 m0, s29, 0xe000
	s_nop 0
	global_load_lds_dwordx4 v140, s[36:37]
	s_waitcnt vmcnt(8)
	s_waitcnt lgkmcnt(0)
	s_barrier
	s_setprio 1
	s_waitcnt lgkmcnt(0)
	v_mfma_f32_16x16x32_bf16 v[126:129], v[148:151], v[180:183], 0
	v_mfma_f32_16x16x32_bf16 v[126:129], v[152:155], v[184:187], v[126:129]
	v_mfma_f32_16x16x32_bf16 v[122:125], v[156:159], v[180:183], 0
	v_mfma_f32_16x16x32_bf16 v[122:125], v[160:163], v[184:187], v[122:125]
	v_mfma_f32_16x16x32_bf16 v[110:113], v[148:151], v[188:191], 0
	v_mfma_f32_16x16x32_bf16 v[110:113], v[152:155], v[192:195], v[110:113]
	v_mfma_f32_16x16x32_bf16 v[102:105], v[156:159], v[188:191], 0
	v_mfma_f32_16x16x32_bf16 v[102:105], v[160:163], v[192:195], v[102:105]
	v_mfma_f32_16x16x32_bf16 v[94:97], v[148:151], v[196:199], 0
	v_mfma_f32_16x16x32_bf16 v[94:97], v[152:155], v[200:203], v[94:97]
	v_mfma_f32_16x16x32_bf16 v[86:89], v[156:159], v[196:199], 0
	v_mfma_f32_16x16x32_bf16 v[86:89], v[160:163], v[200:203], v[86:89]
	v_mfma_f32_16x16x32_bf16 v[78:81], v[148:151], v[208:211], 0
	v_mfma_f32_16x16x32_bf16 v[78:81], v[152:155], v[212:215], v[78:81]
	v_mfma_f32_16x16x32_bf16 v[70:73], v[156:159], v[208:211], 0
	v_mfma_f32_16x16x32_bf16 v[70:73], v[160:163], v[212:215], v[70:73]
	s_setprio 0
	s_setprio 1
	v_mfma_f32_16x16x32_bf16 v[118:121], v[164:167], v[180:183], 0
	v_mfma_f32_16x16x32_bf16 v[118:121], v[168:171], v[184:187], v[118:121]
	v_mfma_f32_16x16x32_bf16 v[114:117], v[172:175], v[180:183], 0
	v_mfma_f32_16x16x32_bf16 v[114:117], v[176:179], v[184:187], v[114:117]
	v_mfma_f32_16x16x32_bf16 v[106:109], v[164:167], v[188:191], 0
	v_mfma_f32_16x16x32_bf16 v[106:109], v[168:171], v[192:195], v[106:109]
	v_mfma_f32_16x16x32_bf16 v[98:101], v[172:175], v[188:191], 0
	v_mfma_f32_16x16x32_bf16 v[98:101], v[176:179], v[192:195], v[98:101]
	v_mfma_f32_16x16x32_bf16 v[90:93], v[164:167], v[196:199], 0
	v_mfma_f32_16x16x32_bf16 v[90:93], v[168:171], v[200:203], v[90:93]
	v_mfma_f32_16x16x32_bf16 v[82:85], v[172:175], v[196:199], 0
	v_mfma_f32_16x16x32_bf16 v[82:85], v[176:179], v[200:203], v[82:85]
	v_mfma_f32_16x16x32_bf16 v[74:77], v[164:167], v[208:211], 0
	v_mfma_f32_16x16x32_bf16 v[74:77], v[168:171], v[212:215], v[74:77]
	v_mfma_f32_16x16x32_bf16 v[66:69], v[172:175], v[208:211], 0
	v_mfma_f32_16x16x32_bf16 v[66:69], v[176:179], v[212:215], v[66:69]
	s_setprio 0
	s_barrier
	s_add_i32 s64, s50, s33
	s_mov_b32 m0, s64
	ds_read_b128 v[180:183], v146 offset:16384
	ds_read_b128 v[184:187], v146 offset:17408
	ds_read_b128 v[188:191], v146 offset:18432
	ds_read_b128 v[192:195], v146 offset:19456
	ds_read_b128 v[196:199], v146 offset:20480
	ds_read_b128 v[200:203], v146 offset:21504
	ds_read_b128 v[208:211], v146 offset:22528
	ds_read_b128 v[212:215], v146 offset:23552
	global_load_lds_dwordx4 v132, s[2:3]
	s_add_i32 m0, s64, 0x2000
	s_add_u32 s64, s2, 0x100000
	s_addc_u32 s65, s3, 0
	s_add_i32 s66, s51, s33
	global_load_lds_dwordx4 v136, s[2:3]
	s_mov_b32 m0, s66
	v_lshl_add_u64 v[220:221], s[38:39], 0, v[134:135]
	global_load_lds_dwordx4 v132, s[64:65]
	s_add_i32 m0, s66, 0x2000
	s_nop 0
	global_load_lds_dwordx4 v136, s[64:65]
	v_lshl_add_u64 v[218:219], s[38:39], 0, v[130:131]
	s_mov_b32 m0, s29
	s_nop 0
	global_load_lds_dwordx4 v130, s[38:39]
	s_mov_b32 m0, s31
	s_nop 0
	global_load_lds_dwordx4 v134, s[38:39]
	s_waitcnt vmcnt(8)
	s_waitcnt lgkmcnt(0)
	s_barrier
	s_setprio 1
	s_waitcnt lgkmcnt(0)
	v_mfma_f32_16x16x32_bf16 v[62:65], v[148:151], v[180:183], 0
	v_mfma_f32_16x16x32_bf16 v[62:65], v[152:155], v[184:187], v[62:65]
	v_mfma_f32_16x16x32_bf16 v[54:57], v[156:159], v[180:183], 0
	v_mfma_f32_16x16x32_bf16 v[54:57], v[160:163], v[184:187], v[54:57]
	v_mfma_f32_16x16x32_bf16 v[46:49], v[148:151], v[188:191], 0
	v_mfma_f32_16x16x32_bf16 v[46:49], v[152:155], v[192:195], v[46:49]
	v_mfma_f32_16x16x32_bf16 v[38:41], v[156:159], v[188:191], 0
	v_mfma_f32_16x16x32_bf16 v[38:41], v[160:163], v[192:195], v[38:41]
	v_mfma_f32_16x16x32_bf16 v[30:33], v[148:151], v[196:199], 0
	v_mfma_f32_16x16x32_bf16 v[30:33], v[152:155], v[200:203], v[30:33]
	v_mfma_f32_16x16x32_bf16 v[22:25], v[156:159], v[196:199], 0
	v_mfma_f32_16x16x32_bf16 v[22:25], v[160:163], v[200:203], v[22:25]
	v_mfma_f32_16x16x32_bf16 v[14:17], v[148:151], v[208:211], 0
	v_mfma_f32_16x16x32_bf16 v[14:17], v[152:155], v[212:215], v[14:17]
	v_mfma_f32_16x16x32_bf16 v[6:9], v[156:159], v[208:211], 0
	v_mfma_f32_16x16x32_bf16 v[6:9], v[160:163], v[212:215], v[6:9]
	s_setprio 0
	s_setprio 1
	v_mfma_f32_16x16x32_bf16 v[58:61], v[164:167], v[180:183], 0
	v_mfma_f32_16x16x32_bf16 v[58:61], v[168:171], v[184:187], v[58:61]
	v_mfma_f32_16x16x32_bf16 v[50:53], v[172:175], v[180:183], 0
	v_mfma_f32_16x16x32_bf16 v[50:53], v[176:179], v[184:187], v[50:53]
	v_mfma_f32_16x16x32_bf16 v[42:45], v[164:167], v[188:191], 0
	v_mfma_f32_16x16x32_bf16 v[42:45], v[168:171], v[192:195], v[42:45]
	v_mfma_f32_16x16x32_bf16 v[34:37], v[172:175], v[188:191], 0
	v_mfma_f32_16x16x32_bf16 v[34:37], v[176:179], v[192:195], v[34:37]
	v_mfma_f32_16x16x32_bf16 v[26:29], v[164:167], v[196:199], 0
	v_mfma_f32_16x16x32_bf16 v[26:29], v[168:171], v[200:203], v[26:29]
	v_mfma_f32_16x16x32_bf16 v[18:21], v[172:175], v[196:199], 0
	v_mfma_f32_16x16x32_bf16 v[18:21], v[176:179], v[200:203], v[18:21]
	v_mfma_f32_16x16x32_bf16 v[10:13], v[164:167], v[208:211], 0
	v_mfma_f32_16x16x32_bf16 v[10:13], v[168:171], v[212:215], v[10:13]
	v_mfma_f32_16x16x32_bf16 v[2:5], v[172:175], v[208:211], 0
	v_mfma_f32_16x16x32_bf16 v[2:5], v[176:179], v[212:215], v[2:5]
	s_setprio 0
	s_barrier
	s_add_i32 s64, 0, 0x18000
	v_add_u32_e32 v147, s64, v142
	s_add_i32 s65, 0, 0x1c000
	ds_read_b128 v[148:151], v147
	ds_read_b128 v[152:155], v147 offset:1024
	ds_read_b128 v[156:159], v147 offset:2048
	ds_read_b128 v[160:163], v147 offset:3072
	v_add_u32_e32 v147, s65, v142
	ds_read_b128 v[164:167], v147
	ds_read_b128 v[168:171], v147 offset:1024
	ds_read_b128 v[172:175], v147 offset:2048
	ds_read_b128 v[176:179], v147 offset:3072
	s_add_u32 s38, s38, 0x100000
	s_addc_u32 s39, s39, 0
	s_mov_b32 m0, s41
	ds_read_b128 v[180:183], v146 offset:32768
	ds_read_b128 v[184:187], v146 offset:33792
	ds_read_b128 v[188:191], v146 offset:34816
	ds_read_b128 v[192:195], v146 offset:35840
	ds_read_b128 v[196:199], v146 offset:36864
	ds_read_b128 v[200:203], v146 offset:37888
	ds_read_b128 v[208:211], v146 offset:38912
	ds_read_b128 v[212:215], v146 offset:39936
	global_load_lds_dwordx4 v130, s[38:39]
	s_mov_b32 m0, s42
	s_nop 0
	global_load_lds_dwordx4 v134, s[38:39]
	s_waitcnt vmcnt(8)
	s_waitcnt lgkmcnt(0)
	s_barrier
	s_setprio 1
	s_waitcnt lgkmcnt(0)
	v_mfma_f32_16x16x32_bf16 v[126:129], v[148:151], v[180:183], v[126:129]
	v_mfma_f32_16x16x32_bf16 v[126:129], v[152:155], v[184:187], v[126:129]
	v_mfma_f32_16x16x32_bf16 v[122:125], v[156:159], v[180:183], v[122:125]
	v_mfma_f32_16x16x32_bf16 v[122:125], v[160:163], v[184:187], v[122:125]
	v_mfma_f32_16x16x32_bf16 v[110:113], v[148:151], v[188:191], v[110:113]
	v_mfma_f32_16x16x32_bf16 v[110:113], v[152:155], v[192:195], v[110:113]
	v_mfma_f32_16x16x32_bf16 v[102:105], v[156:159], v[188:191], v[102:105]
	v_mfma_f32_16x16x32_bf16 v[102:105], v[160:163], v[192:195], v[102:105]
	v_mfma_f32_16x16x32_bf16 v[94:97], v[148:151], v[196:199], v[94:97]
	v_mfma_f32_16x16x32_bf16 v[94:97], v[152:155], v[200:203], v[94:97]
	v_mfma_f32_16x16x32_bf16 v[86:89], v[156:159], v[196:199], v[86:89]
	v_mfma_f32_16x16x32_bf16 v[86:89], v[160:163], v[200:203], v[86:89]
	v_mfma_f32_16x16x32_bf16 v[78:81], v[148:151], v[208:211], v[78:81]
	v_mfma_f32_16x16x32_bf16 v[78:81], v[152:155], v[212:215], v[78:81]
	v_mfma_f32_16x16x32_bf16 v[70:73], v[156:159], v[208:211], v[70:73]
	v_mfma_f32_16x16x32_bf16 v[70:73], v[160:163], v[212:215], v[70:73]
	s_setprio 0
	s_setprio 1
	v_mfma_f32_16x16x32_bf16 v[118:121], v[164:167], v[180:183], v[118:121]
	v_mfma_f32_16x16x32_bf16 v[118:121], v[168:171], v[184:187], v[118:121]
	v_mfma_f32_16x16x32_bf16 v[114:117], v[172:175], v[180:183], v[114:117]
	v_mfma_f32_16x16x32_bf16 v[114:117], v[176:179], v[184:187], v[114:117]
	v_mfma_f32_16x16x32_bf16 v[106:109], v[164:167], v[188:191], v[106:109]
	v_mfma_f32_16x16x32_bf16 v[106:109], v[168:171], v[192:195], v[106:109]
	v_mfma_f32_16x16x32_bf16 v[98:101], v[172:175], v[188:191], v[98:101]
	v_mfma_f32_16x16x32_bf16 v[98:101], v[176:179], v[192:195], v[98:101]
	v_mfma_f32_16x16x32_bf16 v[90:93], v[164:167], v[196:199], v[90:93]
	v_mfma_f32_16x16x32_bf16 v[90:93], v[168:171], v[200:203], v[90:93]
	v_mfma_f32_16x16x32_bf16 v[82:85], v[172:175], v[196:199], v[82:85]
	v_mfma_f32_16x16x32_bf16 v[82:85], v[176:179], v[200:203], v[82:85]
	v_mfma_f32_16x16x32_bf16 v[74:77], v[164:167], v[208:211], v[74:77]
	v_mfma_f32_16x16x32_bf16 v[74:77], v[168:171], v[212:215], v[74:77]
	v_mfma_f32_16x16x32_bf16 v[66:69], v[172:175], v[208:211], v[66:69]
	v_mfma_f32_16x16x32_bf16 v[66:69], v[176:179], v[212:215], v[66:69]
	s_setprio 0
	s_barrier
	s_add_i32 s38, s64, s33
	s_add_u32 s98, s2, s16
	s_addc_u32 s99, s3, s17
	s_mov_b32 m0, s38
	ds_read_b128 v[180:183], v146 offset:49152
	ds_read_b128 v[184:187], v146 offset:50176
	ds_read_b128 v[188:191], v146 offset:51200
	ds_read_b128 v[192:195], v146 offset:52224
	ds_read_b128 v[196:199], v146 offset:53248
	ds_read_b128 v[200:203], v146 offset:54272
	ds_read_b128 v[208:211], v146 offset:55296
	ds_read_b128 v[212:215], v146 offset:56320
	global_load_lds_dwordx4 v132, s[98:99]
	s_add_i32 m0, s38, 0x2000
	s_add_u32 s2, s2, 0x100080
	s_addc_u32 s3, s3, 0
	s_add_i32 s38, s65, s33
	global_load_lds_dwordx4 v136, s[98:99]
	s_mov_b32 m0, s38
	s_nop 0
	global_load_lds_dwordx4 v132, s[2:3]
	s_add_i32 m0, s38, 0x2000
	s_nop 0
	global_load_lds_dwordx4 v136, s[2:3]
	v_lshl_add_u64 v[204:205], v[218:219], 0, s[16:17]
	s_mov_b32 m0, s44
	s_nop 0
	global_load_lds_dwordx4 v[204:205], off
	v_lshl_add_u64 v[204:205], v[220:221], 0, s[16:17]
	s_mov_b32 m0, s45
	s_nop 0
	global_load_lds_dwordx4 v[204:205], off
	s_waitcnt vmcnt(8)
	s_waitcnt lgkmcnt(0)
	s_barrier
	s_setprio 1
	s_waitcnt lgkmcnt(0)
	v_mfma_f32_16x16x32_bf16 v[62:65], v[148:151], v[180:183], v[62:65]
	v_mfma_f32_16x16x32_bf16 v[62:65], v[152:155], v[184:187], v[62:65]
	v_mfma_f32_16x16x32_bf16 v[54:57], v[156:159], v[180:183], v[54:57]
	v_mfma_f32_16x16x32_bf16 v[54:57], v[160:163], v[184:187], v[54:57]
	v_mfma_f32_16x16x32_bf16 v[46:49], v[148:151], v[188:191], v[46:49]
	v_mfma_f32_16x16x32_bf16 v[46:49], v[152:155], v[192:195], v[46:49]
	v_mfma_f32_16x16x32_bf16 v[38:41], v[156:159], v[188:191], v[38:41]
	v_mfma_f32_16x16x32_bf16 v[38:41], v[160:163], v[192:195], v[38:41]
	v_mfma_f32_16x16x32_bf16 v[30:33], v[148:151], v[196:199], v[30:33]
	v_mfma_f32_16x16x32_bf16 v[30:33], v[152:155], v[200:203], v[30:33]
	v_mfma_f32_16x16x32_bf16 v[22:25], v[156:159], v[196:199], v[22:25]
	v_mfma_f32_16x16x32_bf16 v[22:25], v[160:163], v[200:203], v[22:25]
	v_mfma_f32_16x16x32_bf16 v[14:17], v[148:151], v[208:211], v[14:17]
	v_mfma_f32_16x16x32_bf16 v[14:17], v[152:155], v[212:215], v[14:17]
	v_mfma_f32_16x16x32_bf16 v[6:9], v[156:159], v[208:211], v[6:9]
	v_mfma_f32_16x16x32_bf16 v[6:9], v[160:163], v[212:215], v[6:9]
	s_setprio 0
	s_setprio 1
	v_mfma_f32_16x16x32_bf16 v[58:61], v[164:167], v[180:183], v[58:61]
	v_mfma_f32_16x16x32_bf16 v[58:61], v[168:171], v[184:187], v[58:61]
	v_mfma_f32_16x16x32_bf16 v[50:53], v[172:175], v[180:183], v[50:53]
	v_mfma_f32_16x16x32_bf16 v[50:53], v[176:179], v[184:187], v[50:53]
	v_mfma_f32_16x16x32_bf16 v[42:45], v[164:167], v[188:191], v[42:45]
	v_mfma_f32_16x16x32_bf16 v[42:45], v[168:171], v[192:195], v[42:45]
	v_mfma_f32_16x16x32_bf16 v[34:37], v[172:175], v[188:191], v[34:37]
	v_mfma_f32_16x16x32_bf16 v[34:37], v[176:179], v[192:195], v[34:37]
	v_mfma_f32_16x16x32_bf16 v[26:29], v[164:167], v[196:199], v[26:29]
	v_mfma_f32_16x16x32_bf16 v[26:29], v[168:171], v[200:203], v[26:29]
	v_mfma_f32_16x16x32_bf16 v[18:21], v[172:175], v[196:199], v[18:21]
	v_mfma_f32_16x16x32_bf16 v[18:21], v[176:179], v[200:203], v[18:21]
	v_mfma_f32_16x16x32_bf16 v[10:13], v[164:167], v[208:211], v[10:13]
	v_mfma_f32_16x16x32_bf16 v[10:13], v[168:171], v[212:215], v[10:13]
	v_mfma_f32_16x16x32_bf16 v[2:5], v[172:175], v[208:211], v[2:5]
	v_mfma_f32_16x16x32_bf16 v[2:5], v[176:179], v[212:215], v[2:5]
	s_setprio 0
	s_barrier
	s_add_u32 s36, s36, 0x100
	s_addc_u32 s37, s37, 0
	s_add_u32 s59, s59, 0x100
	s_addc_u32 s60, s60, 0
	s_cmp_ge_i32 s61, s35
	s_mov_b32 s2, s61
	s_cbranch_scc1 .Lkpeel_exit_4
.LBB0_800:
	ds_read_b128 v[148:151], v144
	ds_read_b128 v[152:155], v144 offset:1024
	ds_read_b128 v[156:159], v144 offset:2048
	ds_read_b128 v[160:163], v144 offset:3072
	ds_read_b128 v[164:167], v145
	ds_read_b128 v[168:171], v145 offset:1024
	ds_read_b128 v[172:175], v145 offset:2048
	ds_read_b128 v[176:179], v145 offset:3072
	s_add_i32 s61, s2, 2
	s_add_u32 s3, s36, 0xfff00080
	s_addc_u32 s38, s37, -1
	s_cmp_eq_u32 s58, s2
	s_cselect_b32 s2, s57, s59
	s_cselect_b32 s39, s0, s38
	s_cselect_b32 s38, s34, s3
	s_cselect_b32 s3, s56, s60
	s_add_i32 m0, s29, 0xc000
	ds_read_b128 v[180:183], v146
	ds_read_b128 v[184:187], v146 offset:1024
	ds_read_b128 v[188:191], v146 offset:2048
	ds_read_b128 v[192:195], v146 offset:3072
	ds_read_b128 v[196:199], v146 offset:4096
	ds_read_b128 v[200:203], v146 offset:5120
	ds_read_b128 v[208:211], v146 offset:6144
	ds_read_b128 v[212:215], v146 offset:7168
	global_load_lds_dwordx4 v138, s[36:37]
	s_add_i32 m0, s29, 0xe000
	s_nop 0
	global_load_lds_dwordx4 v140, s[36:37]
	s_waitcnt vmcnt(8)
	s_waitcnt lgkmcnt(0)
	s_barrier
	s_setprio 1
	s_waitcnt lgkmcnt(0)
	v_mfma_f32_16x16x32_bf16 v[126:129], v[148:151], v[180:183], v[126:129]
	v_mfma_f32_16x16x32_bf16 v[126:129], v[152:155], v[184:187], v[126:129]
	v_mfma_f32_16x16x32_bf16 v[122:125], v[156:159], v[180:183], v[122:125]
	v_mfma_f32_16x16x32_bf16 v[122:125], v[160:163], v[184:187], v[122:125]
	v_mfma_f32_16x16x32_bf16 v[110:113], v[148:151], v[188:191], v[110:113]
	v_mfma_f32_16x16x32_bf16 v[110:113], v[152:155], v[192:195], v[110:113]
	v_mfma_f32_16x16x32_bf16 v[102:105], v[156:159], v[188:191], v[102:105]
	v_mfma_f32_16x16x32_bf16 v[102:105], v[160:163], v[192:195], v[102:105]
	v_mfma_f32_16x16x32_bf16 v[94:97], v[148:151], v[196:199], v[94:97]
	v_mfma_f32_16x16x32_bf16 v[94:97], v[152:155], v[200:203], v[94:97]
	v_mfma_f32_16x16x32_bf16 v[86:89], v[156:159], v[196:199], v[86:89]
	v_mfma_f32_16x16x32_bf16 v[86:89], v[160:163], v[200:203], v[86:89]
	v_mfma_f32_16x16x32_bf16 v[78:81], v[148:151], v[208:211], v[78:81]
	v_mfma_f32_16x16x32_bf16 v[78:81], v[152:155], v[212:215], v[78:81]
	v_mfma_f32_16x16x32_bf16 v[70:73], v[156:159], v[208:211], v[70:73]
	v_mfma_f32_16x16x32_bf16 v[70:73], v[160:163], v[212:215], v[70:73]
	s_setprio 0
	s_setprio 1
	v_mfma_f32_16x16x32_bf16 v[118:121], v[164:167], v[180:183], v[118:121]
	v_mfma_f32_16x16x32_bf16 v[118:121], v[168:171], v[184:187], v[118:121]
	v_mfma_f32_16x16x32_bf16 v[114:117], v[172:175], v[180:183], v[114:117]
	v_mfma_f32_16x16x32_bf16 v[114:117], v[176:179], v[184:187], v[114:117]
	v_mfma_f32_16x16x32_bf16 v[106:109], v[164:167], v[188:191], v[106:109]
	v_mfma_f32_16x16x32_bf16 v[106:109], v[168:171], v[192:195], v[106:109]
	v_mfma_f32_16x16x32_bf16 v[98:101], v[172:175], v[188:191], v[98:101]
	v_mfma_f32_16x16x32_bf16 v[98:101], v[176:179], v[192:195], v[98:101]
	v_mfma_f32_16x16x32_bf16 v[90:93], v[164:167], v[196:199], v[90:93]
	v_mfma_f32_16x16x32_bf16 v[90:93], v[168:171], v[200:203], v[90:93]
	v_mfma_f32_16x16x32_bf16 v[82:85], v[172:175], v[196:199], v[82:85]
	v_mfma_f32_16x16x32_bf16 v[82:85], v[176:179], v[200:203], v[82:85]
	v_mfma_f32_16x16x32_bf16 v[74:77], v[164:167], v[208:211], v[74:77]
	v_mfma_f32_16x16x32_bf16 v[74:77], v[168:171], v[212:215], v[74:77]
	v_mfma_f32_16x16x32_bf16 v[66:69], v[172:175], v[208:211], v[66:69]
	v_mfma_f32_16x16x32_bf16 v[66:69], v[176:179], v[212:215], v[66:69]
	s_setprio 0
	s_barrier
	s_add_i32 s64, s50, s33
	s_mov_b32 m0, s64
	ds_read_b128 v[180:183], v146 offset:16384
	ds_read_b128 v[184:187], v146 offset:17408
	ds_read_b128 v[188:191], v146 offset:18432
	ds_read_b128 v[192:195], v146 offset:19456
	ds_read_b128 v[196:199], v146 offset:20480
	ds_read_b128 v[200:203], v146 offset:21504
	ds_read_b128 v[208:211], v146 offset:22528
	ds_read_b128 v[212:215], v146 offset:23552
	global_load_lds_dwordx4 v132, s[2:3]
	s_add_i32 m0, s64, 0x2000
	s_add_u32 s64, s2, 0x100000
	s_addc_u32 s65, s3, 0
	s_add_i32 s66, s51, s33
	global_load_lds_dwordx4 v136, s[2:3]
	s_mov_b32 m0, s66
	v_lshl_add_u64 v[220:221], s[38:39], 0, v[134:135]
	global_load_lds_dwordx4 v132, s[64:65]
	s_add_i32 m0, s66, 0x2000
	s_nop 0
	global_load_lds_dwordx4 v136, s[64:65]
	v_lshl_add_u64 v[218:219], s[38:39], 0, v[130:131]
	s_mov_b32 m0, s29
	s_nop 0
	global_load_lds_dwordx4 v130, s[38:39]
	s_mov_b32 m0, s31
	s_nop 0
	global_load_lds_dwordx4 v134, s[38:39]
	s_waitcnt vmcnt(8)
	s_waitcnt lgkmcnt(0)
	s_barrier
	s_setprio 1
	s_waitcnt lgkmcnt(0)
	v_mfma_f32_16x16x32_bf16 v[62:65], v[148:151], v[180:183], v[62:65]
	v_mfma_f32_16x16x32_bf16 v[62:65], v[152:155], v[184:187], v[62:65]
	v_mfma_f32_16x16x32_bf16 v[54:57], v[156:159], v[180:183], v[54:57]
	v_mfma_f32_16x16x32_bf16 v[54:57], v[160:163], v[184:187], v[54:57]
	v_mfma_f32_16x16x32_bf16 v[46:49], v[148:151], v[188:191], v[46:49]
	v_mfma_f32_16x16x32_bf16 v[46:49], v[152:155], v[192:195], v[46:49]
	v_mfma_f32_16x16x32_bf16 v[38:41], v[156:159], v[188:191], v[38:41]
	v_mfma_f32_16x16x32_bf16 v[38:41], v[160:163], v[192:195], v[38:41]
	v_mfma_f32_16x16x32_bf16 v[30:33], v[148:151], v[196:199], v[30:33]
	v_mfma_f32_16x16x32_bf16 v[30:33], v[152:155], v[200:203], v[30:33]
	v_mfma_f32_16x16x32_bf16 v[22:25], v[156:159], v[196:199], v[22:25]
	v_mfma_f32_16x16x32_bf16 v[22:25], v[160:163], v[200:203], v[22:25]
	v_mfma_f32_16x16x32_bf16 v[14:17], v[148:151], v[208:211], v[14:17]
	v_mfma_f32_16x16x32_bf16 v[14:17], v[152:155], v[212:215], v[14:17]
	v_mfma_f32_16x16x32_bf16 v[6:9], v[156:159], v[208:211], v[6:9]
	v_mfma_f32_16x16x32_bf16 v[6:9], v[160:163], v[212:215], v[6:9]
	s_setprio 0
	s_setprio 1
	v_mfma_f32_16x16x32_bf16 v[58:61], v[164:167], v[180:183], v[58:61]
	v_mfma_f32_16x16x32_bf16 v[58:61], v[168:171], v[184:187], v[58:61]
	v_mfma_f32_16x16x32_bf16 v[50:53], v[172:175], v[180:183], v[50:53]
	v_mfma_f32_16x16x32_bf16 v[50:53], v[176:179], v[184:187], v[50:53]
	v_mfma_f32_16x16x32_bf16 v[42:45], v[164:167], v[188:191], v[42:45]
	v_mfma_f32_16x16x32_bf16 v[42:45], v[168:171], v[192:195], v[42:45]
	v_mfma_f32_16x16x32_bf16 v[34:37], v[172:175], v[188:191], v[34:37]
	v_mfma_f32_16x16x32_bf16 v[34:37], v[176:179], v[192:195], v[34:37]
	v_mfma_f32_16x16x32_bf16 v[26:29], v[164:167], v[196:199], v[26:29]
	v_mfma_f32_16x16x32_bf16 v[26:29], v[168:171], v[200:203], v[26:29]
	v_mfma_f32_16x16x32_bf16 v[18:21], v[172:175], v[196:199], v[18:21]
	v_mfma_f32_16x16x32_bf16 v[18:21], v[176:179], v[200:203], v[18:21]
	v_mfma_f32_16x16x32_bf16 v[10:13], v[164:167], v[208:211], v[10:13]
	v_mfma_f32_16x16x32_bf16 v[10:13], v[168:171], v[212:215], v[10:13]
	v_mfma_f32_16x16x32_bf16 v[2:5], v[172:175], v[208:211], v[2:5]
	v_mfma_f32_16x16x32_bf16 v[2:5], v[176:179], v[212:215], v[2:5]
	s_setprio 0
	s_barrier
	s_add_i32 s64, 0, 0x18000
	v_add_u32_e32 v147, s64, v142
	s_add_i32 s65, 0, 0x1c000
	ds_read_b128 v[148:151], v147
	ds_read_b128 v[152:155], v147 offset:1024
	ds_read_b128 v[156:159], v147 offset:2048
	ds_read_b128 v[160:163], v147 offset:3072
	v_add_u32_e32 v147, s65, v142
	ds_read_b128 v[164:167], v147
	ds_read_b128 v[168:171], v147 offset:1024
	ds_read_b128 v[172:175], v147 offset:2048
	ds_read_b128 v[176:179], v147 offset:3072
	s_add_u32 s38, s38, 0x100000
	s_addc_u32 s39, s39, 0
	s_mov_b32 m0, s41
	ds_read_b128 v[180:183], v146 offset:32768
	ds_read_b128 v[184:187], v146 offset:33792
	ds_read_b128 v[188:191], v146 offset:34816
	ds_read_b128 v[192:195], v146 offset:35840
	ds_read_b128 v[196:199], v146 offset:36864
	ds_read_b128 v[200:203], v146 offset:37888
	ds_read_b128 v[208:211], v146 offset:38912
	ds_read_b128 v[212:215], v146 offset:39936
	global_load_lds_dwordx4 v130, s[38:39]
	s_mov_b32 m0, s42
	s_nop 0
	global_load_lds_dwordx4 v134, s[38:39]
	s_waitcnt vmcnt(8)
	s_waitcnt lgkmcnt(0)
	s_barrier
	s_setprio 1
	s_waitcnt lgkmcnt(0)
	v_mfma_f32_16x16x32_bf16 v[126:129], v[148:151], v[180:183], v[126:129]
	v_mfma_f32_16x16x32_bf16 v[126:129], v[152:155], v[184:187], v[126:129]
	v_mfma_f32_16x16x32_bf16 v[122:125], v[156:159], v[180:183], v[122:125]
	v_mfma_f32_16x16x32_bf16 v[122:125], v[160:163], v[184:187], v[122:125]
	v_mfma_f32_16x16x32_bf16 v[110:113], v[148:151], v[188:191], v[110:113]
	v_mfma_f32_16x16x32_bf16 v[110:113], v[152:155], v[192:195], v[110:113]
	v_mfma_f32_16x16x32_bf16 v[102:105], v[156:159], v[188:191], v[102:105]
	v_mfma_f32_16x16x32_bf16 v[102:105], v[160:163], v[192:195], v[102:105]
	v_mfma_f32_16x16x32_bf16 v[94:97], v[148:151], v[196:199], v[94:97]
	v_mfma_f32_16x16x32_bf16 v[94:97], v[152:155], v[200:203], v[94:97]
	v_mfma_f32_16x16x32_bf16 v[86:89], v[156:159], v[196:199], v[86:89]
	v_mfma_f32_16x16x32_bf16 v[86:89], v[160:163], v[200:203], v[86:89]
	v_mfma_f32_16x16x32_bf16 v[78:81], v[148:151], v[208:211], v[78:81]
	v_mfma_f32_16x16x32_bf16 v[78:81], v[152:155], v[212:215], v[78:81]
	v_mfma_f32_16x16x32_bf16 v[70:73], v[156:159], v[208:211], v[70:73]
	v_mfma_f32_16x16x32_bf16 v[70:73], v[160:163], v[212:215], v[70:73]
	s_setprio 0
	s_setprio 1
	v_mfma_f32_16x16x32_bf16 v[118:121], v[164:167], v[180:183], v[118:121]
	v_mfma_f32_16x16x32_bf16 v[118:121], v[168:171], v[184:187], v[118:121]
	v_mfma_f32_16x16x32_bf16 v[114:117], v[172:175], v[180:183], v[114:117]
	v_mfma_f32_16x16x32_bf16 v[114:117], v[176:179], v[184:187], v[114:117]
	v_mfma_f32_16x16x32_bf16 v[106:109], v[164:167], v[188:191], v[106:109]
	v_mfma_f32_16x16x32_bf16 v[106:109], v[168:171], v[192:195], v[106:109]
	v_mfma_f32_16x16x32_bf16 v[98:101], v[172:175], v[188:191], v[98:101]
	v_mfma_f32_16x16x32_bf16 v[98:101], v[176:179], v[192:195], v[98:101]
	v_mfma_f32_16x16x32_bf16 v[90:93], v[164:167], v[196:199], v[90:93]
	v_mfma_f32_16x16x32_bf16 v[90:93], v[168:171], v[200:203], v[90:93]
	v_mfma_f32_16x16x32_bf16 v[82:85], v[172:175], v[196:199], v[82:85]
	v_mfma_f32_16x16x32_bf16 v[82:85], v[176:179], v[200:203], v[82:85]
	v_mfma_f32_16x16x32_bf16 v[74:77], v[164:167], v[208:211], v[74:77]
	v_mfma_f32_16x16x32_bf16 v[74:77], v[168:171], v[212:215], v[74:77]
	v_mfma_f32_16x16x32_bf16 v[66:69], v[172:175], v[208:211], v[66:69]
	v_mfma_f32_16x16x32_bf16 v[66:69], v[176:179], v[212:215], v[66:69]
	s_setprio 0
	s_barrier
	s_add_i32 s38, s64, s33
	s_add_u32 s98, s2, s16
	s_addc_u32 s99, s3, s17
	s_mov_b32 m0, s38
	ds_read_b128 v[180:183], v146 offset:49152
	ds_read_b128 v[184:187], v146 offset:50176
	ds_read_b128 v[188:191], v146 offset:51200
	ds_read_b128 v[192:195], v146 offset:52224
	ds_read_b128 v[196:199], v146 offset:53248
	ds_read_b128 v[200:203], v146 offset:54272
	ds_read_b128 v[208:211], v146 offset:55296
	ds_read_b128 v[212:215], v146 offset:56320
	global_load_lds_dwordx4 v132, s[98:99]
	s_add_i32 m0, s38, 0x2000
	s_add_u32 s2, s2, 0x100080
	s_addc_u32 s3, s3, 0
	s_add_i32 s38, s65, s33
	global_load_lds_dwordx4 v136, s[98:99]
	s_mov_b32 m0, s38
	s_nop 0
	global_load_lds_dwordx4 v132, s[2:3]
	s_add_i32 m0, s38, 0x2000
	s_nop 0
	global_load_lds_dwordx4 v136, s[2:3]
	v_lshl_add_u64 v[204:205], v[218:219], 0, s[16:17]
	s_mov_b32 m0, s44
	s_nop 0
	global_load_lds_dwordx4 v[204:205], off
	v_lshl_add_u64 v[204:205], v[220:221], 0, s[16:17]
	s_mov_b32 m0, s45
	s_nop 0
	global_load_lds_dwordx4 v[204:205], off
	s_waitcnt vmcnt(8)
	s_waitcnt lgkmcnt(0)
	s_barrier
	s_setprio 1
	s_waitcnt lgkmcnt(0)
	v_mfma_f32_16x16x32_bf16 v[62:65], v[148:151], v[180:183], v[62:65]
	v_mfma_f32_16x16x32_bf16 v[62:65], v[152:155], v[184:187], v[62:65]
	v_mfma_f32_16x16x32_bf16 v[54:57], v[156:159], v[180:183], v[54:57]
	v_mfma_f32_16x16x32_bf16 v[54:57], v[160:163], v[184:187], v[54:57]
	v_mfma_f32_16x16x32_bf16 v[46:49], v[148:151], v[188:191], v[46:49]
	v_mfma_f32_16x16x32_bf16 v[46:49], v[152:155], v[192:195], v[46:49]
	v_mfma_f32_16x16x32_bf16 v[38:41], v[156:159], v[188:191], v[38:41]
	v_mfma_f32_16x16x32_bf16 v[38:41], v[160:163], v[192:195], v[38:41]
	v_mfma_f32_16x16x32_bf16 v[30:33], v[148:151], v[196:199], v[30:33]
	v_mfma_f32_16x16x32_bf16 v[30:33], v[152:155], v[200:203], v[30:33]
	v_mfma_f32_16x16x32_bf16 v[22:25], v[156:159], v[196:199], v[22:25]
	v_mfma_f32_16x16x32_bf16 v[22:25], v[160:163], v[200:203], v[22:25]
	v_mfma_f32_16x16x32_bf16 v[14:17], v[148:151], v[208:211], v[14:17]
	v_mfma_f32_16x16x32_bf16 v[14:17], v[152:155], v[212:215], v[14:17]
	v_mfma_f32_16x16x32_bf16 v[6:9], v[156:159], v[208:211], v[6:9]
	v_mfma_f32_16x16x32_bf16 v[6:9], v[160:163], v[212:215], v[6:9]
	s_setprio 0
	s_setprio 1
	v_mfma_f32_16x16x32_bf16 v[58:61], v[164:167], v[180:183], v[58:61]
	v_mfma_f32_16x16x32_bf16 v[58:61], v[168:171], v[184:187], v[58:61]
	v_mfma_f32_16x16x32_bf16 v[50:53], v[172:175], v[180:183], v[50:53]
	v_mfma_f32_16x16x32_bf16 v[50:53], v[176:179], v[184:187], v[50:53]
	v_mfma_f32_16x16x32_bf16 v[42:45], v[164:167], v[188:191], v[42:45]
	v_mfma_f32_16x16x32_bf16 v[42:45], v[168:171], v[192:195], v[42:45]
	v_mfma_f32_16x16x32_bf16 v[34:37], v[172:175], v[188:191], v[34:37]
	v_mfma_f32_16x16x32_bf16 v[34:37], v[176:179], v[192:195], v[34:37]
	v_mfma_f32_16x16x32_bf16 v[26:29], v[164:167], v[196:199], v[26:29]
	v_mfma_f32_16x16x32_bf16 v[26:29], v[168:171], v[200:203], v[26:29]
	v_mfma_f32_16x16x32_bf16 v[18:21], v[172:175], v[196:199], v[18:21]
	v_mfma_f32_16x16x32_bf16 v[18:21], v[176:179], v[200:203], v[18:21]
	v_mfma_f32_16x16x32_bf16 v[10:13], v[164:167], v[208:211], v[10:13]
	v_mfma_f32_16x16x32_bf16 v[10:13], v[168:171], v[212:215], v[10:13]
	v_mfma_f32_16x16x32_bf16 v[2:5], v[172:175], v[208:211], v[2:5]
	v_mfma_f32_16x16x32_bf16 v[2:5], v[176:179], v[212:215], v[2:5]
	s_setprio 0
	s_barrier
	s_add_u32 s36, s36, 0x100
	s_addc_u32 s37, s37, 0
	s_add_u32 s59, s59, 0x100
	s_addc_u32 s60, s60, 0
	s_cmp_ge_i32 s61, s35
	s_mov_b32 s2, s61
	s_cbranch_scc0 .LBB0_800

.LBB0_959:
	s_lshl_b32 s0, s16, 20
	s_and_b32 s0, s0, 0xff00000
	v_readlane_b32 s12, v248, 20
	v_readlane_b32 s13, v248, 21
	s_add_u32 s0, s12, s0
	s_addc_u32 s1, s13, 0
	s_lshr_b32 s12, s16, 13
	s_and_b32 s12, s12, 0x7ff80
	s_add_u32 s0, s0, s12
	s_addc_u32 s1, s1, 0
	s_lshl_b32 s13, s16, 12
	s_and_b32 s13, s13, 0xff00000
	v_readlane_b32 s24, v248, 51
	s_add_u32 s13, s24, s13
	v_readlane_b32 s24, v248, 53
	s_addc_u32 s24, s24, 0
	s_add_u32 s12, s13, s12
	s_addc_u32 s13, s24, 0
	s_cmp_lt_i32 s19, 1
	v_cmp_gt_i64_e64 s[16:17], s[16:17], -1
	s_cbranch_scc1 .LBB0_976
	s_and_b64 s[36:37], s[16:17], exec
	s_cselect_b32 s24, s1, s35
	s_cselect_b32 s53, s0, s34
	s_cselect_b32 s56, s13, s3
	s_cselect_b32 s57, s12, s2
	s_add_i32 s58, s19, -2
	s_add_u32 s34, s34, 0x80080
	s_addc_u32 s35, s35, 0
	s_add_u32 s59, s2, 0x100
	s_addc_u32 s60, s3, 0
	s_mov_b32 s2, 0
	s_add_i32 s61, s2, 2
	s_add_u32 s3, s34, 0xfff80080
	s_addc_u32 s36, s35, -1
	s_add_i32 s64, 0, 0x10000
	s_cmp_eq_u32 s58, s2
	s_cselect_b32 s37, s24, s36
	s_cselect_b32 s36, s53, s3
	v_add_u32_e32 v142, s64, v131
	s_cselect_b32 s3, s56, s60
	s_cselect_b32 s2, s57, s59
	s_add_i32 s66, 0, 0x14000
	ds_read_b128 v[148:151], v142
	ds_read_b128 v[152:155], v142 offset:1024
	ds_read_b128 v[156:159], v142 offset:2048
	ds_read_b128 v[160:163], v142 offset:3072
	v_add_u32_e32 v142, s66, v131
	ds_read_b128 v[188:191], v142
	ds_read_b128 v[192:195], v142 offset:1024
	ds_read_b128 v[196:199], v142 offset:2048
	ds_read_b128 v[200:203], v142 offset:3072
	s_add_i32 m0, s40, 0xc000
	ds_read_b128 v[204:207], v186
	ds_read_b128 v[208:211], v186 offset:1024
	ds_read_b128 v[212:215], v186 offset:2048
	ds_read_b128 v[216:219], v186 offset:3072
	ds_read_b128 v[220:223], v186 offset:4096
	ds_read_b128 v[224:227], v186 offset:5120
	ds_read_b128 v[228:231], v186 offset:6144
	ds_read_b128 v[232:235], v186 offset:7168
	global_load_lds_dwordx4 v144, s[34:35]
	s_add_i32 m0, s40, 0xe000
	s_nop 0
	global_load_lds_dwordx4 v146, s[34:35]
	s_waitcnt vmcnt(8)
	s_waitcnt lgkmcnt(0)
	s_barrier
	s_setprio 1
	s_waitcnt lgkmcnt(0)
	v_mfma_i32_16x16x64_i8 v[126:129], v[148:151], v[204:207], 0
	v_mfma_i32_16x16x64_i8 v[126:129], v[152:155], v[208:211], v[126:129]
	v_mfma_i32_16x16x64_i8 v[122:125], v[156:159], v[204:207], 0
	v_mfma_i32_16x16x64_i8 v[122:125], v[160:163], v[208:211], v[122:125]
	v_mfma_i32_16x16x64_i8 v[118:121], v[148:151], v[212:215], 0
	v_mfma_i32_16x16x64_i8 v[118:121], v[152:155], v[216:219], v[118:121]
	v_mfma_i32_16x16x64_i8 v[114:117], v[156:159], v[212:215], 0
	v_mfma_i32_16x16x64_i8 v[114:117], v[160:163], v[216:219], v[114:117]
	v_mfma_i32_16x16x64_i8 v[110:113], v[148:151], v[220:223], 0
	v_mfma_i32_16x16x64_i8 v[110:113], v[152:155], v[224:227], v[110:113]
	v_mfma_i32_16x16x64_i8 v[106:109], v[156:159], v[220:223], 0
	v_mfma_i32_16x16x64_i8 v[106:109], v[160:163], v[224:227], v[106:109]
	v_mfma_i32_16x16x64_i8 v[102:105], v[148:151], v[228:231], 0
	v_mfma_i32_16x16x64_i8 v[102:105], v[152:155], v[232:235], v[102:105]
	v_mfma_i32_16x16x64_i8 v[98:101], v[156:159], v[228:231], 0
	v_mfma_i32_16x16x64_i8 v[98:101], v[160:163], v[232:235], v[98:101]
	s_setprio 0
	s_setprio 1
	v_mfma_i32_16x16x64_i8 v[94:97], v[188:191], v[204:207], 0
	v_mfma_i32_16x16x64_i8 v[94:97], v[192:195], v[208:211], v[94:97]
	v_mfma_i32_16x16x64_i8 v[90:93], v[196:199], v[204:207], 0
	v_mfma_i32_16x16x64_i8 v[90:93], v[200:203], v[208:211], v[90:93]
	v_mfma_i32_16x16x64_i8 v[86:89], v[188:191], v[212:215], 0
	v_mfma_i32_16x16x64_i8 v[86:89], v[192:195], v[216:219], v[86:89]
	v_mfma_i32_16x16x64_i8 v[82:85], v[196:199], v[212:215], 0
	v_mfma_i32_16x16x64_i8 v[82:85], v[200:203], v[216:219], v[82:85]
	v_mfma_i32_16x16x64_i8 v[78:81], v[188:191], v[220:223], 0
	v_mfma_i32_16x16x64_i8 v[78:81], v[192:195], v[224:227], v[78:81]
	v_mfma_i32_16x16x64_i8 v[74:77], v[196:199], v[220:223], 0
	v_mfma_i32_16x16x64_i8 v[74:77], v[200:203], v[224:227], v[74:77]
	v_mfma_i32_16x16x64_i8 v[70:73], v[188:191], v[228:231], 0
	v_mfma_i32_16x16x64_i8 v[70:73], v[192:195], v[232:235], v[70:73]
	v_mfma_i32_16x16x64_i8 v[66:69], v[196:199], v[228:231], 0
	v_mfma_i32_16x16x64_i8 v[66:69], v[200:203], v[232:235], v[66:69]
	s_setprio 0
	s_barrier
	s_add_i32 s64, s64, s39
	s_mov_b32 m0, s64
	ds_read_b128 v[204:207], v186 offset:16384
	ds_read_b128 v[208:211], v186 offset:17408
	ds_read_b128 v[212:215], v186 offset:18432
	ds_read_b128 v[216:219], v186 offset:19456
	ds_read_b128 v[220:223], v186 offset:20480
	ds_read_b128 v[224:227], v186 offset:21504
	ds_read_b128 v[228:231], v186 offset:22528
	ds_read_b128 v[232:235], v186 offset:23552
	global_load_lds_dwordx4 v136, s[2:3]
	s_add_i32 m0, s64, 0x2000
	s_add_u32 s64, s2, 0x80000
	s_addc_u32 s65, s3, 0
	s_add_i32 s66, s66, s39
	global_load_lds_dwordx4 v140, s[2:3]
	s_mov_b32 m0, s66
	v_lshl_add_u64 v[242:243], s[36:37], 0, v[138:139]
	global_load_lds_dwordx4 v136, s[64:65]
	s_add_i32 m0, s66, 0x2000
	s_nop 0
	global_load_lds_dwordx4 v140, s[64:65]
	v_lshl_add_u64 v[240:241], s[36:37], 0, v[134:135]
	s_mov_b32 m0, s40
	s_nop 0
	global_load_lds_dwordx4 v134, s[36:37]
	s_mov_b32 m0, s41
	s_nop 0
	global_load_lds_dwordx4 v138, s[36:37]
	s_waitcnt vmcnt(8)
	s_waitcnt lgkmcnt(0)
	s_barrier
	s_setprio 1
	s_waitcnt lgkmcnt(0)
	v_mfma_i32_16x16x64_i8 v[62:65], v[148:151], v[204:207], 0
	v_mfma_i32_16x16x64_i8 v[62:65], v[152:155], v[208:211], v[62:65]
	v_mfma_i32_16x16x64_i8 v[58:61], v[156:159], v[204:207], 0
	v_mfma_i32_16x16x64_i8 v[58:61], v[160:163], v[208:211], v[58:61]
	v_mfma_i32_16x16x64_i8 v[54:57], v[148:151], v[212:215], 0
	v_mfma_i32_16x16x64_i8 v[54:57], v[152:155], v[216:219], v[54:57]
	v_mfma_i32_16x16x64_i8 v[50:53], v[156:159], v[212:215], 0
	v_mfma_i32_16x16x64_i8 v[50:53], v[160:163], v[216:219], v[50:53]
	v_mfma_i32_16x16x64_i8 v[46:49], v[148:151], v[220:223], 0
	v_mfma_i32_16x16x64_i8 v[46:49], v[152:155], v[224:227], v[46:49]
	v_mfma_i32_16x16x64_i8 v[42:45], v[156:159], v[220:223], 0
	v_mfma_i32_16x16x64_i8 v[42:45], v[160:163], v[224:227], v[42:45]
	v_mfma_i32_16x16x64_i8 v[38:41], v[148:151], v[228:231], 0
	v_mfma_i32_16x16x64_i8 v[38:41], v[152:155], v[232:235], v[38:41]
	v_mfma_i32_16x16x64_i8 v[34:37], v[156:159], v[228:231], 0
	v_mfma_i32_16x16x64_i8 v[34:37], v[160:163], v[232:235], v[34:37]
	s_setprio 0
	s_setprio 1
	v_mfma_i32_16x16x64_i8 v[30:33], v[188:191], v[204:207], 0
	v_mfma_i32_16x16x64_i8 v[30:33], v[192:195], v[208:211], v[30:33]
	v_mfma_i32_16x16x64_i8 v[26:29], v[196:199], v[204:207], 0
	v_mfma_i32_16x16x64_i8 v[26:29], v[200:203], v[208:211], v[26:29]
	v_mfma_i32_16x16x64_i8 v[22:25], v[188:191], v[212:215], 0
	v_mfma_i32_16x16x64_i8 v[22:25], v[192:195], v[216:219], v[22:25]
	v_mfma_i32_16x16x64_i8 v[18:21], v[196:199], v[212:215], 0
	v_mfma_i32_16x16x64_i8 v[18:21], v[200:203], v[216:219], v[18:21]
	v_mfma_i32_16x16x64_i8 v[14:17], v[188:191], v[220:223], 0
	v_mfma_i32_16x16x64_i8 v[14:17], v[192:195], v[224:227], v[14:17]
	v_mfma_i32_16x16x64_i8 v[10:13], v[196:199], v[220:223], 0
	v_mfma_i32_16x16x64_i8 v[10:13], v[200:203], v[224:227], v[10:13]
	v_mfma_i32_16x16x64_i8 v[6:9], v[188:191], v[228:231], 0
	v_mfma_i32_16x16x64_i8 v[6:9], v[192:195], v[232:235], v[6:9]
	v_mfma_i32_16x16x64_i8 v[2:5], v[196:199], v[228:231], 0
	v_mfma_i32_16x16x64_i8 v[2:5], v[200:203], v[232:235], v[2:5]
	s_setprio 0
	s_barrier
	s_add_i32 s64, 0, 0x18000
	v_add_u32_e32 v142, s64, v131
	s_add_i32 s65, 0, 0x1c000
	ds_read_b128 v[148:151], v142
	ds_read_b128 v[152:155], v142 offset:1024
	ds_read_b128 v[156:159], v142 offset:2048
	ds_read_b128 v[160:163], v142 offset:3072
	v_add_u32_e32 v142, s65, v131
	ds_read_b128 v[188:191], v142
	ds_read_b128 v[192:195], v142 offset:1024
	ds_read_b128 v[196:199], v142 offset:2048
	ds_read_b128 v[200:203], v142 offset:3072
	s_add_u32 s36, s36, 0x80000
	s_addc_u32 s37, s37, 0
	s_mov_b32 m0, s42
	ds_read_b128 v[204:207], v186 offset:32768
	ds_read_b128 v[208:211], v186 offset:33792
	ds_read_b128 v[212:215], v186 offset:34816
	ds_read_b128 v[216:219], v186 offset:35840
	ds_read_b128 v[220:223], v186 offset:36864
	ds_read_b128 v[224:227], v186 offset:37888
	ds_read_b128 v[228:231], v186 offset:38912
	ds_read_b128 v[232:235], v186 offset:39936
	global_load_lds_dwordx4 v134, s[36:37]
	s_mov_b32 m0, s43
	s_nop 0
	global_load_lds_dwordx4 v138, s[36:37]
	s_waitcnt vmcnt(8)
	s_waitcnt lgkmcnt(0)
	s_barrier
	s_setprio 1
	s_waitcnt lgkmcnt(0)
	v_mfma_i32_16x16x64_i8 v[126:129], v[148:151], v[204:207], v[126:129]
	v_mfma_i32_16x16x64_i8 v[126:129], v[152:155], v[208:211], v[126:129]
	v_mfma_i32_16x16x64_i8 v[122:125], v[156:159], v[204:207], v[122:125]
	v_mfma_i32_16x16x64_i8 v[122:125], v[160:163], v[208:211], v[122:125]
	v_mfma_i32_16x16x64_i8 v[118:121], v[148:151], v[212:215], v[118:121]
	v_mfma_i32_16x16x64_i8 v[118:121], v[152:155], v[216:219], v[118:121]
	v_mfma_i32_16x16x64_i8 v[114:117], v[156:159], v[212:215], v[114:117]
	v_mfma_i32_16x16x64_i8 v[114:117], v[160:163], v[216:219], v[114:117]
	v_mfma_i32_16x16x64_i8 v[110:113], v[148:151], v[220:223], v[110:113]
	v_mfma_i32_16x16x64_i8 v[110:113], v[152:155], v[224:227], v[110:113]
	v_mfma_i32_16x16x64_i8 v[106:109], v[156:159], v[220:223], v[106:109]
	v_mfma_i32_16x16x64_i8 v[106:109], v[160:163], v[224:227], v[106:109]
	v_mfma_i32_16x16x64_i8 v[102:105], v[148:151], v[228:231], v[102:105]
	v_mfma_i32_16x16x64_i8 v[102:105], v[152:155], v[232:235], v[102:105]
	v_mfma_i32_16x16x64_i8 v[98:101], v[156:159], v[228:231], v[98:101]
	v_mfma_i32_16x16x64_i8 v[98:101], v[160:163], v[232:235], v[98:101]
	s_setprio 0
	s_setprio 1
	v_mfma_i32_16x16x64_i8 v[94:97], v[188:191], v[204:207], v[94:97]
	v_mfma_i32_16x16x64_i8 v[94:97], v[192:195], v[208:211], v[94:97]
	v_mfma_i32_16x16x64_i8 v[90:93], v[196:199], v[204:207], v[90:93]
	v_mfma_i32_16x16x64_i8 v[90:93], v[200:203], v[208:211], v[90:93]
	v_mfma_i32_16x16x64_i8 v[86:89], v[188:191], v[212:215], v[86:89]
	v_mfma_i32_16x16x64_i8 v[86:89], v[192:195], v[216:219], v[86:89]
	v_mfma_i32_16x16x64_i8 v[82:85], v[196:199], v[212:215], v[82:85]
	v_mfma_i32_16x16x64_i8 v[82:85], v[200:203], v[216:219], v[82:85]
	v_mfma_i32_16x16x64_i8 v[78:81], v[188:191], v[220:223], v[78:81]
	v_mfma_i32_16x16x64_i8 v[78:81], v[192:195], v[224:227], v[78:81]
	v_mfma_i32_16x16x64_i8 v[74:77], v[196:199], v[220:223], v[74:77]
	v_mfma_i32_16x16x64_i8 v[74:77], v[200:203], v[224:227], v[74:77]
	v_mfma_i32_16x16x64_i8 v[70:73], v[188:191], v[228:231], v[70:73]
	v_mfma_i32_16x16x64_i8 v[70:73], v[192:195], v[232:235], v[70:73]
	v_mfma_i32_16x16x64_i8 v[66:69], v[196:199], v[228:231], v[66:69]
	v_mfma_i32_16x16x64_i8 v[66:69], v[200:203], v[232:235], v[66:69]
	s_setprio 0
	s_barrier
	s_add_i32 s36, s64, s39
	s_add_u32 s98, s2, s28
	s_addc_u32 s99, s3, s29
	s_mov_b32 m0, s36
	ds_read_b128 v[204:207], v186 offset:49152
	ds_read_b128 v[208:211], v186 offset:50176
	ds_read_b128 v[212:215], v186 offset:51200
	ds_read_b128 v[216:219], v186 offset:52224
	ds_read_b128 v[220:223], v186 offset:53248
	ds_read_b128 v[224:227], v186 offset:54272
	ds_read_b128 v[228:231], v186 offset:55296
	ds_read_b128 v[232:235], v186 offset:56320
	global_load_lds_dwordx4 v136, s[98:99]
	s_add_i32 m0, s36, 0x2000
	s_add_u32 s2, s2, 0x80080
	s_addc_u32 s3, s3, 0
	s_add_i32 s36, s65, s39
	global_load_lds_dwordx4 v140, s[98:99]
	s_mov_b32 m0, s36
	s_nop 0
	global_load_lds_dwordx4 v136, s[2:3]
	s_add_i32 m0, s36, 0x2000
	s_nop 0
	global_load_lds_dwordx4 v140, s[2:3]
	v_lshl_add_u64 v[236:237], v[240:241], 0, s[28:29]
	s_mov_b32 m0, s45
	s_nop 0
	global_load_lds_dwordx4 v[236:237], off
	v_lshl_add_u64 v[236:237], v[242:243], 0, s[28:29]
	s_mov_b32 m0, s52
	s_nop 0
	global_load_lds_dwordx4 v[236:237], off
	s_waitcnt vmcnt(8)
	s_waitcnt lgkmcnt(0)
	s_barrier
	s_setprio 1
	s_waitcnt lgkmcnt(0)
	v_mfma_i32_16x16x64_i8 v[62:65], v[148:151], v[204:207], v[62:65]
	v_mfma_i32_16x16x64_i8 v[62:65], v[152:155], v[208:211], v[62:65]
	v_mfma_i32_16x16x64_i8 v[58:61], v[156:159], v[204:207], v[58:61]
	v_mfma_i32_16x16x64_i8 v[58:61], v[160:163], v[208:211], v[58:61]
	v_mfma_i32_16x16x64_i8 v[54:57], v[148:151], v[212:215], v[54:57]
	v_mfma_i32_16x16x64_i8 v[54:57], v[152:155], v[216:219], v[54:57]
	v_mfma_i32_16x16x64_i8 v[50:53], v[156:159], v[212:215], v[50:53]
	v_mfma_i32_16x16x64_i8 v[50:53], v[160:163], v[216:219], v[50:53]
	v_mfma_i32_16x16x64_i8 v[46:49], v[148:151], v[220:223], v[46:49]
	v_mfma_i32_16x16x64_i8 v[46:49], v[152:155], v[224:227], v[46:49]
	v_mfma_i32_16x16x64_i8 v[42:45], v[156:159], v[220:223], v[42:45]
	v_mfma_i32_16x16x64_i8 v[42:45], v[160:163], v[224:227], v[42:45]
	v_mfma_i32_16x16x64_i8 v[38:41], v[148:151], v[228:231], v[38:41]
	v_mfma_i32_16x16x64_i8 v[38:41], v[152:155], v[232:235], v[38:41]
	v_mfma_i32_16x16x64_i8 v[34:37], v[156:159], v[228:231], v[34:37]
	v_mfma_i32_16x16x64_i8 v[34:37], v[160:163], v[232:235], v[34:37]
	s_setprio 0
	s_setprio 1
	v_mfma_i32_16x16x64_i8 v[30:33], v[188:191], v[204:207], v[30:33]
	v_mfma_i32_16x16x64_i8 v[30:33], v[192:195], v[208:211], v[30:33]
	v_mfma_i32_16x16x64_i8 v[26:29], v[196:199], v[204:207], v[26:29]
	v_mfma_i32_16x16x64_i8 v[26:29], v[200:203], v[208:211], v[26:29]
	v_mfma_i32_16x16x64_i8 v[22:25], v[188:191], v[212:215], v[22:25]
	v_mfma_i32_16x16x64_i8 v[22:25], v[192:195], v[216:219], v[22:25]
	v_mfma_i32_16x16x64_i8 v[18:21], v[196:199], v[212:215], v[18:21]
	v_mfma_i32_16x16x64_i8 v[18:21], v[200:203], v[216:219], v[18:21]
	v_mfma_i32_16x16x64_i8 v[14:17], v[188:191], v[220:223], v[14:17]
	v_mfma_i32_16x16x64_i8 v[14:17], v[192:195], v[224:227], v[14:17]
	v_mfma_i32_16x16x64_i8 v[10:13], v[196:199], v[220:223], v[10:13]
	v_mfma_i32_16x16x64_i8 v[10:13], v[200:203], v[224:227], v[10:13]
	v_mfma_i32_16x16x64_i8 v[6:9], v[188:191], v[228:231], v[6:9]
	v_mfma_i32_16x16x64_i8 v[6:9], v[192:195], v[232:235], v[6:9]
	v_mfma_i32_16x16x64_i8 v[2:5], v[196:199], v[228:231], v[2:5]
	v_mfma_i32_16x16x64_i8 v[2:5], v[200:203], v[232:235], v[2:5]
	s_setprio 0
	s_barrier
	s_add_u32 s34, s34, 0x100
	s_addc_u32 s35, s35, 0
	s_add_u32 s59, s59, 0x100
	s_addc_u32 s60, s60, 0
	s_cmp_ge_i32 s61, s19
	s_mov_b32 s2, s61
	s_cbranch_scc1 .Lkpeel_exit_5
.LBB0_961:
	s_add_i32 s61, s2, 2
	s_add_u32 s3, s34, 0xfff80080
	s_addc_u32 s36, s35, -1
	s_add_i32 s64, 0, 0x10000
	s_cmp_eq_u32 s58, s2
	s_cselect_b32 s37, s24, s36
	s_cselect_b32 s36, s53, s3
	v_add_u32_e32 v142, s64, v131
	s_cselect_b32 s3, s56, s60
	s_cselect_b32 s2, s57, s59
	s_add_i32 s66, 0, 0x14000
	ds_read_b128 v[148:151], v142
	ds_read_b128 v[152:155], v142 offset:1024
	ds_read_b128 v[156:159], v142 offset:2048
	ds_read_b128 v[160:163], v142 offset:3072
	v_add_u32_e32 v142, s66, v131
	ds_read_b128 v[188:191], v142
	ds_read_b128 v[192:195], v142 offset:1024
	ds_read_b128 v[196:199], v142 offset:2048
	ds_read_b128 v[200:203], v142 offset:3072
	s_add_i32 m0, s40, 0xc000
	ds_read_b128 v[204:207], v186
	ds_read_b128 v[208:211], v186 offset:1024
	ds_read_b128 v[212:215], v186 offset:2048
	ds_read_b128 v[216:219], v186 offset:3072
	ds_read_b128 v[220:223], v186 offset:4096
	ds_read_b128 v[224:227], v186 offset:5120
	ds_read_b128 v[228:231], v186 offset:6144
	ds_read_b128 v[232:235], v186 offset:7168
	global_load_lds_dwordx4 v144, s[34:35]
	s_add_i32 m0, s40, 0xe000
	s_nop 0
	global_load_lds_dwordx4 v146, s[34:35]
	s_waitcnt vmcnt(8)
	s_waitcnt lgkmcnt(0)
	s_barrier
	s_setprio 1
	s_waitcnt lgkmcnt(0)
	v_mfma_i32_16x16x64_i8 v[126:129], v[148:151], v[204:207], v[126:129]
	v_mfma_i32_16x16x64_i8 v[126:129], v[152:155], v[208:211], v[126:129]
	v_mfma_i32_16x16x64_i8 v[122:125], v[156:159], v[204:207], v[122:125]
	v_mfma_i32_16x16x64_i8 v[122:125], v[160:163], v[208:211], v[122:125]
	v_mfma_i32_16x16x64_i8 v[118:121], v[148:151], v[212:215], v[118:121]
	v_mfma_i32_16x16x64_i8 v[118:121], v[152:155], v[216:219], v[118:121]
	v_mfma_i32_16x16x64_i8 v[114:117], v[156:159], v[212:215], v[114:117]
	v_mfma_i32_16x16x64_i8 v[114:117], v[160:163], v[216:219], v[114:117]
	v_mfma_i32_16x16x64_i8 v[110:113], v[148:151], v[220:223], v[110:113]
	v_mfma_i32_16x16x64_i8 v[110:113], v[152:155], v[224:227], v[110:113]
	v_mfma_i32_16x16x64_i8 v[106:109], v[156:159], v[220:223], v[106:109]
	v_mfma_i32_16x16x64_i8 v[106:109], v[160:163], v[224:227], v[106:109]
	v_mfma_i32_16x16x64_i8 v[102:105], v[148:151], v[228:231], v[102:105]
	v_mfma_i32_16x16x64_i8 v[102:105], v[152:155], v[232:235], v[102:105]
	v_mfma_i32_16x16x64_i8 v[98:101], v[156:159], v[228:231], v[98:101]
	v_mfma_i32_16x16x64_i8 v[98:101], v[160:163], v[232:235], v[98:101]
	s_setprio 0
	s_setprio 1
	v_mfma_i32_16x16x64_i8 v[94:97], v[188:191], v[204:207], v[94:97]
	v_mfma_i32_16x16x64_i8 v[94:97], v[192:195], v[208:211], v[94:97]
	v_mfma_i32_16x16x64_i8 v[90:93], v[196:199], v[204:207], v[90:93]
	v_mfma_i32_16x16x64_i8 v[90:93], v[200:203], v[208:211], v[90:93]
	v_mfma_i32_16x16x64_i8 v[86:89], v[188:191], v[212:215], v[86:89]
	v_mfma_i32_16x16x64_i8 v[86:89], v[192:195], v[216:219], v[86:89]
	v_mfma_i32_16x16x64_i8 v[82:85], v[196:199], v[212:215], v[82:85]
	v_mfma_i32_16x16x64_i8 v[82:85], v[200:203], v[216:219], v[82:85]
	v_mfma_i32_16x16x64_i8 v[78:81], v[188:191], v[220:223], v[78:81]
	v_mfma_i32_16x16x64_i8 v[78:81], v[192:195], v[224:227], v[78:81]
	v_mfma_i32_16x16x64_i8 v[74:77], v[196:199], v[220:223], v[74:77]
	v_mfma_i32_16x16x64_i8 v[74:77], v[200:203], v[224:227], v[74:77]
	v_mfma_i32_16x16x64_i8 v[70:73], v[188:191], v[228:231], v[70:73]
	v_mfma_i32_16x16x64_i8 v[70:73], v[192:195], v[232:235], v[70:73]
	v_mfma_i32_16x16x64_i8 v[66:69], v[196:199], v[228:231], v[66:69]
	v_mfma_i32_16x16x64_i8 v[66:69], v[200:203], v[232:235], v[66:69]
	s_setprio 0
	s_barrier
	s_add_i32 s64, s64, s39
	s_mov_b32 m0, s64
	ds_read_b128 v[204:207], v186 offset:16384
	ds_read_b128 v[208:211], v186 offset:17408
	ds_read_b128 v[212:215], v186 offset:18432
	ds_read_b128 v[216:219], v186 offset:19456
	ds_read_b128 v[220:223], v186 offset:20480
	ds_read_b128 v[224:227], v186 offset:21504
	ds_read_b128 v[228:231], v186 offset:22528
	ds_read_b128 v[232:235], v186 offset:23552
	global_load_lds_dwordx4 v136, s[2:3]
	s_add_i32 m0, s64, 0x2000
	s_add_u32 s64, s2, 0x80000
	s_addc_u32 s65, s3, 0
	s_add_i32 s66, s66, s39
	global_load_lds_dwordx4 v140, s[2:3]
	s_mov_b32 m0, s66
	v_lshl_add_u64 v[242:243], s[36:37], 0, v[138:139]
	global_load_lds_dwordx4 v136, s[64:65]
	s_add_i32 m0, s66, 0x2000
	s_nop 0
	global_load_lds_dwordx4 v140, s[64:65]
	v_lshl_add_u64 v[240:241], s[36:37], 0, v[134:135]
	s_mov_b32 m0, s40
	s_nop 0
	global_load_lds_dwordx4 v134, s[36:37]
	s_mov_b32 m0, s41
	s_nop 0
	global_load_lds_dwordx4 v138, s[36:37]
	s_waitcnt vmcnt(8)
	s_waitcnt lgkmcnt(0)
	s_barrier
	s_setprio 1
	s_waitcnt lgkmcnt(0)
	v_mfma_i32_16x16x64_i8 v[62:65], v[148:151], v[204:207], v[62:65]
	v_mfma_i32_16x16x64_i8 v[62:65], v[152:155], v[208:211], v[62:65]
	v_mfma_i32_16x16x64_i8 v[58:61], v[156:159], v[204:207], v[58:61]
	v_mfma_i32_16x16x64_i8 v[58:61], v[160:163], v[208:211], v[58:61]
	v_mfma_i32_16x16x64_i8 v[54:57], v[148:151], v[212:215], v[54:57]
	v_mfma_i32_16x16x64_i8 v[54:57], v[152:155], v[216:219], v[54:57]
	v_mfma_i32_16x16x64_i8 v[50:53], v[156:159], v[212:215], v[50:53]
	v_mfma_i32_16x16x64_i8 v[50:53], v[160:163], v[216:219], v[50:53]
	v_mfma_i32_16x16x64_i8 v[46:49], v[148:151], v[220:223], v[46:49]
	v_mfma_i32_16x16x64_i8 v[46:49], v[152:155], v[224:227], v[46:49]
	v_mfma_i32_16x16x64_i8 v[42:45], v[156:159], v[220:223], v[42:45]
	v_mfma_i32_16x16x64_i8 v[42:45], v[160:163], v[224:227], v[42:45]
	v_mfma_i32_16x16x64_i8 v[38:41], v[148:151], v[228:231], v[38:41]
	v_mfma_i32_16x16x64_i8 v[38:41], v[152:155], v[232:235], v[38:41]
	v_mfma_i32_16x16x64_i8 v[34:37], v[156:159], v[228:231], v[34:37]
	v_mfma_i32_16x16x64_i8 v[34:37], v[160:163], v[232:235], v[34:37]
	s_setprio 0
	s_setprio 1
	v_mfma_i32_16x16x64_i8 v[30:33], v[188:191], v[204:207], v[30:33]
	v_mfma_i32_16x16x64_i8 v[30:33], v[192:195], v[208:211], v[30:33]
	v_mfma_i32_16x16x64_i8 v[26:29], v[196:199], v[204:207], v[26:29]
	v_mfma_i32_16x16x64_i8 v[26:29], v[200:203], v[208:211], v[26:29]
	v_mfma_i32_16x16x64_i8 v[22:25], v[188:191], v[212:215], v[22:25]
	v_mfma_i32_16x16x64_i8 v[22:25], v[192:195], v[216:219], v[22:25]
	v_mfma_i32_16x16x64_i8 v[18:21], v[196:199], v[212:215], v[18:21]
	v_mfma_i32_16x16x64_i8 v[18:21], v[200:203], v[216:219], v[18:21]
	v_mfma_i32_16x16x64_i8 v[14:17], v[188:191], v[220:223], v[14:17]
	v_mfma_i32_16x16x64_i8 v[14:17], v[192:195], v[224:227], v[14:17]
	v_mfma_i32_16x16x64_i8 v[10:13], v[196:199], v[220:223], v[10:13]
	v_mfma_i32_16x16x64_i8 v[10:13], v[200:203], v[224:227], v[10:13]
	v_mfma_i32_16x16x64_i8 v[6:9], v[188:191], v[228:231], v[6:9]
	v_mfma_i32_16x16x64_i8 v[6:9], v[192:195], v[232:235], v[6:9]
	v_mfma_i32_16x16x64_i8 v[2:5], v[196:199], v[228:231], v[2:5]
	v_mfma_i32_16x16x64_i8 v[2:5], v[200:203], v[232:235], v[2:5]
	s_setprio 0
	s_barrier
	s_add_i32 s64, 0, 0x18000
	v_add_u32_e32 v142, s64, v131
	s_add_i32 s65, 0, 0x1c000
	ds_read_b128 v[148:151], v142
	ds_read_b128 v[152:155], v142 offset:1024
	ds_read_b128 v[156:159], v142 offset:2048
	ds_read_b128 v[160:163], v142 offset:3072
	v_add_u32_e32 v142, s65, v131
	ds_read_b128 v[188:191], v142
	ds_read_b128 v[192:195], v142 offset:1024
	ds_read_b128 v[196:199], v142 offset:2048
	ds_read_b128 v[200:203], v142 offset:3072
	s_add_u32 s36, s36, 0x80000
	s_addc_u32 s37, s37, 0
	s_mov_b32 m0, s42
	ds_read_b128 v[204:207], v186 offset:32768
	ds_read_b128 v[208:211], v186 offset:33792
	ds_read_b128 v[212:215], v186 offset:34816
	ds_read_b128 v[216:219], v186 offset:35840
	ds_read_b128 v[220:223], v186 offset:36864
	ds_read_b128 v[224:227], v186 offset:37888
	ds_read_b128 v[228:231], v186 offset:38912
	ds_read_b128 v[232:235], v186 offset:39936
	global_load_lds_dwordx4 v134, s[36:37]
	s_mov_b32 m0, s43
	s_nop 0
	global_load_lds_dwordx4 v138, s[36:37]
	s_waitcnt vmcnt(8)
	s_waitcnt lgkmcnt(0)
	s_barrier
	s_setprio 1
	s_waitcnt lgkmcnt(0)
	v_mfma_i32_16x16x64_i8 v[126:129], v[148:151], v[204:207], v[126:129]
	v_mfma_i32_16x16x64_i8 v[126:129], v[152:155], v[208:211], v[126:129]
	v_mfma_i32_16x16x64_i8 v[122:125], v[156:159], v[204:207], v[122:125]
	v_mfma_i32_16x16x64_i8 v[122:125], v[160:163], v[208:211], v[122:125]
	v_mfma_i32_16x16x64_i8 v[118:121], v[148:151], v[212:215], v[118:121]
	v_mfma_i32_16x16x64_i8 v[118:121], v[152:155], v[216:219], v[118:121]
	v_mfma_i32_16x16x64_i8 v[114:117], v[156:159], v[212:215], v[114:117]
	v_mfma_i32_16x16x64_i8 v[114:117], v[160:163], v[216:219], v[114:117]
	v_mfma_i32_16x16x64_i8 v[110:113], v[148:151], v[220:223], v[110:113]
	v_mfma_i32_16x16x64_i8 v[110:113], v[152:155], v[224:227], v[110:113]
	v_mfma_i32_16x16x64_i8 v[106:109], v[156:159], v[220:223], v[106:109]
	v_mfma_i32_16x16x64_i8 v[106:109], v[160:163], v[224:227], v[106:109]
	v_mfma_i32_16x16x64_i8 v[102:105], v[148:151], v[228:231], v[102:105]
	v_mfma_i32_16x16x64_i8 v[102:105], v[152:155], v[232:235], v[102:105]
	v_mfma_i32_16x16x64_i8 v[98:101], v[156:159], v[228:231], v[98:101]
	v_mfma_i32_16x16x64_i8 v[98:101], v[160:163], v[232:235], v[98:101]
	s_setprio 0
	s_setprio 1
	v_mfma_i32_16x16x64_i8 v[94:97], v[188:191], v[204:207], v[94:97]
	v_mfma_i32_16x16x64_i8 v[94:97], v[192:195], v[208:211], v[94:97]
	v_mfma_i32_16x16x64_i8 v[90:93], v[196:199], v[204:207], v[90:93]
	v_mfma_i32_16x16x64_i8 v[90:93], v[200:203], v[208:211], v[90:93]
	v_mfma_i32_16x16x64_i8 v[86:89], v[188:191], v[212:215], v[86:89]
	v_mfma_i32_16x16x64_i8 v[86:89], v[192:195], v[216:219], v[86:89]
	v_mfma_i32_16x16x64_i8 v[82:85], v[196:199], v[212:215], v[82:85]
	v_mfma_i32_16x16x64_i8 v[82:85], v[200:203], v[216:219], v[82:85]
	v_mfma_i32_16x16x64_i8 v[78:81], v[188:191], v[220:223], v[78:81]
	v_mfma_i32_16x16x64_i8 v[78:81], v[192:195], v[224:227], v[78:81]
	v_mfma_i32_16x16x64_i8 v[74:77], v[196:199], v[220:223], v[74:77]
	v_mfma_i32_16x16x64_i8 v[74:77], v[200:203], v[224:227], v[74:77]
	v_mfma_i32_16x16x64_i8 v[70:73], v[188:191], v[228:231], v[70:73]
	v_mfma_i32_16x16x64_i8 v[70:73], v[192:195], v[232:235], v[70:73]
	v_mfma_i32_16x16x64_i8 v[66:69], v[196:199], v[228:231], v[66:69]
	v_mfma_i32_16x16x64_i8 v[66:69], v[200:203], v[232:235], v[66:69]
	s_setprio 0
	s_barrier
	s_add_i32 s36, s64, s39
	s_add_u32 s98, s2, s28
	s_addc_u32 s99, s3, s29
	s_mov_b32 m0, s36
	ds_read_b128 v[204:207], v186 offset:49152
	ds_read_b128 v[208:211], v186 offset:50176
	ds_read_b128 v[212:215], v186 offset:51200
	ds_read_b128 v[216:219], v186 offset:52224
	ds_read_b128 v[220:223], v186 offset:53248
	ds_read_b128 v[224:227], v186 offset:54272
	ds_read_b128 v[228:231], v186 offset:55296
	ds_read_b128 v[232:235], v186 offset:56320
	global_load_lds_dwordx4 v136, s[98:99]
	s_add_i32 m0, s36, 0x2000
	s_add_u32 s2, s2, 0x80080
	s_addc_u32 s3, s3, 0
	s_add_i32 s36, s65, s39
	global_load_lds_dwordx4 v140, s[98:99]
	s_mov_b32 m0, s36
	s_nop 0
	global_load_lds_dwordx4 v136, s[2:3]
	s_add_i32 m0, s36, 0x2000
	s_nop 0
	global_load_lds_dwordx4 v140, s[2:3]
	v_lshl_add_u64 v[236:237], v[240:241], 0, s[28:29]
	s_mov_b32 m0, s45
	s_nop 0
	global_load_lds_dwordx4 v[236:237], off
	v_lshl_add_u64 v[236:237], v[242:243], 0, s[28:29]
	s_mov_b32 m0, s52
	s_nop 0
	global_load_lds_dwordx4 v[236:237], off
	s_waitcnt vmcnt(8)
	s_waitcnt lgkmcnt(0)
	s_barrier
	s_setprio 1
	s_waitcnt lgkmcnt(0)
	v_mfma_i32_16x16x64_i8 v[62:65], v[148:151], v[204:207], v[62:65]
	v_mfma_i32_16x16x64_i8 v[62:65], v[152:155], v[208:211], v[62:65]
	v_mfma_i32_16x16x64_i8 v[58:61], v[156:159], v[204:207], v[58:61]
	v_mfma_i32_16x16x64_i8 v[58:61], v[160:163], v[208:211], v[58:61]
	v_mfma_i32_16x16x64_i8 v[54:57], v[148:151], v[212:215], v[54:57]
	v_mfma_i32_16x16x64_i8 v[54:57], v[152:155], v[216:219], v[54:57]
	v_mfma_i32_16x16x64_i8 v[50:53], v[156:159], v[212:215], v[50:53]
	v_mfma_i32_16x16x64_i8 v[50:53], v[160:163], v[216:219], v[50:53]
	v_mfma_i32_16x16x64_i8 v[46:49], v[148:151], v[220:223], v[46:49]
	v_mfma_i32_16x16x64_i8 v[46:49], v[152:155], v[224:227], v[46:49]
	v_mfma_i32_16x16x64_i8 v[42:45], v[156:159], v[220:223], v[42:45]
	v_mfma_i32_16x16x64_i8 v[42:45], v[160:163], v[224:227], v[42:45]
	v_mfma_i32_16x16x64_i8 v[38:41], v[148:151], v[228:231], v[38:41]
	v_mfma_i32_16x16x64_i8 v[38:41], v[152:155], v[232:235], v[38:41]
	v_mfma_i32_16x16x64_i8 v[34:37], v[156:159], v[228:231], v[34:37]
	v_mfma_i32_16x16x64_i8 v[34:37], v[160:163], v[232:235], v[34:37]
	s_setprio 0
	s_setprio 1
	v_mfma_i32_16x16x64_i8 v[30:33], v[188:191], v[204:207], v[30:33]
	v_mfma_i32_16x16x64_i8 v[30:33], v[192:195], v[208:211], v[30:33]
	v_mfma_i32_16x16x64_i8 v[26:29], v[196:199], v[204:207], v[26:29]
	v_mfma_i32_16x16x64_i8 v[26:29], v[200:203], v[208:211], v[26:29]
	v_mfma_i32_16x16x64_i8 v[22:25], v[188:191], v[212:215], v[22:25]
	v_mfma_i32_16x16x64_i8 v[22:25], v[192:195], v[216:219], v[22:25]
	v_mfma_i32_16x16x64_i8 v[18:21], v[196:199], v[212:215], v[18:21]
	v_mfma_i32_16x16x64_i8 v[18:21], v[200:203], v[216:219], v[18:21]
	v_mfma_i32_16x16x64_i8 v[14:17], v[188:191], v[220:223], v[14:17]
	v_mfma_i32_16x16x64_i8 v[14:17], v[192:195], v[224:227], v[14:17]
	v_mfma_i32_16x16x64_i8 v[10:13], v[196:199], v[220:223], v[10:13]
	v_mfma_i32_16x16x64_i8 v[10:13], v[200:203], v[224:227], v[10:13]
	v_mfma_i32_16x16x64_i8 v[6:9], v[188:191], v[228:231], v[6:9]
	v_mfma_i32_16x16x64_i8 v[6:9], v[192:195], v[232:235], v[6:9]
	v_mfma_i32_16x16x64_i8 v[2:5], v[196:199], v[228:231], v[2:5]
	v_mfma_i32_16x16x64_i8 v[2:5], v[200:203], v[232:235], v[2:5]
	s_setprio 0
	s_barrier
	s_add_u32 s34, s34, 0x100
	s_addc_u32 s35, s35, 0
	s_add_u32 s59, s59, 0x100
	s_addc_u32 s60, s60, 0
	s_cmp_ge_i32 s61, s19
	s_mov_b32 s2, s61
	s_cbranch_scc0 .LBB0_961

.LBB0_1126:
	s_cmp_lt_i32 s29, 1
	s_cbranch_scc1 .LBB0_1148
	s_add_i32 s18, s29, -2
	s_add_u32 s30, s30, 0x2b0080
	s_addc_u32 s31, s31, 0
	s_add_u32 s28, s2, 0x100
	s_addc_u32 s52, s3, 0
	s_mov_b32 s2, 0
	ds_read_b128 v[148:151], v145
	ds_read_b128 v[152:155], v145 offset:1024
	ds_read_b128 v[156:159], v145 offset:2048
	ds_read_b128 v[160:163], v145 offset:3072
	ds_read_b128 v[164:167], v146
	ds_read_b128 v[170:173], v146 offset:1024
	ds_read_b128 v[174:177], v146 offset:2048
	ds_read_b128 v[178:181], v146 offset:3072
	s_add_i32 s53, s2, 2
	s_add_u32 s3, s30, 0xffd50080
	s_addc_u32 s34, s31, -1
	s_cmp_eq_u32 s18, s2
	s_cselect_b32 s2, s26, s28
	s_cselect_b32 s35, s25, s34
	s_cselect_b32 s34, s24, s3
	s_cselect_b32 s3, s27, s52
	s_add_i32 m0, s37, 0xc000
	ds_read_b128 v[182:185], v147
	ds_read_b128 v[186:189], v147 offset:1024
	ds_read_b128 v[190:193], v147 offset:2048
	ds_read_b128 v[194:197], v147 offset:3072
	ds_read_b128 v[198:201], v147 offset:4096
	ds_read_b128 v[202:205], v147 offset:5120
	ds_read_b128 v[206:209], v147 offset:6144
	ds_read_b128 v[210:213], v147 offset:7168
	global_load_lds_dwordx4 v140, s[30:31]
	s_add_i32 m0, s37, 0xe000
	s_nop 0
	global_load_lds_dwordx4 v142, s[30:31]
	s_waitcnt vmcnt(8)
	s_waitcnt lgkmcnt(0)
	s_barrier
	s_setprio 1
	s_waitcnt lgkmcnt(0)
	v_mfma_f32_16x16x32_bf16 v[124:127], v[148:151], v[182:185], 0
	v_mfma_f32_16x16x32_bf16 v[124:127], v[152:155], v[186:189], v[124:127]
	v_mfma_f32_16x16x32_bf16 v[120:123], v[156:159], v[182:185], 0
	v_mfma_f32_16x16x32_bf16 v[120:123], v[160:163], v[186:189], v[120:123]
	v_mfma_f32_16x16x32_bf16 v[108:111], v[148:151], v[190:193], 0
	v_mfma_f32_16x16x32_bf16 v[108:111], v[152:155], v[194:197], v[108:111]
	v_mfma_f32_16x16x32_bf16 v[100:103], v[156:159], v[190:193], 0
	v_mfma_f32_16x16x32_bf16 v[100:103], v[160:163], v[194:197], v[100:103]
	v_mfma_f32_16x16x32_bf16 v[92:95], v[148:151], v[198:201], 0
	v_mfma_f32_16x16x32_bf16 v[92:95], v[152:155], v[202:205], v[92:95]
	v_mfma_f32_16x16x32_bf16 v[84:87], v[156:159], v[198:201], 0
	v_mfma_f32_16x16x32_bf16 v[84:87], v[160:163], v[202:205], v[84:87]
	v_mfma_f32_16x16x32_bf16 v[76:79], v[148:151], v[206:209], 0
	v_mfma_f32_16x16x32_bf16 v[76:79], v[152:155], v[210:213], v[76:79]
	v_mfma_f32_16x16x32_bf16 v[68:71], v[156:159], v[206:209], 0
	v_mfma_f32_16x16x32_bf16 v[68:71], v[160:163], v[210:213], v[68:71]
	s_setprio 0
	s_setprio 1
	v_mfma_f32_16x16x32_bf16 v[116:119], v[164:167], v[182:185], 0
	v_mfma_f32_16x16x32_bf16 v[116:119], v[170:173], v[186:189], v[116:119]
	v_mfma_f32_16x16x32_bf16 v[112:115], v[174:177], v[182:185], 0
	v_mfma_f32_16x16x32_bf16 v[112:115], v[178:181], v[186:189], v[112:115]
	v_mfma_f32_16x16x32_bf16 v[104:107], v[164:167], v[190:193], 0
	v_mfma_f32_16x16x32_bf16 v[104:107], v[170:173], v[194:197], v[104:107]
	v_mfma_f32_16x16x32_bf16 v[96:99], v[174:177], v[190:193], 0
	v_mfma_f32_16x16x32_bf16 v[96:99], v[178:181], v[194:197], v[96:99]
	v_mfma_f32_16x16x32_bf16 v[88:91], v[164:167], v[198:201], 0
	v_mfma_f32_16x16x32_bf16 v[88:91], v[170:173], v[202:205], v[88:91]
	v_mfma_f32_16x16x32_bf16 v[80:83], v[174:177], v[198:201], 0
	v_mfma_f32_16x16x32_bf16 v[80:83], v[178:181], v[202:205], v[80:83]
	v_mfma_f32_16x16x32_bf16 v[72:75], v[164:167], v[206:209], 0
	v_mfma_f32_16x16x32_bf16 v[72:75], v[170:173], v[210:213], v[72:75]
	v_mfma_f32_16x16x32_bf16 v[64:67], v[174:177], v[206:209], 0
	v_mfma_f32_16x16x32_bf16 v[64:67], v[178:181], v[210:213], v[64:67]
	s_setprio 0
	s_barrier
	s_add_i32 s56, s46, s33
	s_mov_b32 m0, s56
	ds_read_b128 v[182:185], v147 offset:16384
	ds_read_b128 v[186:189], v147 offset:17408
	ds_read_b128 v[190:193], v147 offset:18432
	ds_read_b128 v[194:197], v147 offset:19456
	ds_read_b128 v[198:201], v147 offset:20480
	ds_read_b128 v[202:205], v147 offset:21504
	ds_read_b128 v[206:209], v147 offset:22528
	ds_read_b128 v[210:213], v147 offset:23552
	global_load_lds_dwordx4 v134, s[2:3]
	s_add_i32 m0, s56, 0x2000
	s_add_u32 s56, s2, 0x2b0000
	s_addc_u32 s57, s3, 0
	s_add_i32 s58, s47, s33
	global_load_lds_dwordx4 v138, s[2:3]
	s_mov_b32 m0, s58
	v_lshl_add_u64 v[220:221], s[34:35], 0, v[136:137]
	global_load_lds_dwordx4 v134, s[56:57]
	s_add_i32 m0, s58, 0x2000
	s_nop 0
	global_load_lds_dwordx4 v138, s[56:57]
	v_lshl_add_u64 v[218:219], s[34:35], 0, v[128:129]
	s_mov_b32 m0, s37
	s_nop 0
	global_load_lds_dwordx4 v128, s[34:35]
	s_mov_b32 m0, s38
	s_nop 0
	global_load_lds_dwordx4 v136, s[34:35]
	s_waitcnt vmcnt(8)
	s_waitcnt lgkmcnt(0)
	s_barrier
	s_setprio 1
	s_waitcnt lgkmcnt(0)
	v_mfma_f32_16x16x32_bf16 v[60:63], v[148:151], v[182:185], 0
	v_mfma_f32_16x16x32_bf16 v[60:63], v[152:155], v[186:189], v[60:63]
	v_mfma_f32_16x16x32_bf16 v[52:55], v[156:159], v[182:185], 0
	v_mfma_f32_16x16x32_bf16 v[52:55], v[160:163], v[186:189], v[52:55]
	v_mfma_f32_16x16x32_bf16 v[44:47], v[148:151], v[190:193], 0
	v_mfma_f32_16x16x32_bf16 v[44:47], v[152:155], v[194:197], v[44:47]
	v_mfma_f32_16x16x32_bf16 v[36:39], v[156:159], v[190:193], 0
	v_mfma_f32_16x16x32_bf16 v[36:39], v[160:163], v[194:197], v[36:39]
	v_mfma_f32_16x16x32_bf16 v[28:31], v[148:151], v[198:201], 0
	v_mfma_f32_16x16x32_bf16 v[28:31], v[152:155], v[202:205], v[28:31]
	v_mfma_f32_16x16x32_bf16 v[20:23], v[156:159], v[198:201], 0
	v_mfma_f32_16x16x32_bf16 v[20:23], v[160:163], v[202:205], v[20:23]
	v_mfma_f32_16x16x32_bf16 v[12:15], v[148:151], v[206:209], 0
	v_mfma_f32_16x16x32_bf16 v[12:15], v[152:155], v[210:213], v[12:15]
	v_mfma_f32_16x16x32_bf16 v[4:7], v[156:159], v[206:209], 0
	v_mfma_f32_16x16x32_bf16 v[4:7], v[160:163], v[210:213], v[4:7]
	s_setprio 0
	s_setprio 1
	v_mfma_f32_16x16x32_bf16 v[56:59], v[164:167], v[182:185], 0
	v_mfma_f32_16x16x32_bf16 v[56:59], v[170:173], v[186:189], v[56:59]
	v_mfma_f32_16x16x32_bf16 v[48:51], v[174:177], v[182:185], 0
	v_mfma_f32_16x16x32_bf16 v[48:51], v[178:181], v[186:189], v[48:51]
	v_mfma_f32_16x16x32_bf16 v[40:43], v[164:167], v[190:193], 0
	v_mfma_f32_16x16x32_bf16 v[40:43], v[170:173], v[194:197], v[40:43]
	v_mfma_f32_16x16x32_bf16 v[32:35], v[174:177], v[190:193], 0
	v_mfma_f32_16x16x32_bf16 v[32:35], v[178:181], v[194:197], v[32:35]
	v_mfma_f32_16x16x32_bf16 v[24:27], v[164:167], v[198:201], 0
	v_mfma_f32_16x16x32_bf16 v[24:27], v[170:173], v[202:205], v[24:27]
	v_mfma_f32_16x16x32_bf16 v[16:19], v[174:177], v[198:201], 0
	v_mfma_f32_16x16x32_bf16 v[16:19], v[178:181], v[202:205], v[16:19]
	v_mfma_f32_16x16x32_bf16 v[8:11], v[164:167], v[206:209], 0
	v_mfma_f32_16x16x32_bf16 v[8:11], v[170:173], v[210:213], v[8:11]
	v_mfma_f32_16x16x32_bf16 v[0:3], v[174:177], v[206:209], 0
	v_mfma_f32_16x16x32_bf16 v[0:3], v[178:181], v[210:213], v[0:3]
	s_setprio 0
	s_barrier
	s_add_i32 s56, 0, 0x18000
	s_add_i32 s57, 0, 0x1c000
	v_add_u32_e32 v160, s56, v133
	v_add_u32_e32 v168, s57, v133
	ds_read_b128 v[148:151], v160
	ds_read_b128 v[152:155], v160 offset:1024
	ds_read_b128 v[156:159], v160 offset:2048
	ds_read_b128 v[160:163], v160 offset:3072
	ds_read_b128 v[164:167], v168
	ds_read_b128 v[170:173], v168 offset:1024
	ds_read_b128 v[174:177], v168 offset:2048
	ds_read_b128 v[178:181], v168 offset:3072
	s_add_u32 s34, s34, 0x2b0000
	s_addc_u32 s35, s35, 0
	s_mov_b32 m0, s39
	ds_read_b128 v[182:185], v147 offset:32768
	ds_read_b128 v[186:189], v147 offset:33792
	ds_read_b128 v[190:193], v147 offset:34816
	ds_read_b128 v[194:197], v147 offset:35840
	ds_read_b128 v[198:201], v147 offset:36864
	ds_read_b128 v[202:205], v147 offset:37888
	ds_read_b128 v[206:209], v147 offset:38912
	ds_read_b128 v[210:213], v147 offset:39936
	global_load_lds_dwordx4 v128, s[34:35]
	s_mov_b32 m0, s40
	s_nop 0
	global_load_lds_dwordx4 v136, s[34:35]
	s_waitcnt vmcnt(8)
	s_waitcnt lgkmcnt(0)
	s_barrier
	s_setprio 1
	s_waitcnt lgkmcnt(0)
	v_mfma_f32_16x16x32_bf16 v[124:127], v[148:151], v[182:185], v[124:127]
	v_mfma_f32_16x16x32_bf16 v[124:127], v[152:155], v[186:189], v[124:127]
	v_mfma_f32_16x16x32_bf16 v[120:123], v[156:159], v[182:185], v[120:123]
	v_mfma_f32_16x16x32_bf16 v[120:123], v[160:163], v[186:189], v[120:123]
	v_mfma_f32_16x16x32_bf16 v[108:111], v[148:151], v[190:193], v[108:111]
	v_mfma_f32_16x16x32_bf16 v[108:111], v[152:155], v[194:197], v[108:111]
	v_mfma_f32_16x16x32_bf16 v[100:103], v[156:159], v[190:193], v[100:103]
	v_mfma_f32_16x16x32_bf16 v[100:103], v[160:163], v[194:197], v[100:103]
	v_mfma_f32_16x16x32_bf16 v[92:95], v[148:151], v[198:201], v[92:95]
	v_mfma_f32_16x16x32_bf16 v[92:95], v[152:155], v[202:205], v[92:95]
	v_mfma_f32_16x16x32_bf16 v[84:87], v[156:159], v[198:201], v[84:87]
	v_mfma_f32_16x16x32_bf16 v[84:87], v[160:163], v[202:205], v[84:87]
	v_mfma_f32_16x16x32_bf16 v[76:79], v[148:151], v[206:209], v[76:79]
	v_mfma_f32_16x16x32_bf16 v[76:79], v[152:155], v[210:213], v[76:79]
	v_mfma_f32_16x16x32_bf16 v[68:71], v[156:159], v[206:209], v[68:71]
	v_mfma_f32_16x16x32_bf16 v[68:71], v[160:163], v[210:213], v[68:71]
	s_setprio 0
	s_setprio 1
	v_mfma_f32_16x16x32_bf16 v[116:119], v[164:167], v[182:185], v[116:119]
	v_mfma_f32_16x16x32_bf16 v[116:119], v[170:173], v[186:189], v[116:119]
	v_mfma_f32_16x16x32_bf16 v[112:115], v[174:177], v[182:185], v[112:115]
	v_mfma_f32_16x16x32_bf16 v[112:115], v[178:181], v[186:189], v[112:115]
	v_mfma_f32_16x16x32_bf16 v[104:107], v[164:167], v[190:193], v[104:107]
	v_mfma_f32_16x16x32_bf16 v[104:107], v[170:173], v[194:197], v[104:107]
	v_mfma_f32_16x16x32_bf16 v[96:99], v[174:177], v[190:193], v[96:99]
	v_mfma_f32_16x16x32_bf16 v[96:99], v[178:181], v[194:197], v[96:99]
	v_mfma_f32_16x16x32_bf16 v[88:91], v[164:167], v[198:201], v[88:91]
	v_mfma_f32_16x16x32_bf16 v[88:91], v[170:173], v[202:205], v[88:91]
	v_mfma_f32_16x16x32_bf16 v[80:83], v[174:177], v[198:201], v[80:83]
	v_mfma_f32_16x16x32_bf16 v[80:83], v[178:181], v[202:205], v[80:83]
	v_mfma_f32_16x16x32_bf16 v[72:75], v[164:167], v[206:209], v[72:75]
	v_mfma_f32_16x16x32_bf16 v[72:75], v[170:173], v[210:213], v[72:75]
	v_mfma_f32_16x16x32_bf16 v[64:67], v[174:177], v[206:209], v[64:67]
	v_mfma_f32_16x16x32_bf16 v[64:67], v[178:181], v[210:213], v[64:67]
	s_setprio 0
	s_barrier
	s_add_i32 s34, s56, s33
	s_add_u32 s98, s2, s6
	s_addc_u32 s99, s3, s7
	s_mov_b32 m0, s34
	ds_read_b128 v[182:185], v147 offset:49152
	ds_read_b128 v[186:189], v147 offset:50176
	ds_read_b128 v[190:193], v147 offset:51200
	ds_read_b128 v[194:197], v147 offset:52224
	ds_read_b128 v[198:201], v147 offset:53248
	ds_read_b128 v[202:205], v147 offset:54272
	ds_read_b128 v[206:209], v147 offset:55296
	ds_read_b128 v[210:213], v147 offset:56320
	global_load_lds_dwordx4 v134, s[98:99]
	s_add_i32 m0, s34, 0x2000
	s_add_u32 s2, s2, 0x2b0080
	s_addc_u32 s3, s3, 0
	s_add_i32 s34, s57, s33
	global_load_lds_dwordx4 v138, s[98:99]
	s_mov_b32 m0, s34
	s_nop 0
	global_load_lds_dwordx4 v134, s[2:3]
	s_add_i32 m0, s34, 0x2000
	s_nop 0
	global_load_lds_dwordx4 v138, s[2:3]
	v_lshl_add_u64 v[214:215], v[218:219], 0, s[6:7]
	s_mov_b32 m0, s42
	s_nop 0
	global_load_lds_dwordx4 v[214:215], off
	v_lshl_add_u64 v[214:215], v[220:221], 0, s[6:7]
	s_mov_b32 m0, s43
	s_nop 0
	global_load_lds_dwordx4 v[214:215], off
	s_waitcnt vmcnt(8)
	s_waitcnt lgkmcnt(0)
	s_barrier
	s_setprio 1
	s_waitcnt lgkmcnt(0)
	v_mfma_f32_16x16x32_bf16 v[60:63], v[148:151], v[182:185], v[60:63]
	v_mfma_f32_16x16x32_bf16 v[60:63], v[152:155], v[186:189], v[60:63]
	v_mfma_f32_16x16x32_bf16 v[52:55], v[156:159], v[182:185], v[52:55]
	v_mfma_f32_16x16x32_bf16 v[52:55], v[160:163], v[186:189], v[52:55]
	v_mfma_f32_16x16x32_bf16 v[44:47], v[148:151], v[190:193], v[44:47]
	v_mfma_f32_16x16x32_bf16 v[44:47], v[152:155], v[194:197], v[44:47]
	v_mfma_f32_16x16x32_bf16 v[36:39], v[156:159], v[190:193], v[36:39]
	v_mfma_f32_16x16x32_bf16 v[36:39], v[160:163], v[194:197], v[36:39]
	v_mfma_f32_16x16x32_bf16 v[28:31], v[148:151], v[198:201], v[28:31]
	v_mfma_f32_16x16x32_bf16 v[28:31], v[152:155], v[202:205], v[28:31]
	v_mfma_f32_16x16x32_bf16 v[20:23], v[156:159], v[198:201], v[20:23]
	v_mfma_f32_16x16x32_bf16 v[20:23], v[160:163], v[202:205], v[20:23]
	v_mfma_f32_16x16x32_bf16 v[12:15], v[148:151], v[206:209], v[12:15]
	v_mfma_f32_16x16x32_bf16 v[12:15], v[152:155], v[210:213], v[12:15]
	v_mfma_f32_16x16x32_bf16 v[4:7], v[156:159], v[206:209], v[4:7]
	v_mfma_f32_16x16x32_bf16 v[4:7], v[160:163], v[210:213], v[4:7]
	s_setprio 0
	s_setprio 1
	v_mfma_f32_16x16x32_bf16 v[56:59], v[164:167], v[182:185], v[56:59]
	v_mfma_f32_16x16x32_bf16 v[56:59], v[170:173], v[186:189], v[56:59]
	v_mfma_f32_16x16x32_bf16 v[48:51], v[174:177], v[182:185], v[48:51]
	v_mfma_f32_16x16x32_bf16 v[48:51], v[178:181], v[186:189], v[48:51]
	v_mfma_f32_16x16x32_bf16 v[40:43], v[164:167], v[190:193], v[40:43]
	v_mfma_f32_16x16x32_bf16 v[40:43], v[170:173], v[194:197], v[40:43]
	v_mfma_f32_16x16x32_bf16 v[32:35], v[174:177], v[190:193], v[32:35]
	v_mfma_f32_16x16x32_bf16 v[32:35], v[178:181], v[194:197], v[32:35]
	v_mfma_f32_16x16x32_bf16 v[24:27], v[164:167], v[198:201], v[24:27]
	v_mfma_f32_16x16x32_bf16 v[24:27], v[170:173], v[202:205], v[24:27]
	v_mfma_f32_16x16x32_bf16 v[16:19], v[174:177], v[198:201], v[16:19]
	v_mfma_f32_16x16x32_bf16 v[16:19], v[178:181], v[202:205], v[16:19]
	v_mfma_f32_16x16x32_bf16 v[8:11], v[164:167], v[206:209], v[8:11]
	v_mfma_f32_16x16x32_bf16 v[8:11], v[170:173], v[210:213], v[8:11]
	v_mfma_f32_16x16x32_bf16 v[0:3], v[174:177], v[206:209], v[0:3]
	v_mfma_f32_16x16x32_bf16 v[0:3], v[178:181], v[210:213], v[0:3]
	s_setprio 0
	s_barrier
	s_add_u32 s30, s30, 0x100
	s_addc_u32 s31, s31, 0
	s_add_u32 s28, s28, 0x100
	s_addc_u32 s52, s52, 0
	s_cmp_ge_i32 s53, s29
	s_mov_b32 s2, s53
	s_cbranch_scc1 .Lkpeel_exit_6
.LBB0_1128:
	ds_read_b128 v[148:151], v145
	ds_read_b128 v[152:155], v145 offset:1024
	ds_read_b128 v[156:159], v145 offset:2048
	ds_read_b128 v[160:163], v145 offset:3072
	ds_read_b128 v[164:167], v146
	ds_read_b128 v[170:173], v146 offset:1024
	ds_read_b128 v[174:177], v146 offset:2048
	ds_read_b128 v[178:181], v146 offset:3072
	s_add_i32 s53, s2, 2
	s_add_u32 s3, s30, 0xffd50080
	s_addc_u32 s34, s31, -1
	s_cmp_eq_u32 s18, s2
	s_cselect_b32 s2, s26, s28
	s_cselect_b32 s35, s25, s34
	s_cselect_b32 s34, s24, s3
	s_cselect_b32 s3, s27, s52
	s_add_i32 m0, s37, 0xc000
	ds_read_b128 v[182:185], v147
	ds_read_b128 v[186:189], v147 offset:1024
	ds_read_b128 v[190:193], v147 offset:2048
	ds_read_b128 v[194:197], v147 offset:3072
	ds_read_b128 v[198:201], v147 offset:4096
	ds_read_b128 v[202:205], v147 offset:5120
	ds_read_b128 v[206:209], v147 offset:6144
	ds_read_b128 v[210:213], v147 offset:7168
	global_load_lds_dwordx4 v140, s[30:31]
	s_add_i32 m0, s37, 0xe000
	s_nop 0
	global_load_lds_dwordx4 v142, s[30:31]
	s_waitcnt vmcnt(8)
	s_waitcnt lgkmcnt(0)
	s_barrier
	s_setprio 1
	s_waitcnt lgkmcnt(0)
	v_mfma_f32_16x16x32_bf16 v[124:127], v[148:151], v[182:185], v[124:127]
	v_mfma_f32_16x16x32_bf16 v[124:127], v[152:155], v[186:189], v[124:127]
	v_mfma_f32_16x16x32_bf16 v[120:123], v[156:159], v[182:185], v[120:123]
	v_mfma_f32_16x16x32_bf16 v[120:123], v[160:163], v[186:189], v[120:123]
	v_mfma_f32_16x16x32_bf16 v[108:111], v[148:151], v[190:193], v[108:111]
	v_mfma_f32_16x16x32_bf16 v[108:111], v[152:155], v[194:197], v[108:111]
	v_mfma_f32_16x16x32_bf16 v[100:103], v[156:159], v[190:193], v[100:103]
	v_mfma_f32_16x16x32_bf16 v[100:103], v[160:163], v[194:197], v[100:103]
	v_mfma_f32_16x16x32_bf16 v[92:95], v[148:151], v[198:201], v[92:95]
	v_mfma_f32_16x16x32_bf16 v[92:95], v[152:155], v[202:205], v[92:95]
	v_mfma_f32_16x16x32_bf16 v[84:87], v[156:159], v[198:201], v[84:87]
	v_mfma_f32_16x16x32_bf16 v[84:87], v[160:163], v[202:205], v[84:87]
	v_mfma_f32_16x16x32_bf16 v[76:79], v[148:151], v[206:209], v[76:79]
	v_mfma_f32_16x16x32_bf16 v[76:79], v[152:155], v[210:213], v[76:79]
	v_mfma_f32_16x16x32_bf16 v[68:71], v[156:159], v[206:209], v[68:71]
	v_mfma_f32_16x16x32_bf16 v[68:71], v[160:163], v[210:213], v[68:71]
	s_setprio 0
	s_setprio 1
	v_mfma_f32_16x16x32_bf16 v[116:119], v[164:167], v[182:185], v[116:119]
	v_mfma_f32_16x16x32_bf16 v[116:119], v[170:173], v[186:189], v[116:119]
	v_mfma_f32_16x16x32_bf16 v[112:115], v[174:177], v[182:185], v[112:115]
	v_mfma_f32_16x16x32_bf16 v[112:115], v[178:181], v[186:189], v[112:115]
	v_mfma_f32_16x16x32_bf16 v[104:107], v[164:167], v[190:193], v[104:107]
	v_mfma_f32_16x16x32_bf16 v[104:107], v[170:173], v[194:197], v[104:107]
	v_mfma_f32_16x16x32_bf16 v[96:99], v[174:177], v[190:193], v[96:99]
	v_mfma_f32_16x16x32_bf16 v[96:99], v[178:181], v[194:197], v[96:99]
	v_mfma_f32_16x16x32_bf16 v[88:91], v[164:167], v[198:201], v[88:91]
	v_mfma_f32_16x16x32_bf16 v[88:91], v[170:173], v[202:205], v[88:91]
	v_mfma_f32_16x16x32_bf16 v[80:83], v[174:177], v[198:201], v[80:83]
	v_mfma_f32_16x16x32_bf16 v[80:83], v[178:181], v[202:205], v[80:83]
	v_mfma_f32_16x16x32_bf16 v[72:75], v[164:167], v[206:209], v[72:75]
	v_mfma_f32_16x16x32_bf16 v[72:75], v[170:173], v[210:213], v[72:75]
	v_mfma_f32_16x16x32_bf16 v[64:67], v[174:177], v[206:209], v[64:67]
	v_mfma_f32_16x16x32_bf16 v[64:67], v[178:181], v[210:213], v[64:67]
	s_setprio 0
	s_barrier
	s_add_i32 s56, s46, s33
	s_mov_b32 m0, s56
	ds_read_b128 v[182:185], v147 offset:16384
	ds_read_b128 v[186:189], v147 offset:17408
	ds_read_b128 v[190:193], v147 offset:18432
	ds_read_b128 v[194:197], v147 offset:19456
	ds_read_b128 v[198:201], v147 offset:20480
	ds_read_b128 v[202:205], v147 offset:21504
	ds_read_b128 v[206:209], v147 offset:22528
	ds_read_b128 v[210:213], v147 offset:23552
	global_load_lds_dwordx4 v134, s[2:3]
	s_add_i32 m0, s56, 0x2000
	s_add_u32 s56, s2, 0x2b0000
	s_addc_u32 s57, s3, 0
	s_add_i32 s58, s47, s33
	global_load_lds_dwordx4 v138, s[2:3]
	s_mov_b32 m0, s58
	v_lshl_add_u64 v[220:221], s[34:35], 0, v[136:137]
	global_load_lds_dwordx4 v134, s[56:57]
	s_add_i32 m0, s58, 0x2000
	s_nop 0
	global_load_lds_dwordx4 v138, s[56:57]
	v_lshl_add_u64 v[218:219], s[34:35], 0, v[128:129]
	s_mov_b32 m0, s37
	s_nop 0
	global_load_lds_dwordx4 v128, s[34:35]
	s_mov_b32 m0, s38
	s_nop 0
	global_load_lds_dwordx4 v136, s[34:35]
	s_waitcnt vmcnt(8)
	s_waitcnt lgkmcnt(0)
	s_barrier
	s_setprio 1
	s_waitcnt lgkmcnt(0)
	v_mfma_f32_16x16x32_bf16 v[60:63], v[148:151], v[182:185], v[60:63]
	v_mfma_f32_16x16x32_bf16 v[60:63], v[152:155], v[186:189], v[60:63]
	v_mfma_f32_16x16x32_bf16 v[52:55], v[156:159], v[182:185], v[52:55]
	v_mfma_f32_16x16x32_bf16 v[52:55], v[160:163], v[186:189], v[52:55]
	v_mfma_f32_16x16x32_bf16 v[44:47], v[148:151], v[190:193], v[44:47]
	v_mfma_f32_16x16x32_bf16 v[44:47], v[152:155], v[194:197], v[44:47]
	v_mfma_f32_16x16x32_bf16 v[36:39], v[156:159], v[190:193], v[36:39]
	v_mfma_f32_16x16x32_bf16 v[36:39], v[160:163], v[194:197], v[36:39]
	v_mfma_f32_16x16x32_bf16 v[28:31], v[148:151], v[198:201], v[28:31]
	v_mfma_f32_16x16x32_bf16 v[28:31], v[152:155], v[202:205], v[28:31]
	v_mfma_f32_16x16x32_bf16 v[20:23], v[156:159], v[198:201], v[20:23]
	v_mfma_f32_16x16x32_bf16 v[20:23], v[160:163], v[202:205], v[20:23]
	v_mfma_f32_16x16x32_bf16 v[12:15], v[148:151], v[206:209], v[12:15]
	v_mfma_f32_16x16x32_bf16 v[12:15], v[152:155], v[210:213], v[12:15]
	v_mfma_f32_16x16x32_bf16 v[4:7], v[156:159], v[206:209], v[4:7]
	v_mfma_f32_16x16x32_bf16 v[4:7], v[160:163], v[210:213], v[4:7]
	s_setprio 0
	s_setprio 1
	v_mfma_f32_16x16x32_bf16 v[56:59], v[164:167], v[182:185], v[56:59]
	v_mfma_f32_16x16x32_bf16 v[56:59], v[170:173], v[186:189], v[56:59]
	v_mfma_f32_16x16x32_bf16 v[48:51], v[174:177], v[182:185], v[48:51]
	v_mfma_f32_16x16x32_bf16 v[48:51], v[178:181], v[186:189], v[48:51]
	v_mfma_f32_16x16x32_bf16 v[40:43], v[164:167], v[190:193], v[40:43]
	v_mfma_f32_16x16x32_bf16 v[40:43], v[170:173], v[194:197], v[40:43]
	v_mfma_f32_16x16x32_bf16 v[32:35], v[174:177], v[190:193], v[32:35]
	v_mfma_f32_16x16x32_bf16 v[32:35], v[178:181], v[194:197], v[32:35]
	v_mfma_f32_16x16x32_bf16 v[24:27], v[164:167], v[198:201], v[24:27]
	v_mfma_f32_16x16x32_bf16 v[24:27], v[170:173], v[202:205], v[24:27]
	v_mfma_f32_16x16x32_bf16 v[16:19], v[174:177], v[198:201], v[16:19]
	v_mfma_f32_16x16x32_bf16 v[16:19], v[178:181], v[202:205], v[16:19]
	v_mfma_f32_16x16x32_bf16 v[8:11], v[164:167], v[206:209], v[8:11]
	v_mfma_f32_16x16x32_bf16 v[8:11], v[170:173], v[210:213], v[8:11]
	v_mfma_f32_16x16x32_bf16 v[0:3], v[174:177], v[206:209], v[0:3]
	v_mfma_f32_16x16x32_bf16 v[0:3], v[178:181], v[210:213], v[0:3]
	s_setprio 0
	s_barrier
	s_add_i32 s56, 0, 0x18000
	s_add_i32 s57, 0, 0x1c000
	v_add_u32_e32 v160, s56, v133
	v_add_u32_e32 v168, s57, v133
	ds_read_b128 v[148:151], v160
	ds_read_b128 v[152:155], v160 offset:1024
	ds_read_b128 v[156:159], v160 offset:2048
	ds_read_b128 v[160:163], v160 offset:3072
	ds_read_b128 v[164:167], v168
	ds_read_b128 v[170:173], v168 offset:1024
	ds_read_b128 v[174:177], v168 offset:2048
	ds_read_b128 v[178:181], v168 offset:3072
	s_add_u32 s34, s34, 0x2b0000
	s_addc_u32 s35, s35, 0
	s_mov_b32 m0, s39
	ds_read_b128 v[182:185], v147 offset:32768
	ds_read_b128 v[186:189], v147 offset:33792
	ds_read_b128 v[190:193], v147 offset:34816
	ds_read_b128 v[194:197], v147 offset:35840
	ds_read_b128 v[198:201], v147 offset:36864
	ds_read_b128 v[202:205], v147 offset:37888
	ds_read_b128 v[206:209], v147 offset:38912
	ds_read_b128 v[210:213], v147 offset:39936
	global_load_lds_dwordx4 v128, s[34:35]
	s_mov_b32 m0, s40
	s_nop 0
	global_load_lds_dwordx4 v136, s[34:35]
	s_waitcnt vmcnt(8)
	s_waitcnt lgkmcnt(0)
	s_barrier
	s_setprio 1
	s_waitcnt lgkmcnt(0)
	v_mfma_f32_16x16x32_bf16 v[124:127], v[148:151], v[182:185], v[124:127]
	v_mfma_f32_16x16x32_bf16 v[124:127], v[152:155], v[186:189], v[124:127]
	v_mfma_f32_16x16x32_bf16 v[120:123], v[156:159], v[182:185], v[120:123]
	v_mfma_f32_16x16x32_bf16 v[120:123], v[160:163], v[186:189], v[120:123]
	v_mfma_f32_16x16x32_bf16 v[108:111], v[148:151], v[190:193], v[108:111]
	v_mfma_f32_16x16x32_bf16 v[108:111], v[152:155], v[194:197], v[108:111]
	v_mfma_f32_16x16x32_bf16 v[100:103], v[156:159], v[190:193], v[100:103]
	v_mfma_f32_16x16x32_bf16 v[100:103], v[160:163], v[194:197], v[100:103]
	v_mfma_f32_16x16x32_bf16 v[92:95], v[148:151], v[198:201], v[92:95]
	v_mfma_f32_16x16x32_bf16 v[92:95], v[152:155], v[202:205], v[92:95]
	v_mfma_f32_16x16x32_bf16 v[84:87], v[156:159], v[198:201], v[84:87]
	v_mfma_f32_16x16x32_bf16 v[84:87], v[160:163], v[202:205], v[84:87]
	v_mfma_f32_16x16x32_bf16 v[76:79], v[148:151], v[206:209], v[76:79]
	v_mfma_f32_16x16x32_bf16 v[76:79], v[152:155], v[210:213], v[76:79]
	v_mfma_f32_16x16x32_bf16 v[68:71], v[156:159], v[206:209], v[68:71]
	v_mfma_f32_16x16x32_bf16 v[68:71], v[160:163], v[210:213], v[68:71]
	s_setprio 0
	s_setprio 1
	v_mfma_f32_16x16x32_bf16 v[116:119], v[164:167], v[182:185], v[116:119]
	v_mfma_f32_16x16x32_bf16 v[116:119], v[170:173], v[186:189], v[116:119]
	v_mfma_f32_16x16x32_bf16 v[112:115], v[174:177], v[182:185], v[112:115]
	v_mfma_f32_16x16x32_bf16 v[112:115], v[178:181], v[186:189], v[112:115]
	v_mfma_f32_16x16x32_bf16 v[104:107], v[164:167], v[190:193], v[104:107]
	v_mfma_f32_16x16x32_bf16 v[104:107], v[170:173], v[194:197], v[104:107]
	v_mfma_f32_16x16x32_bf16 v[96:99], v[174:177], v[190:193], v[96:99]
	v_mfma_f32_16x16x32_bf16 v[96:99], v[178:181], v[194:197], v[96:99]
	v_mfma_f32_16x16x32_bf16 v[88:91], v[164:167], v[198:201], v[88:91]
	v_mfma_f32_16x16x32_bf16 v[88:91], v[170:173], v[202:205], v[88:91]
	v_mfma_f32_16x16x32_bf16 v[80:83], v[174:177], v[198:201], v[80:83]
	v_mfma_f32_16x16x32_bf16 v[80:83], v[178:181], v[202:205], v[80:83]
	v_mfma_f32_16x16x32_bf16 v[72:75], v[164:167], v[206:209], v[72:75]
	v_mfma_f32_16x16x32_bf16 v[72:75], v[170:173], v[210:213], v[72:75]
	v_mfma_f32_16x16x32_bf16 v[64:67], v[174:177], v[206:209], v[64:67]
	v_mfma_f32_16x16x32_bf16 v[64:67], v[178:181], v[210:213], v[64:67]
	s_setprio 0
	s_barrier
	s_add_i32 s34, s56, s33
	s_add_u32 s98, s2, s6
	s_addc_u32 s99, s3, s7
	s_mov_b32 m0, s34
	ds_read_b128 v[182:185], v147 offset:49152
	ds_read_b128 v[186:189], v147 offset:50176
	ds_read_b128 v[190:193], v147 offset:51200
	ds_read_b128 v[194:197], v147 offset:52224
	ds_read_b128 v[198:201], v147 offset:53248
	ds_read_b128 v[202:205], v147 offset:54272
	ds_read_b128 v[206:209], v147 offset:55296
	ds_read_b128 v[210:213], v147 offset:56320
	global_load_lds_dwordx4 v134, s[98:99]
	s_add_i32 m0, s34, 0x2000
	s_add_u32 s2, s2, 0x2b0080
	s_addc_u32 s3, s3, 0
	s_add_i32 s34, s57, s33
	global_load_lds_dwordx4 v138, s[98:99]
	s_mov_b32 m0, s34
	s_nop 0
	global_load_lds_dwordx4 v134, s[2:3]
	s_add_i32 m0, s34, 0x2000
	s_nop 0
	global_load_lds_dwordx4 v138, s[2:3]
	v_lshl_add_u64 v[214:215], v[218:219], 0, s[6:7]
	s_mov_b32 m0, s42
	s_nop 0
	global_load_lds_dwordx4 v[214:215], off
	v_lshl_add_u64 v[214:215], v[220:221], 0, s[6:7]
	s_mov_b32 m0, s43
	s_nop 0
	global_load_lds_dwordx4 v[214:215], off
	s_waitcnt vmcnt(8)
	s_waitcnt lgkmcnt(0)
	s_barrier
	s_setprio 1
	s_waitcnt lgkmcnt(0)
	v_mfma_f32_16x16x32_bf16 v[60:63], v[148:151], v[182:185], v[60:63]
	v_mfma_f32_16x16x32_bf16 v[60:63], v[152:155], v[186:189], v[60:63]
	v_mfma_f32_16x16x32_bf16 v[52:55], v[156:159], v[182:185], v[52:55]
	v_mfma_f32_16x16x32_bf16 v[52:55], v[160:163], v[186:189], v[52:55]
	v_mfma_f32_16x16x32_bf16 v[44:47], v[148:151], v[190:193], v[44:47]
	v_mfma_f32_16x16x32_bf16 v[44:47], v[152:155], v[194:197], v[44:47]
	v_mfma_f32_16x16x32_bf16 v[36:39], v[156:159], v[190:193], v[36:39]
	v_mfma_f32_16x16x32_bf16 v[36:39], v[160:163], v[194:197], v[36:39]
	v_mfma_f32_16x16x32_bf16 v[28:31], v[148:151], v[198:201], v[28:31]
	v_mfma_f32_16x16x32_bf16 v[28:31], v[152:155], v[202:205], v[28:31]
	v_mfma_f32_16x16x32_bf16 v[20:23], v[156:159], v[198:201], v[20:23]
	v_mfma_f32_16x16x32_bf16 v[20:23], v[160:163], v[202:205], v[20:23]
	v_mfma_f32_16x16x32_bf16 v[12:15], v[148:151], v[206:209], v[12:15]
	v_mfma_f32_16x16x32_bf16 v[12:15], v[152:155], v[210:213], v[12:15]
	v_mfma_f32_16x16x32_bf16 v[4:7], v[156:159], v[206:209], v[4:7]
	v_mfma_f32_16x16x32_bf16 v[4:7], v[160:163], v[210:213], v[4:7]
	s_setprio 0
	s_setprio 1
	v_mfma_f32_16x16x32_bf16 v[56:59], v[164:167], v[182:185], v[56:59]
	v_mfma_f32_16x16x32_bf16 v[56:59], v[170:173], v[186:189], v[56:59]
	v_mfma_f32_16x16x32_bf16 v[48:51], v[174:177], v[182:185], v[48:51]
	v_mfma_f32_16x16x32_bf16 v[48:51], v[178:181], v[186:189], v[48:51]
	v_mfma_f32_16x16x32_bf16 v[40:43], v[164:167], v[190:193], v[40:43]
	v_mfma_f32_16x16x32_bf16 v[40:43], v[170:173], v[194:197], v[40:43]
	v_mfma_f32_16x16x32_bf16 v[32:35], v[174:177], v[190:193], v[32:35]
	v_mfma_f32_16x16x32_bf16 v[32:35], v[178:181], v[194:197], v[32:35]
	v_mfma_f32_16x16x32_bf16 v[24:27], v[164:167], v[198:201], v[24:27]
	v_mfma_f32_16x16x32_bf16 v[24:27], v[170:173], v[202:205], v[24:27]
	v_mfma_f32_16x16x32_bf16 v[16:19], v[174:177], v[198:201], v[16:19]
	v_mfma_f32_16x16x32_bf16 v[16:19], v[178:181], v[202:205], v[16:19]
	v_mfma_f32_16x16x32_bf16 v[8:11], v[164:167], v[206:209], v[8:11]
	v_mfma_f32_16x16x32_bf16 v[8:11], v[170:173], v[210:213], v[8:11]
	v_mfma_f32_16x16x32_bf16 v[0:3], v[174:177], v[206:209], v[0:3]
	v_mfma_f32_16x16x32_bf16 v[0:3], v[178:181], v[210:213], v[0:3]
	s_setprio 0
	s_barrier
	s_add_u32 s30, s30, 0x100
	s_addc_u32 s31, s31, 0
	s_add_u32 s28, s28, 0x100
	s_addc_u32 s52, s52, 0
	s_cmp_ge_i32 s53, s29
	s_mov_b32 s2, s53
	s_cbranch_scc0 .LBB0_1128
